# v14: v13 + first K-iteration of every tile peeled with SrcC=0 (no accumulator zeroing v_movs); measure 1
# speedup vs baseline: 1.0238x; 1.0183x over previous
; #define PG8_STAGE(bufoff, gbase, voff) do { _Pragma("unroll") for (int _i = 0; _i < 2; ++_i) \
;         __builtin_amdgcn_global_load_lds((const unsigned*)((const char*)(gbase) + (voff)[_i]), (LAS unsigned*)(lds + (bufoff) + ldsw + _i * 8192), 16, 0, 0); } while (0)
; #define PG8_WAIT_V(n) asm volatile("s_waitcnt vmcnt(" #n ")" ::: "memory")
; #define PG8_BAR __builtin_amdgcn_s_barrier()
; template <class Epi, class Ptrs>
; __device__ __forceinline__ void gemm_phase(LAS unsigned char* lds, const int K, const StaticOrder& S, const Ptrs& P, const Epi& E) {
;     const int tid = threadIdx.x, wid = __builtin_amdgcn_readfirstlane(tid >> 6), lane = tid & 63, wr = wid >> 2, wc = wid & 3, fr = lane & 15, fq = lane >> 4;
;     const int nt = K / BK;
;     unsigned voffA[2], voffB[2];
; #pragma unroll
;     for (int i = 0; i < 2; ++i) { int R, C; stage_rc(tid * 16 + i * 8192, R, C); const int Rb = (R & ~31) + perm32(R & 31);
;         voffA[i] = (unsigned)(R * K + C) * 2u; voffB[i] = (unsigned)(Rb * K + C) * 2u; }
;     const size_t kstep = (size_t)(BK * 2);
;     const size_t hstep = (size_t)HALF * K * 2;
;     const unsigned ldsw = (unsigned)wid * 1024u;
;     const int aoff = lds_byte(wr * 64 + fr, fq * 8), boff = lds_byte(wc * 32 + fr, fq * 8);
;     ...
;     Unit cur, nxt; int ui = 0;
;     if (!S.next(0, cur)) return;
;     f32x4 acc[2][2][4][2];
; #pragma unroll
;     for (int a = 0; a < 2; ++a)
; #pragma unroll
;         for (int b = 0; b < 2; ++b)
; #pragma unroll
;             for (int m = 0; m < 4; ++m)
; #pragma unroll
;                 for (int n = 0; n < 2; ++n) acc[a][b][m][n] = (f32x4){0.f, 0.f, 0.f, 0.f};
;     bf16x8 At[4][2], B0[2][2], B1[2][2];
;     const char* cA; const char* cB; P.get(cur, cA, cB);
;     PG8_STAGE(PG8_SB(0, 0), cB, voffB); PG8_STAGE(PG8_SA(0, 0), cA, voffA); PG8_STAGE(PG8_SB(0, 1), cB + hstep, voffB); PG8_STAGE(PG8_SA(0, 1), cA + hstep, voffA);
;     if (wr == 1) PG8_BAR;
;     PG8_WAIT_V(4); PG8_BAR;
;     PG8_STAGE(PG8_SB(1, 0), cB + kstep, voffB); PG8_STAGE(PG8_SA(1, 0), cA + kstep, voffA); PG8_STAGE(PG8_SB(1, 1), cB + hstep + kstep, voffB);
;     PG8_WAIT_V(6); PG8_BAR;
.LBB0_120:
	s_add_u32 s4, s28, 0x35000000
	s_addc_u32 s5, s29, 0
	s_mov_b64 s[58:59], 0x80
	v_writelane_b32 v254, s4, 0
	v_lshl_add_u64 v[6:7], v[6:7], 0, s[58:59]
	s_waitcnt vmcnt(4)
	s_barrier
	v_writelane_b32 v254, s5, 1
	s_add_u32 s4, s28, 0x26000000
	s_addc_u32 s5, s29, 0
	s_add_u32 s42, s28, 0x32000000
	s_addc_u32 s43, s29, 0
	s_add_u32 s44, s28, 0x2000000
	s_addc_u32 s45, s29, 0
	s_add_u32 s48, s26, 0xc000000
	s_addc_u32 s49, s27, 0
	s_add_u32 s54, s28, 0x3e000000
	s_addc_u32 s55, s29, 0
	s_add_u32 s56, s28, 0xe000000
	s_addc_u32 s57, s29, 0
	s_lshl_b32 s1, s1, 5
	s_and_b32 s88, s1, 0x60
	s_add_i32 m0, s67, 0x18000
	v_writelane_b32 v254, s4, 2
	s_ashr_i32 s86, s3, 31
	s_ashr_i32 s87, s2, 31
	s_lshl_b32 s20, s0, 13
	s_lshl_b32 s1, s88, 7
	global_load_lds_dwordx4 v[6:7], off
	v_lshl_add_u64 v[4:5], v[4:5], 0, s[58:59]
	s_add_i32 m0, s67, 0x1a000
	s_add_i32 s89, s67, 0x8000
	s_add_i32 s90, s67, 0xa000
	v_writelane_b32 v254, s5, 3
	global_load_lds_dwordx4 v[4:5], off
	v_lshl_add_u64 v[2:3], v[2:3], 0, s[58:59]
	s_mov_b32 m0, s89
	s_add_u32 s4, s78, 0x40080
	global_load_lds_dwordx4 v[2:3], off
	v_lshl_add_u64 v[0:1], v[0:1], 0, s[58:59]
	s_mov_b32 m0, s90
	s_addc_u32 s5, s79, 0
	global_load_lds_dwordx4 v[0:1], off
	s_add_i32 m0, s67, 0x1c000
	v_lshl_add_u64 v[0:1], s[4:5], 0, v[134:135]
	global_load_lds_dwordx4 v[0:1], off
	v_lshl_add_u64 v[0:1], s[4:5], 0, v[138:139]
	s_add_i32 m0, s67, 0x1e000
	v_lshlrev_b32_e32 v2, 6, v208
	global_load_lds_dwordx4 v[0:1], off
	v_and_b32_e32 v0, 15, v208
	v_lshlrev_b32_e32 v1, 1, v130
	s_movk_i32 s4, 0x3c0
	v_lshlrev_b32_e32 v3, 2, v208
	v_and_or_b32 v2, v2, s4, v1
	v_and_b32_e32 v3, 32, v3
	v_cmp_eq_u32_e64 s[10:11], 0, v0
	v_lshl_or_b32 v129, s0, 6, v0
	v_lshl_or_b32 v0, v0, 6, v1
	v_lshlrev_b32_e32 v1, 8, v208
	v_bitop3_b32 v131, s1, v2, v3 bitop3:0xf6
	v_and_b32_e32 v1, 0x38000, v1
	v_lshlrev_b32_e32 v2, 11, v10
	v_or3_b32 v1, v8, v1, v2
	v_add_u32_e32 v142, v1, v9
	v_lshlrev_b32_e32 v1, 4, v11
	s_waitcnt vmcnt(6)
	v_and_b32_e32 v1, 0x78000, v1
	v_bitop3_b32 v0, v0, s20, v3 bitop3:0xde
	v_or3_b32 v1, v8, v1, v2
	s_add_i32 s91, 0, 0x10000
	s_add_i32 s92, 0, 0x14000
	v_or_b32_e32 v204, s88, v130
	v_mov_b32_e32 v143, v141
	v_add_u32_e32 v144, v1, v9
	v_mov_b32_e32 v145, v141
	v_mov_b64_e32 v[146:147], 0x2100
	v_mov_b64_e32 v[148:149], 0x20ff
	v_add_u32_e32 v205, s91, v131
	v_add_u32_e32 v206, 0, v0
	v_add_u32_e32 v207, s92, v131
	s_mov_b32 s60, 0xbfb8aa3b
	s_lshl_b32 s62, s0, 2
	s_mov_b32 s64, 0x3dd2d3e7
	s_mov_b32 s66, 0xc0135761
	s_mov_b32 s93, 0x600000
	s_mov_b32 s94, 0x900000
	s_mov_b32 s95, 0x1800000
	s_mov_b32 s96, 0x1b00000
	s_mov_b32 s97, 0x1e00000
	s_mov_b32 s98, 0x2100000
	s_mov_b32 s99, 0x40000
	s_mov_b32 s22, 0x48000
	s_mov_b32 s23, 0x50000
	s_nop 0
	s_nop 0
	s_nop 0
	s_nop 0
	s_nop 0
	s_nop 0
	s_nop 0
	s_nop 0
	s_nop 0
	s_nop 0
	s_nop 0
	s_nop 0
	s_nop 0
	s_nop 0
	s_nop 0
	s_nop 0
	s_nop 0
	s_nop 0
	s_nop 0
	s_nop 0
	s_nop 0
	s_nop 0
	s_nop 0
	s_nop 0
	s_mov_b32 s24, 0
	s_cmpk_lt_u32 s61, 0x100
	s_cbranch_scc1 .Lsprio_0
	s_setprio 1

; #define PG8_STAGE(bufoff, gbase, voff) do { _Pragma("unroll") for (int _i = 0; _i < 2; ++_i) \
;         __builtin_amdgcn_global_load_lds((const unsigned*)((const char*)(gbase) + (voff)[_i]), (LAS unsigned*)(lds + (bufoff) + ldsw + _i * 8192), 16, 0, 0); } while (0)
; #define PG8_LDA(dst, b, h) do { _Pragma("unroll") for (int m = 0; m < 4; ++m) _Pragma("unroll") for (int k = 0; k < 2; ++k) dst[m][k] = *(const LAS bf16x8*)(lds + PG8_SA(b, h) + aoff + m * 2048 + k * 1024); } while (0)
; #define PG8_LDB(dst, b, h) do { _Pragma("unroll") for (int n = 0; n < 2; ++n) _Pragma("unroll") for (int k = 0; k < 2; ++k) dst[n][k] = *(const LAS bf16x8*)(lds + PG8_SB(b, h) + boff + n * 2048 + k * 1024); } while (0)
; #define PG8_WAIT_V(n) asm volatile("s_waitcnt vmcnt(" #n ")" ::: "memory")
; #define PG8_WAIT_L(n) asm volatile("s_waitcnt lgkmcnt(" #n ")" ::: "memory")
; #define PG8_BAR __builtin_amdgcn_s_barrier()
; template <class Epi, class Ptrs>
; __device__ __forceinline__ void gemm_phase(LAS unsigned char* lds, const int K, const StaticOrder& S, const Ptrs& P, const Epi& E) {
;     ...
;         for (int t = 0; t < nt; t += 2) {
;             const bool last = (t == nt - 2);
;             const char* a1 = cA + (size_t)(t + 1) * kstep;
;             const char* a2 = last ? nA : cA + (size_t)(t + 2) * kstep; const char* b2 = last ? nB : cB + (size_t)(t + 2) * kstep;
;             const char* a3 = a2 + kstep; const char* b3 = b2 + kstep;
;             PG8_LDB(B0, 0, 0); PG8_SCHED; PG8_LDA(At, 0, 0); PG8_STAGE(PG8_SA(1, 1), a1 + hstep, voffA);
;             PG8_WAIT_L(8); PG8_BAR; PG8_WAIT_L(0); PG8_MMA(0, 0, At, B0); PG8_BAR; PG8_SCHED;
;             PG8_LDB(B1, 0, 1); PG8_STAGE(PG8_SB(0, 0), b2, voffB);
;             PG8_BAR; PG8_WAIT_L(0); PG8_MMA(0, 1, At, B1); PG8_BAR;
;             PG8_LDA(At, 0, 1); PG8_STAGE(PG8_SA(0, 0), a2, voffA);
;             PG8_BAR; PG8_WAIT_L(0); PG8_MMA(1, 0, At, B0); PG8_BAR; PG8_SCHED;
;             PG8_STAGE(PG8_SB(0, 1), b2 + hstep, voffB);
;             PG8_WAIT_V(6); PG8_BAR; PG8_MMA(1, 1, At, B1); PG8_BAR;
;     ...
; #pragma unroll
;         for (int a = 0; a < 2; ++a)
; #pragma unroll
;             for (int b = 0; b < 2; ++b)
; #pragma unroll
;                 for (int m = 0; m < 4; ++m)
; #pragma unroll
;                     for (int n = 0; n < 2; ++n) acc[a][b][m][n] = (f32x4){0.f, 0.f, 0.f, 0.f};
.LBB0_126:
	s_add_u32 s6, s6, 0x40080
	s_addc_u32 s7, s7, 0
	s_add_u32 s20, s78, 0x100
	s_addc_u32 s25, s79, 0
	s_mov_b32 s63, -2
	v_add_u32_e32 v252, 0x18000, v131
	v_add_u32_e32 v253, 0x1c000, v131
	ds_read_b128 v[150:153], v205
	ds_read_b128 v[154:157], v205 offset:1024
	ds_read_b128 v[158:161], v205 offset:2048
	ds_read_b128 v[162:165], v205 offset:3072
	s_add_u32 s69, s6, 0xfffc0080
	s_addc_u32 s71, s7, -1
	s_cmp_eq_u32 s63, 12
	s_cselect_b32 s81, s1, s71
	s_cselect_b32 s80, s0, s69
	s_cselect_b32 s79, s73, s25
	s_cselect_b32 s78, s72, s20
	s_add_i32 m0, s67, 0xc000
	ds_read_b128 v[166:169], v206
	ds_read_b128 v[170:173], v206 offset:1024
	ds_read_b128 v[174:177], v206 offset:2048
	ds_read_b128 v[178:181], v206 offset:3072
	ds_read_b128 v[182:185], v206 offset:4096
	ds_read_b128 v[186:189], v206 offset:5120
	ds_read_b128 v[190:193], v206 offset:6144
	ds_read_b128 v[194:197], v206 offset:7168
	global_load_lds_dwordx4 v142, s[6:7]
	s_add_i32 m0, s67, 0xe000
	s_nop 0
	global_load_lds_dwordx4 v144, s[6:7]
	s_waitcnt lgkmcnt(8)
	s_barrier
	s_waitcnt lgkmcnt(0)
	v_mfma_f32_16x16x32_bf16 v[120:123], v[150:153], v[166:169], 0
	v_mfma_f32_16x16x32_bf16 v[120:123], v[154:157], v[170:173], v[120:123]
	v_mfma_f32_16x16x32_bf16 v[116:119], v[162:165], v[170:173], 0
	v_mfma_f32_16x16x32_bf16 v[116:119], v[158:161], v[166:169], v[116:119]
	v_mfma_f32_16x16x32_bf16 v[100:103], v[158:161], v[174:177], 0
	v_mfma_f32_16x16x32_bf16 v[100:103], v[162:165], v[178:181], v[100:103]
	v_mfma_f32_16x16x32_bf16 v[104:107], v[154:157], v[178:181], 0
	v_mfma_f32_16x16x32_bf16 v[104:107], v[150:153], v[174:177], v[104:107]
	v_mfma_f32_16x16x32_bf16 v[88:91], v[150:153], v[182:185], 0
	v_mfma_f32_16x16x32_bf16 v[88:91], v[154:157], v[186:189], v[88:91]
	v_mfma_f32_16x16x32_bf16 v[84:87], v[162:165], v[186:189], 0
	v_mfma_f32_16x16x32_bf16 v[84:87], v[158:161], v[182:185], v[84:87]
	v_mfma_f32_16x16x32_bf16 v[68:71], v[158:161], v[190:193], 0
	v_mfma_f32_16x16x32_bf16 v[68:71], v[162:165], v[194:197], v[68:71]
	v_mfma_f32_16x16x32_bf16 v[72:75], v[154:157], v[194:197], 0
	v_mfma_f32_16x16x32_bf16 v[72:75], v[150:153], v[190:193], v[72:75]
	s_barrier
	s_add_i32 s69, s91, s65
	s_add_u32 s100, s78, 0x80
	s_addc_u32 s101, s79, 0
	s_mov_b32 m0, s69
	ds_read_b128 v[198:201], v207
	ds_read_b128 v[210:213], v207 offset:1024
	ds_read_b128 v[214:217], v207 offset:2048
	ds_read_b128 v[218:221], v207 offset:3072
	global_load_lds_dwordx4 v134, s[78:79]
	s_add_i32 m0, s69, 0x2000
	s_nop 0
	global_load_lds_dwordx4 v138, s[78:79]
	s_barrier
	s_waitcnt lgkmcnt(0)
	v_mfma_f32_16x16x32_bf16 v[124:127], v[198:201], v[166:169], 0
	v_mfma_f32_16x16x32_bf16 v[124:127], v[210:213], v[170:173], v[124:127]
	v_mfma_f32_16x16x32_bf16 v[112:115], v[218:221], v[170:173], 0
	v_mfma_f32_16x16x32_bf16 v[112:115], v[214:217], v[166:169], v[112:115]
	v_mfma_f32_16x16x32_bf16 v[96:99], v[214:217], v[174:177], 0
	v_mfma_f32_16x16x32_bf16 v[96:99], v[218:221], v[178:181], v[96:99]
	v_mfma_f32_16x16x32_bf16 v[108:111], v[210:213], v[178:181], 0
	v_mfma_f32_16x16x32_bf16 v[108:111], v[198:201], v[174:177], v[108:111]
	v_mfma_f32_16x16x32_bf16 v[92:95], v[198:201], v[182:185], 0
	v_mfma_f32_16x16x32_bf16 v[92:95], v[210:213], v[186:189], v[92:95]
	v_mfma_f32_16x16x32_bf16 v[80:83], v[218:221], v[186:189], 0
	v_mfma_f32_16x16x32_bf16 v[80:83], v[214:217], v[182:185], v[80:83]
	v_mfma_f32_16x16x32_bf16 v[64:67], v[214:217], v[190:193], 0
	v_mfma_f32_16x16x32_bf16 v[64:67], v[218:221], v[194:197], v[64:67]
	v_mfma_f32_16x16x32_bf16 v[76:79], v[210:213], v[194:197], 0
	v_mfma_f32_16x16x32_bf16 v[76:79], v[198:201], v[190:193], v[76:79]
	s_barrier
	s_mov_b32 m0, s67
	ds_read_b128 v[166:169], v206 offset:16384
	ds_read_b128 v[170:173], v206 offset:17408
	ds_read_b128 v[174:177], v206 offset:18432
	ds_read_b128 v[178:181], v206 offset:19456
	ds_read_b128 v[182:185], v206 offset:20480
	ds_read_b128 v[186:189], v206 offset:21504
	ds_read_b128 v[190:193], v206 offset:22528
	ds_read_b128 v[194:197], v206 offset:23552
	global_load_lds_dwordx4 v132, s[80:81]
	s_mov_b32 m0, s75
	s_nop 0
	global_load_lds_dwordx4 v136, s[80:81]
	s_barrier
	s_waitcnt lgkmcnt(0)
	v_mfma_f32_16x16x32_bf16 v[56:59], v[150:153], v[166:169], 0
	v_mfma_f32_16x16x32_bf16 v[56:59], v[154:157], v[170:173], v[56:59]
	v_mfma_f32_16x16x32_bf16 v[52:55], v[162:165], v[170:173], 0
	v_mfma_f32_16x16x32_bf16 v[52:55], v[158:161], v[166:169], v[52:55]
	v_mfma_f32_16x16x32_bf16 v[36:39], v[158:161], v[174:177], 0
	v_mfma_f32_16x16x32_bf16 v[36:39], v[162:165], v[178:181], v[36:39]
	v_mfma_f32_16x16x32_bf16 v[40:43], v[154:157], v[178:181], 0
	v_mfma_f32_16x16x32_bf16 v[40:43], v[150:153], v[174:177], v[40:43]
	v_mfma_f32_16x16x32_bf16 v[24:27], v[150:153], v[182:185], 0
	v_mfma_f32_16x16x32_bf16 v[24:27], v[154:157], v[186:189], v[24:27]
	v_mfma_f32_16x16x32_bf16 v[20:23], v[162:165], v[186:189], 0
	v_mfma_f32_16x16x32_bf16 v[20:23], v[158:161], v[182:185], v[20:23]
	v_mfma_f32_16x16x32_bf16 v[4:7], v[158:161], v[190:193], 0
	v_mfma_f32_16x16x32_bf16 v[4:7], v[162:165], v[194:197], v[4:7]
	v_mfma_f32_16x16x32_bf16 v[8:11], v[154:157], v[194:197], 0
	v_mfma_f32_16x16x32_bf16 v[8:11], v[150:153], v[190:193], v[8:11]
	s_barrier
	s_add_u32 s82, s78, 0x40000
	s_addc_u32 s83, s79, 0
	s_add_i32 s69, s92, s65
	s_mov_b32 m0, s69
	s_nop 0
	global_load_lds_dwordx4 v134, s[82:83]
	s_add_i32 m0, s69, 0x2000
	s_nop 0
	global_load_lds_dwordx4 v138, s[82:83]
	s_waitcnt vmcnt(6)
	s_barrier
; #define PG8_STAGE(bufoff, gbase, voff) do { _Pragma("unroll") for (int _i = 0; _i < 2; ++_i) \
;         __builtin_amdgcn_global_load_lds((const unsigned*)((const char*)(gbase) + (voff)[_i]), (LAS unsigned*)(lds + (bufoff) + ldsw + _i * 8192), 16, 0, 0); } while (0)
; #define PG8_LDA(dst, b, h) do { _Pragma("unroll") for (int m = 0; m < 4; ++m) _Pragma("unroll") for (int k = 0; k < 2; ++k) dst[m][k] = *(const LAS bf16x8*)(lds + PG8_SA(b, h) + aoff + m * 2048 + k * 1024); } while (0)
; #define PG8_LDB(dst, b, h) do { _Pragma("unroll") for (int n = 0; n < 2; ++n) _Pragma("unroll") for (int k = 0; k < 2; ++k) dst[n][k] = *(const LAS bf16x8*)(lds + PG8_SB(b, h) + boff + n * 2048 + k * 1024); } while (0)
; #define PG8_MMA(ai, bj, At, Bt) do { __builtin_amdgcn_s_setprio(1); _Pragma("unroll") for (int m = 0; m < 4; ++m) _Pragma("unroll") for (int n = 0; n < 2; ++n) _Pragma("unroll") for (int k = 0; k < 2; ++k) \
;         acc[ai][bj][m][n] = __builtin_amdgcn_mfma_f32_16x16x32_bf16(Bt[n][k], At[m][k], acc[ai][bj][m][n], 0, 0, 0); __builtin_amdgcn_s_setprio(0); } while (0)
; #define PG8_WAIT_V(n) asm volatile("s_waitcnt vmcnt(" #n ")" ::: "memory")
; #define PG8_WAIT_L(n) asm volatile("s_waitcnt lgkmcnt(" #n ")" ::: "memory")
; #define PG8_BAR __builtin_amdgcn_s_barrier()
; #define PG8_SCHED __builtin_amdgcn_sched_barrier(0)
; template <class Epi, class Ptrs>
; __device__ __forceinline__ void gemm_phase(LAS unsigned char* lds, const int K, const StaticOrder& S, const Ptrs& P, const Epi& E) {
;     ...
;             PG8_WAIT_V(6); PG8_BAR; PG8_MMA(1, 1, At, B1); PG8_BAR;
;             PG8_LDB(B0, 1, 0); PG8_SCHED; PG8_LDA(At, 1, 0); PG8_STAGE(PG8_SA(0, 1), a2 + hstep, voffA);
;             PG8_WAIT_L(8); PG8_BAR; PG8_WAIT_L(0); PG8_MMA(0, 0, At, B0); PG8_BAR; PG8_SCHED;
;             PG8_LDB(B1, 1, 1); PG8_STAGE(PG8_SB(1, 0), b3, voffB);
;             PG8_BAR; PG8_WAIT_L(0); PG8_MMA(0, 1, At, B1); PG8_BAR;
;             PG8_LDA(At, 1, 1); PG8_STAGE(PG8_SA(1, 0), a3, voffA);
;             PG8_BAR; PG8_WAIT_L(0); PG8_MMA(1, 0, At, B0); PG8_BAR; PG8_SCHED;
	v_mfma_f32_16x16x32_bf16 v[60:63], v[198:201], v[166:169], 0
	v_mfma_f32_16x16x32_bf16 v[60:63], v[210:213], v[170:173], v[60:63]
	v_mfma_f32_16x16x32_bf16 v[48:51], v[218:221], v[170:173], 0
	v_mfma_f32_16x16x32_bf16 v[48:51], v[214:217], v[166:169], v[48:51]
	v_mfma_f32_16x16x32_bf16 v[32:35], v[214:217], v[174:177], 0
	v_mfma_f32_16x16x32_bf16 v[32:35], v[218:221], v[178:181], v[32:35]
	v_mfma_f32_16x16x32_bf16 v[44:47], v[210:213], v[178:181], 0
	v_mfma_f32_16x16x32_bf16 v[44:47], v[198:201], v[174:177], v[44:47]
	v_mfma_f32_16x16x32_bf16 v[28:31], v[198:201], v[182:185], 0
	v_mfma_f32_16x16x32_bf16 v[28:31], v[210:213], v[186:189], v[28:31]
	v_mfma_f32_16x16x32_bf16 v[16:19], v[218:221], v[186:189], 0
	v_mfma_f32_16x16x32_bf16 v[16:19], v[214:217], v[182:185], v[16:19]
	v_mfma_f32_16x16x32_bf16 v[0:3], v[214:217], v[190:193], 0
	v_mfma_f32_16x16x32_bf16 v[0:3], v[218:221], v[194:197], v[0:3]
	v_mfma_f32_16x16x32_bf16 v[12:15], v[210:213], v[194:197], 0
	v_mfma_f32_16x16x32_bf16 v[12:15], v[198:201], v[190:193], v[12:15]
	s_barrier
	s_add_i32 s69, 0, 0x18000
	ds_read_b128 v[150:153], v252
	ds_read_b128 v[154:157], v252 offset:1024
	ds_read_b128 v[158:161], v252 offset:2048
	ds_read_b128 v[162:165], v252 offset:3072
	s_add_u32 s80, s80, 0x40000
	s_addc_u32 s81, s81, 0
	s_mov_b32 m0, s77
	ds_read_b128 v[166:169], v206 offset:32768
	ds_read_b128 v[170:173], v206 offset:33792
	ds_read_b128 v[174:177], v206 offset:34816
	ds_read_b128 v[178:181], v206 offset:35840
	ds_read_b128 v[182:185], v206 offset:36864
	ds_read_b128 v[186:189], v206 offset:37888
	ds_read_b128 v[190:193], v206 offset:38912
	ds_read_b128 v[194:197], v206 offset:39936
	global_load_lds_dwordx4 v132, s[80:81]
	s_mov_b32 m0, s85
	s_nop 0
	global_load_lds_dwordx4 v136, s[80:81]
	s_waitcnt lgkmcnt(8)
	s_barrier
	s_waitcnt lgkmcnt(0)
	v_mfma_f32_16x16x32_bf16 v[120:123], v[150:153], v[166:169], v[120:123]
	v_mfma_f32_16x16x32_bf16 v[120:123], v[154:157], v[170:173], v[120:123]
	v_mfma_f32_16x16x32_bf16 v[116:119], v[162:165], v[170:173], v[116:119]
	v_mfma_f32_16x16x32_bf16 v[116:119], v[158:161], v[166:169], v[116:119]
	v_mfma_f32_16x16x32_bf16 v[100:103], v[158:161], v[174:177], v[100:103]
	v_mfma_f32_16x16x32_bf16 v[100:103], v[162:165], v[178:181], v[100:103]
	v_mfma_f32_16x16x32_bf16 v[104:107], v[154:157], v[178:181], v[104:107]
	v_mfma_f32_16x16x32_bf16 v[104:107], v[150:153], v[174:177], v[104:107]
	v_mfma_f32_16x16x32_bf16 v[88:91], v[150:153], v[182:185], v[88:91]
	v_mfma_f32_16x16x32_bf16 v[88:91], v[154:157], v[186:189], v[88:91]
	v_mfma_f32_16x16x32_bf16 v[84:87], v[162:165], v[186:189], v[84:87]
	v_mfma_f32_16x16x32_bf16 v[84:87], v[158:161], v[182:185], v[84:87]
	v_mfma_f32_16x16x32_bf16 v[68:71], v[158:161], v[190:193], v[68:71]
	v_mfma_f32_16x16x32_bf16 v[68:71], v[162:165], v[194:197], v[68:71]
	v_mfma_f32_16x16x32_bf16 v[72:75], v[154:157], v[194:197], v[72:75]
	v_mfma_f32_16x16x32_bf16 v[72:75], v[150:153], v[190:193], v[72:75]
	s_barrier
	s_add_i32 s71, 0, 0x1c000
	s_add_i32 s69, s69, s65
	s_mov_b32 m0, s69
	ds_read_b128 v[198:201], v253
	ds_read_b128 v[210:213], v253 offset:1024
	ds_read_b128 v[214:217], v253 offset:2048
	ds_read_b128 v[218:221], v253 offset:3072
	global_load_lds_dwordx4 v134, s[100:101]
	s_add_i32 m0, s69, 0x2000
	s_nop 0
	global_load_lds_dwordx4 v138, s[100:101]
	s_barrier
	s_waitcnt lgkmcnt(0)
	v_mfma_f32_16x16x32_bf16 v[124:127], v[198:201], v[166:169], v[124:127]
	v_mfma_f32_16x16x32_bf16 v[124:127], v[210:213], v[170:173], v[124:127]
	v_mfma_f32_16x16x32_bf16 v[112:115], v[218:221], v[170:173], v[112:115]
	v_mfma_f32_16x16x32_bf16 v[112:115], v[214:217], v[166:169], v[112:115]
	v_mfma_f32_16x16x32_bf16 v[96:99], v[214:217], v[174:177], v[96:99]
	v_mfma_f32_16x16x32_bf16 v[96:99], v[218:221], v[178:181], v[96:99]
	v_mfma_f32_16x16x32_bf16 v[108:111], v[210:213], v[178:181], v[108:111]
	v_mfma_f32_16x16x32_bf16 v[108:111], v[198:201], v[174:177], v[108:111]
	v_mfma_f32_16x16x32_bf16 v[92:95], v[198:201], v[182:185], v[92:95]
	v_mfma_f32_16x16x32_bf16 v[92:95], v[210:213], v[186:189], v[92:95]
	v_mfma_f32_16x16x32_bf16 v[80:83], v[218:221], v[186:189], v[80:83]
	v_mfma_f32_16x16x32_bf16 v[80:83], v[214:217], v[182:185], v[80:83]
	v_mfma_f32_16x16x32_bf16 v[64:67], v[214:217], v[190:193], v[64:67]
	v_mfma_f32_16x16x32_bf16 v[64:67], v[218:221], v[194:197], v[64:67]
	v_mfma_f32_16x16x32_bf16 v[76:79], v[210:213], v[194:197], v[76:79]
	v_mfma_f32_16x16x32_bf16 v[76:79], v[198:201], v[190:193], v[76:79]
	s_barrier
	s_mov_b32 m0, s89
	s_add_u32 s100, s80, 0xfffc0080
	s_addc_u32 s101, s81, -1
	ds_read_b128 v[166:169], v206 offset:49152
	ds_read_b128 v[170:173], v206 offset:50176
	ds_read_b128 v[174:177], v206 offset:51200
	ds_read_b128 v[178:181], v206 offset:52224
	ds_read_b128 v[182:185], v206 offset:53248
	ds_read_b128 v[186:189], v206 offset:54272
	ds_read_b128 v[190:193], v206 offset:55296
	ds_read_b128 v[194:197], v206 offset:56320
	global_load_lds_dwordx4 v132, s[100:101]
	s_mov_b32 m0, s90
	s_nop 0
	global_load_lds_dwordx4 v136, s[100:101]
	s_barrier
	s_waitcnt lgkmcnt(0)
	v_mfma_f32_16x16x32_bf16 v[56:59], v[150:153], v[166:169], v[56:59]
	v_mfma_f32_16x16x32_bf16 v[56:59], v[154:157], v[170:173], v[56:59]
	v_mfma_f32_16x16x32_bf16 v[52:55], v[162:165], v[170:173], v[52:55]
	v_mfma_f32_16x16x32_bf16 v[52:55], v[158:161], v[166:169], v[52:55]
	v_mfma_f32_16x16x32_bf16 v[36:39], v[158:161], v[174:177], v[36:39]
	v_mfma_f32_16x16x32_bf16 v[36:39], v[162:165], v[178:181], v[36:39]
	v_mfma_f32_16x16x32_bf16 v[40:43], v[154:157], v[178:181], v[40:43]
	v_mfma_f32_16x16x32_bf16 v[40:43], v[150:153], v[174:177], v[40:43]
	v_mfma_f32_16x16x32_bf16 v[24:27], v[150:153], v[182:185], v[24:27]
	v_mfma_f32_16x16x32_bf16 v[24:27], v[154:157], v[186:189], v[24:27]
	v_mfma_f32_16x16x32_bf16 v[20:23], v[162:165], v[186:189], v[20:23]
	v_mfma_f32_16x16x32_bf16 v[20:23], v[158:161], v[182:185], v[20:23]
	v_mfma_f32_16x16x32_bf16 v[4:7], v[158:161], v[190:193], v[4:7]
	v_mfma_f32_16x16x32_bf16 v[4:7], v[162:165], v[194:197], v[4:7]
	v_mfma_f32_16x16x32_bf16 v[8:11], v[154:157], v[194:197], v[8:11]
	v_mfma_f32_16x16x32_bf16 v[8:11], v[150:153], v[190:193], v[8:11]
	s_barrier
; #define PG8_STAGE(bufoff, gbase, voff) do { _Pragma("unroll") for (int _i = 0; _i < 2; ++_i) \
;         __builtin_amdgcn_global_load_lds((const unsigned*)((const char*)(gbase) + (voff)[_i]), (LAS unsigned*)(lds + (bufoff) + ldsw + _i * 8192), 16, 0, 0); } while (0)
; #define PG8_LDA(dst, b, h) do { _Pragma("unroll") for (int m = 0; m < 4; ++m) _Pragma("unroll") for (int k = 0; k < 2; ++k) dst[m][k] = *(const LAS bf16x8*)(lds + PG8_SA(b, h) + aoff + m * 2048 + k * 1024); } while (0)
; #define PG8_WAIT_V(n) asm volatile("s_waitcnt vmcnt(" #n ")" ::: "memory")
; #define PG8_BAR __builtin_amdgcn_s_barrier()
; template <class Epi, class Ptrs>
; __device__ __forceinline__ void gemm_phase(LAS unsigned char* lds, const int K, const StaticOrder& S, const Ptrs& P, const Epi& E) {
;     ...
;         for (int t = 0; t < nt; t += 2) {
;             const bool last = (t == nt - 2);
;             const char* a1 = cA + (size_t)(t + 1) * kstep;
;             const char* a2 = last ? nA : cA + (size_t)(t + 2) * kstep; const char* b2 = last ? nB : cB + (size_t)(t + 2) * kstep;
;             const char* a3 = a2 + kstep; const char* b3 = b2 + kstep;
;             PG8_LDB(B0, 0, 0); PG8_SCHED; PG8_LDA(At, 0, 0); PG8_STAGE(PG8_SA(1, 1), a1 + hstep, voffA);
;             PG8_WAIT_L(8); PG8_BAR; PG8_WAIT_L(0); PG8_MMA(0, 0, At, B0); PG8_BAR; PG8_SCHED;
;             PG8_LDB(B1, 0, 1); PG8_STAGE(PG8_SB(0, 0), b2, voffB);
;             PG8_BAR; PG8_WAIT_L(0); PG8_MMA(0, 1, At, B1); PG8_BAR;
;             PG8_LDA(At, 0, 1); PG8_STAGE(PG8_SA(0, 0), a2, voffA);
;             PG8_BAR; PG8_WAIT_L(0); PG8_MMA(1, 0, At, B0); PG8_BAR; PG8_SCHED;
;             PG8_STAGE(PG8_SB(0, 1), b2 + hstep, voffB);
;             PG8_WAIT_V(6); PG8_BAR; PG8_MMA(1, 1, At, B1); PG8_BAR;
;             PG8_LDB(B0, 1, 0); PG8_SCHED; PG8_LDA(At, 1, 0); PG8_STAGE(PG8_SA(0, 1), a2 + hstep, voffA);
;             PG8_WAIT_L(8); PG8_BAR; PG8_WAIT_L(0); PG8_MMA(0, 0, At, B0); PG8_BAR; PG8_SCHED;
;             PG8_LDB(B1, 1, 1); PG8_STAGE(PG8_SB(1, 0), b3, voffB);
;             PG8_BAR; PG8_WAIT_L(0); PG8_MMA(0, 1, At, B1); PG8_BAR;
;             PG8_LDA(At, 1, 1); PG8_STAGE(PG8_SA(1, 0), a3, voffA);
;             PG8_BAR; PG8_WAIT_L(0); PG8_MMA(1, 0, At, B0); PG8_BAR; PG8_SCHED;
;             PG8_STAGE(PG8_SB(1, 1), b3 + hstep, voffB);
;             PG8_WAIT_V(6); PG8_BAR; PG8_MMA(1, 1, At, B1); PG8_BAR;
	s_add_u32 s78, s78, 0x40080
	s_addc_u32 s79, s79, 0
	s_add_i32 s69, s71, s65
	s_mov_b32 m0, s69
	s_nop 0
	global_load_lds_dwordx4 v134, s[78:79]
	s_add_i32 m0, s69, 0x2000
	s_nop 0
	global_load_lds_dwordx4 v138, s[78:79]
	s_waitcnt vmcnt(6)
	s_barrier
	v_mfma_f32_16x16x32_bf16 v[60:63], v[198:201], v[166:169], v[60:63]
	v_mfma_f32_16x16x32_bf16 v[60:63], v[210:213], v[170:173], v[60:63]
	v_mfma_f32_16x16x32_bf16 v[48:51], v[218:221], v[170:173], v[48:51]
	v_mfma_f32_16x16x32_bf16 v[48:51], v[214:217], v[166:169], v[48:51]
	v_mfma_f32_16x16x32_bf16 v[32:35], v[214:217], v[174:177], v[32:35]
	v_mfma_f32_16x16x32_bf16 v[32:35], v[218:221], v[178:181], v[32:35]
	v_mfma_f32_16x16x32_bf16 v[44:47], v[210:213], v[178:181], v[44:47]
	v_mfma_f32_16x16x32_bf16 v[44:47], v[198:201], v[174:177], v[44:47]
	v_mfma_f32_16x16x32_bf16 v[28:31], v[198:201], v[182:185], v[28:31]
	v_mfma_f32_16x16x32_bf16 v[28:31], v[210:213], v[186:189], v[28:31]
	v_mfma_f32_16x16x32_bf16 v[16:19], v[218:221], v[186:189], v[16:19]
	v_mfma_f32_16x16x32_bf16 v[16:19], v[214:217], v[182:185], v[16:19]
	v_mfma_f32_16x16x32_bf16 v[0:3], v[214:217], v[190:193], v[0:3]
	v_mfma_f32_16x16x32_bf16 v[0:3], v[218:221], v[194:197], v[0:3]
	v_mfma_f32_16x16x32_bf16 v[12:15], v[210:213], v[194:197], v[12:15]
	v_mfma_f32_16x16x32_bf16 v[12:15], v[198:201], v[190:193], v[12:15]
	s_barrier
	s_add_i32 s63, s63, 2
	s_add_u32 s6, s6, 0x100
	s_addc_u32 s7, s7, 0
	s_add_u32 s20, s20, 0x100
	s_addc_u32 s25, s25, 0
	s_cmp_gt_u32 s63, 13
.LBB0_127:
	ds_read_b128 v[150:153], v205
	ds_read_b128 v[154:157], v205 offset:1024
	ds_read_b128 v[158:161], v205 offset:2048
	ds_read_b128 v[162:165], v205 offset:3072
	s_add_u32 s69, s6, 0xfffc0080
	s_addc_u32 s71, s7, -1
	s_cmp_eq_u32 s63, 12
	s_cselect_b32 s81, s1, s71
	s_cselect_b32 s80, s0, s69
	s_cselect_b32 s79, s73, s25
	s_cselect_b32 s78, s72, s20
	s_add_i32 m0, s67, 0xc000
	ds_read_b128 v[166:169], v206
	ds_read_b128 v[170:173], v206 offset:1024
	ds_read_b128 v[174:177], v206 offset:2048
	ds_read_b128 v[178:181], v206 offset:3072
	ds_read_b128 v[182:185], v206 offset:4096
	ds_read_b128 v[186:189], v206 offset:5120
	ds_read_b128 v[190:193], v206 offset:6144
	ds_read_b128 v[194:197], v206 offset:7168
	global_load_lds_dwordx4 v142, s[6:7]
	s_add_i32 m0, s67, 0xe000
	s_nop 0
	global_load_lds_dwordx4 v144, s[6:7]
	s_waitcnt lgkmcnt(8)
	s_barrier
	s_waitcnt lgkmcnt(0)
	v_mfma_f32_16x16x32_bf16 v[120:123], v[150:153], v[166:169], v[120:123]
	v_mfma_f32_16x16x32_bf16 v[120:123], v[154:157], v[170:173], v[120:123]
	v_mfma_f32_16x16x32_bf16 v[116:119], v[162:165], v[170:173], v[116:119]
	v_mfma_f32_16x16x32_bf16 v[116:119], v[158:161], v[166:169], v[116:119]
	v_mfma_f32_16x16x32_bf16 v[100:103], v[158:161], v[174:177], v[100:103]
	v_mfma_f32_16x16x32_bf16 v[100:103], v[162:165], v[178:181], v[100:103]
	v_mfma_f32_16x16x32_bf16 v[104:107], v[154:157], v[178:181], v[104:107]
	v_mfma_f32_16x16x32_bf16 v[104:107], v[150:153], v[174:177], v[104:107]
	v_mfma_f32_16x16x32_bf16 v[88:91], v[150:153], v[182:185], v[88:91]
	v_mfma_f32_16x16x32_bf16 v[88:91], v[154:157], v[186:189], v[88:91]
	v_mfma_f32_16x16x32_bf16 v[84:87], v[162:165], v[186:189], v[84:87]
	v_mfma_f32_16x16x32_bf16 v[84:87], v[158:161], v[182:185], v[84:87]
	v_mfma_f32_16x16x32_bf16 v[68:71], v[158:161], v[190:193], v[68:71]
	v_mfma_f32_16x16x32_bf16 v[68:71], v[162:165], v[194:197], v[68:71]
	v_mfma_f32_16x16x32_bf16 v[72:75], v[154:157], v[194:197], v[72:75]
	v_mfma_f32_16x16x32_bf16 v[72:75], v[150:153], v[190:193], v[72:75]
	s_barrier
	s_add_i32 s69, s91, s65
	s_add_u32 s100, s78, 0x80
	s_addc_u32 s101, s79, 0
	s_mov_b32 m0, s69
	ds_read_b128 v[198:201], v207
	ds_read_b128 v[210:213], v207 offset:1024
	ds_read_b128 v[214:217], v207 offset:2048
	ds_read_b128 v[218:221], v207 offset:3072
	global_load_lds_dwordx4 v134, s[78:79]
	s_add_i32 m0, s69, 0x2000
	s_nop 0
	global_load_lds_dwordx4 v138, s[78:79]
	s_barrier
	s_waitcnt lgkmcnt(0)
	v_mfma_f32_16x16x32_bf16 v[124:127], v[198:201], v[166:169], v[124:127]
	v_mfma_f32_16x16x32_bf16 v[124:127], v[210:213], v[170:173], v[124:127]
	v_mfma_f32_16x16x32_bf16 v[112:115], v[218:221], v[170:173], v[112:115]
	v_mfma_f32_16x16x32_bf16 v[112:115], v[214:217], v[166:169], v[112:115]
	v_mfma_f32_16x16x32_bf16 v[96:99], v[214:217], v[174:177], v[96:99]
	v_mfma_f32_16x16x32_bf16 v[96:99], v[218:221], v[178:181], v[96:99]
	v_mfma_f32_16x16x32_bf16 v[108:111], v[210:213], v[178:181], v[108:111]
	v_mfma_f32_16x16x32_bf16 v[108:111], v[198:201], v[174:177], v[108:111]
	v_mfma_f32_16x16x32_bf16 v[92:95], v[198:201], v[182:185], v[92:95]
	v_mfma_f32_16x16x32_bf16 v[92:95], v[210:213], v[186:189], v[92:95]
	v_mfma_f32_16x16x32_bf16 v[80:83], v[218:221], v[186:189], v[80:83]
	v_mfma_f32_16x16x32_bf16 v[80:83], v[214:217], v[182:185], v[80:83]
	v_mfma_f32_16x16x32_bf16 v[64:67], v[214:217], v[190:193], v[64:67]
	v_mfma_f32_16x16x32_bf16 v[64:67], v[218:221], v[194:197], v[64:67]
	v_mfma_f32_16x16x32_bf16 v[76:79], v[210:213], v[194:197], v[76:79]
	v_mfma_f32_16x16x32_bf16 v[76:79], v[198:201], v[190:193], v[76:79]
	s_barrier
	s_mov_b32 m0, s67
	ds_read_b128 v[166:169], v206 offset:16384
	ds_read_b128 v[170:173], v206 offset:17408
	ds_read_b128 v[174:177], v206 offset:18432
	ds_read_b128 v[178:181], v206 offset:19456
	ds_read_b128 v[182:185], v206 offset:20480
	ds_read_b128 v[186:189], v206 offset:21504
	ds_read_b128 v[190:193], v206 offset:22528
	ds_read_b128 v[194:197], v206 offset:23552
	global_load_lds_dwordx4 v132, s[80:81]
	s_mov_b32 m0, s75
	s_nop 0
	global_load_lds_dwordx4 v136, s[80:81]
	s_barrier
; #define PG8_STAGE(bufoff, gbase, voff) do { _Pragma("unroll") for (int _i = 0; _i < 2; ++_i) \
;         __builtin_amdgcn_global_load_lds((const unsigned*)((const char*)(gbase) + (voff)[_i]), (LAS unsigned*)(lds + (bufoff) + ldsw + _i * 8192), 16, 0, 0); } while (0)
; #define PG8_LDA(dst, b, h) do { _Pragma("unroll") for (int m = 0; m < 4; ++m) _Pragma("unroll") for (int k = 0; k < 2; ++k) dst[m][k] = *(const LAS bf16x8*)(lds + PG8_SA(b, h) + aoff + m * 2048 + k * 1024); } while (0)
; #define PG8_LDB(dst, b, h) do { _Pragma("unroll") for (int n = 0; n < 2; ++n) _Pragma("unroll") for (int k = 0; k < 2; ++k) dst[n][k] = *(const LAS bf16x8*)(lds + PG8_SB(b, h) + boff + n * 2048 + k * 1024); } while (0)
; #define PG8_MMA(ai, bj, At, Bt) do { __builtin_amdgcn_s_setprio(1); _Pragma("unroll") for (int m = 0; m < 4; ++m) _Pragma("unroll") for (int n = 0; n < 2; ++n) _Pragma("unroll") for (int k = 0; k < 2; ++k) \
;         acc[ai][bj][m][n] = __builtin_amdgcn_mfma_f32_16x16x32_bf16(Bt[n][k], At[m][k], acc[ai][bj][m][n], 0, 0, 0); __builtin_amdgcn_s_setprio(0); } while (0)
; #define PG8_WAIT_V(n) asm volatile("s_waitcnt vmcnt(" #n ")" ::: "memory")
; #define PG8_WAIT_L(n) asm volatile("s_waitcnt lgkmcnt(" #n ")" ::: "memory")
; #define PG8_BAR __builtin_amdgcn_s_barrier()
; #define PG8_SCHED __builtin_amdgcn_sched_barrier(0)
; template <class Epi, class Ptrs>
; __device__ __forceinline__ void gemm_phase(LAS unsigned char* lds, const int K, const StaticOrder& S, const Ptrs& P, const Epi& E) {
;     ...
;             PG8_BAR; PG8_WAIT_L(0); PG8_MMA(1, 0, At, B0); PG8_BAR; PG8_SCHED;
;             PG8_STAGE(PG8_SB(0, 1), b2 + hstep, voffB);
;             PG8_WAIT_V(6); PG8_BAR; PG8_MMA(1, 1, At, B1); PG8_BAR;
;             PG8_LDB(B0, 1, 0); PG8_SCHED; PG8_LDA(At, 1, 0); PG8_STAGE(PG8_SA(0, 1), a2 + hstep, voffA);
;             PG8_WAIT_L(8); PG8_BAR; PG8_WAIT_L(0); PG8_MMA(0, 0, At, B0); PG8_BAR; PG8_SCHED;
;             PG8_LDB(B1, 1, 1); PG8_STAGE(PG8_SB(1, 0), b3, voffB);
;             PG8_BAR; PG8_WAIT_L(0); PG8_MMA(0, 1, At, B1); PG8_BAR;
	s_waitcnt lgkmcnt(0)
	v_mfma_f32_16x16x32_bf16 v[56:59], v[150:153], v[166:169], v[56:59]
	v_mfma_f32_16x16x32_bf16 v[56:59], v[154:157], v[170:173], v[56:59]
	v_mfma_f32_16x16x32_bf16 v[52:55], v[162:165], v[170:173], v[52:55]
	v_mfma_f32_16x16x32_bf16 v[52:55], v[158:161], v[166:169], v[52:55]
	v_mfma_f32_16x16x32_bf16 v[36:39], v[158:161], v[174:177], v[36:39]
	v_mfma_f32_16x16x32_bf16 v[36:39], v[162:165], v[178:181], v[36:39]
	v_mfma_f32_16x16x32_bf16 v[40:43], v[154:157], v[178:181], v[40:43]
	v_mfma_f32_16x16x32_bf16 v[40:43], v[150:153], v[174:177], v[40:43]
	v_mfma_f32_16x16x32_bf16 v[24:27], v[150:153], v[182:185], v[24:27]
	v_mfma_f32_16x16x32_bf16 v[24:27], v[154:157], v[186:189], v[24:27]
	v_mfma_f32_16x16x32_bf16 v[20:23], v[162:165], v[186:189], v[20:23]
	v_mfma_f32_16x16x32_bf16 v[20:23], v[158:161], v[182:185], v[20:23]
	v_mfma_f32_16x16x32_bf16 v[4:7], v[158:161], v[190:193], v[4:7]
	v_mfma_f32_16x16x32_bf16 v[4:7], v[162:165], v[194:197], v[4:7]
	v_mfma_f32_16x16x32_bf16 v[8:11], v[154:157], v[194:197], v[8:11]
	v_mfma_f32_16x16x32_bf16 v[8:11], v[150:153], v[190:193], v[8:11]
	s_barrier
	s_add_u32 s82, s78, 0x40000
	s_addc_u32 s83, s79, 0
	s_add_i32 s69, s92, s65
	s_mov_b32 m0, s69
	s_nop 0
	global_load_lds_dwordx4 v134, s[82:83]
	s_add_i32 m0, s69, 0x2000
	s_nop 0
	global_load_lds_dwordx4 v138, s[82:83]
	s_waitcnt vmcnt(6)
	s_barrier
	v_mfma_f32_16x16x32_bf16 v[60:63], v[198:201], v[166:169], v[60:63]
	v_mfma_f32_16x16x32_bf16 v[60:63], v[210:213], v[170:173], v[60:63]
	v_mfma_f32_16x16x32_bf16 v[48:51], v[218:221], v[170:173], v[48:51]
	v_mfma_f32_16x16x32_bf16 v[48:51], v[214:217], v[166:169], v[48:51]
	v_mfma_f32_16x16x32_bf16 v[32:35], v[214:217], v[174:177], v[32:35]
	v_mfma_f32_16x16x32_bf16 v[32:35], v[218:221], v[178:181], v[32:35]
	v_mfma_f32_16x16x32_bf16 v[44:47], v[210:213], v[178:181], v[44:47]
	v_mfma_f32_16x16x32_bf16 v[44:47], v[198:201], v[174:177], v[44:47]
	v_mfma_f32_16x16x32_bf16 v[28:31], v[198:201], v[182:185], v[28:31]
	v_mfma_f32_16x16x32_bf16 v[28:31], v[210:213], v[186:189], v[28:31]
	v_mfma_f32_16x16x32_bf16 v[16:19], v[218:221], v[186:189], v[16:19]
	v_mfma_f32_16x16x32_bf16 v[16:19], v[214:217], v[182:185], v[16:19]
	v_mfma_f32_16x16x32_bf16 v[0:3], v[214:217], v[190:193], v[0:3]
	v_mfma_f32_16x16x32_bf16 v[0:3], v[218:221], v[194:197], v[0:3]
	v_mfma_f32_16x16x32_bf16 v[12:15], v[210:213], v[194:197], v[12:15]
	v_mfma_f32_16x16x32_bf16 v[12:15], v[198:201], v[190:193], v[12:15]
	s_barrier
	s_add_i32 s69, 0, 0x18000
	ds_read_b128 v[150:153], v252
	ds_read_b128 v[154:157], v252 offset:1024
	ds_read_b128 v[158:161], v252 offset:2048
	ds_read_b128 v[162:165], v252 offset:3072
	s_add_u32 s80, s80, 0x40000
	s_addc_u32 s81, s81, 0
	s_mov_b32 m0, s77
	ds_read_b128 v[166:169], v206 offset:32768
	ds_read_b128 v[170:173], v206 offset:33792
	ds_read_b128 v[174:177], v206 offset:34816
	ds_read_b128 v[178:181], v206 offset:35840
	ds_read_b128 v[182:185], v206 offset:36864
	ds_read_b128 v[186:189], v206 offset:37888
	ds_read_b128 v[190:193], v206 offset:38912
	ds_read_b128 v[194:197], v206 offset:39936
	global_load_lds_dwordx4 v132, s[80:81]
	s_mov_b32 m0, s85
	s_nop 0
	global_load_lds_dwordx4 v136, s[80:81]
	s_waitcnt lgkmcnt(8)
	s_barrier
	s_waitcnt lgkmcnt(0)
	v_mfma_f32_16x16x32_bf16 v[120:123], v[150:153], v[166:169], v[120:123]
	v_mfma_f32_16x16x32_bf16 v[120:123], v[154:157], v[170:173], v[120:123]
	v_mfma_f32_16x16x32_bf16 v[116:119], v[162:165], v[170:173], v[116:119]
	v_mfma_f32_16x16x32_bf16 v[116:119], v[158:161], v[166:169], v[116:119]
	v_mfma_f32_16x16x32_bf16 v[100:103], v[158:161], v[174:177], v[100:103]
	v_mfma_f32_16x16x32_bf16 v[100:103], v[162:165], v[178:181], v[100:103]
	v_mfma_f32_16x16x32_bf16 v[104:107], v[154:157], v[178:181], v[104:107]
	v_mfma_f32_16x16x32_bf16 v[104:107], v[150:153], v[174:177], v[104:107]
	v_mfma_f32_16x16x32_bf16 v[88:91], v[150:153], v[182:185], v[88:91]
	v_mfma_f32_16x16x32_bf16 v[88:91], v[154:157], v[186:189], v[88:91]
	v_mfma_f32_16x16x32_bf16 v[84:87], v[162:165], v[186:189], v[84:87]
	v_mfma_f32_16x16x32_bf16 v[84:87], v[158:161], v[182:185], v[84:87]
	v_mfma_f32_16x16x32_bf16 v[68:71], v[158:161], v[190:193], v[68:71]
	v_mfma_f32_16x16x32_bf16 v[68:71], v[162:165], v[194:197], v[68:71]
	v_mfma_f32_16x16x32_bf16 v[72:75], v[154:157], v[194:197], v[72:75]
	v_mfma_f32_16x16x32_bf16 v[72:75], v[150:153], v[190:193], v[72:75]
	s_barrier
	s_add_i32 s71, 0, 0x1c000
	s_add_i32 s69, s69, s65
	s_mov_b32 m0, s69
	ds_read_b128 v[198:201], v253
	ds_read_b128 v[210:213], v253 offset:1024
	ds_read_b128 v[214:217], v253 offset:2048
	ds_read_b128 v[218:221], v253 offset:3072
	global_load_lds_dwordx4 v134, s[100:101]
	s_add_i32 m0, s69, 0x2000
	s_nop 0
	global_load_lds_dwordx4 v138, s[100:101]
	s_barrier
; #define PG8_WAIT_V(n) asm volatile("s_waitcnt vmcnt(" #n ")" ::: "memory")
; template <class Epi, class Ptrs>
; __device__ __forceinline__ void gemm_phase(LAS unsigned char* lds, const int K, const StaticOrder& S, const Ptrs& P, const Epi& E) {
;     ...
;             PG8_BAR; PG8_WAIT_L(0); PG8_MMA(1, 0, At, B0); PG8_BAR; PG8_SCHED;
;             PG8_STAGE(PG8_SB(1, 1), b3 + hstep, voffB);
;             PG8_WAIT_V(6); PG8_BAR; PG8_MMA(1, 1, At, B1); PG8_BAR;
;     __device__ __forceinline__ void operator()(const f32x4 (&acc)[2][2][4][2], const Unit& u, int ui, int wr, int wc, int fr, int fq) const {
;         const int pn = u.pn;
;         if (pn < 8) {
;             bf16_t* base = (bf16_t*)(ws + WS_U) + (size_t)(u.pm * 256 + wr * 64 + fr) * DM + pn * 128 + wc * 32 + 8 * fq;
; #pragma unroll
;             for (int ai = 0; ai < 2; ++ai)
; #pragma unroll
;                 for (int m = 0; m < 4; ++m) {
;                     const f32x4 g0 = g1_4(acc[ai][0][m][0], acc[ai][1][m][0]), g1 = g1_4(acc[ai][0][m][1], acc[ai][1][m][1]);
;                     *(u32x4*)(base + (size_t)(ai * 128 + m * 16) * DM) = pack8(g0, g1); }
;             return; }
;         if (pn >= 17 && pn < 21) {
;             bf16_t* base = (bf16_t*)(dout + DO_GVT) + (size_t)((pn - 17) * 256 + wr * 64 + fr) * MTOK + u.pm * 256 + wc * 32 + 8 * fq;
;             float* pp = (float*)(ws + WS_PART) + (size_t)(u.pm * 256 + wc * 32 + 8 * fq) * 8 + (pn - 17) * 2 + wr;
; #pragma unroll
;             for (int bj = 0; bj < 2; ++bj) { f32x4 sq0 = {0.f, 0.f, 0.f, 0.f}, sq1 = {0.f, 0.f, 0.f, 0.f};
; #pragma unroll
;                 for (int ai = 0; ai < 2; ++ai)
; #pragma unroll
;                     for (int m = 0; m < 4; ++m) { const f32x4 g0 = gelu4(acc[ai][bj][m][0]), g1 = gelu4(acc[ai][bj][m][1]);
;                         sq0 += g0 * g0; sq1 += g1 * g1;
;                         *(u32x4*)(base + (size_t)(ai * 128 + m * 16) * MTOK + bj * 128) = pack8(g0, g1); }
; #pragma unroll
;                 for (int j = 0; j < 4; ++j) { const float t0 = row16_sum(sq0[j]), t1 = row16_sum(sq1[j]); if (fr == 0) { pp[(size_t)(bj * 128 + j) * 8] = t0; pp[(size_t)(bj * 128 + 4 + j) * 8] = t1; } } }
;             return; }
;         bf16_t* base; size_t ld; int row0, col0, act;
;         if (pn < 12)      { base = (bf16_t*)(ws + WS_Q);  ld = DM;  row0 = u.pm * 256; col0 = (pn - 8) * 256;  act = 0; }
	s_waitcnt lgkmcnt(0)
	v_mfma_f32_16x16x32_bf16 v[124:127], v[198:201], v[166:169], v[124:127]
	v_mfma_f32_16x16x32_bf16 v[124:127], v[210:213], v[170:173], v[124:127]
	v_mfma_f32_16x16x32_bf16 v[112:115], v[218:221], v[170:173], v[112:115]
	v_mfma_f32_16x16x32_bf16 v[112:115], v[214:217], v[166:169], v[112:115]
	v_mfma_f32_16x16x32_bf16 v[96:99], v[214:217], v[174:177], v[96:99]
	v_mfma_f32_16x16x32_bf16 v[96:99], v[218:221], v[178:181], v[96:99]
	v_mfma_f32_16x16x32_bf16 v[108:111], v[210:213], v[178:181], v[108:111]
	v_mfma_f32_16x16x32_bf16 v[108:111], v[198:201], v[174:177], v[108:111]
	v_mfma_f32_16x16x32_bf16 v[92:95], v[198:201], v[182:185], v[92:95]
	v_mfma_f32_16x16x32_bf16 v[92:95], v[210:213], v[186:189], v[92:95]
	v_mfma_f32_16x16x32_bf16 v[80:83], v[218:221], v[186:189], v[80:83]
	v_mfma_f32_16x16x32_bf16 v[80:83], v[214:217], v[182:185], v[80:83]
	v_mfma_f32_16x16x32_bf16 v[64:67], v[214:217], v[190:193], v[64:67]
	v_mfma_f32_16x16x32_bf16 v[64:67], v[218:221], v[194:197], v[64:67]
	v_mfma_f32_16x16x32_bf16 v[76:79], v[210:213], v[194:197], v[76:79]
	v_mfma_f32_16x16x32_bf16 v[76:79], v[198:201], v[190:193], v[76:79]
	s_barrier
	s_mov_b32 m0, s89
	s_add_u32 s100, s80, 0xfffc0080
	s_addc_u32 s101, s81, -1
	ds_read_b128 v[166:169], v206 offset:49152
	ds_read_b128 v[170:173], v206 offset:50176
	ds_read_b128 v[174:177], v206 offset:51200
	ds_read_b128 v[178:181], v206 offset:52224
	ds_read_b128 v[182:185], v206 offset:53248
	ds_read_b128 v[186:189], v206 offset:54272
	ds_read_b128 v[190:193], v206 offset:55296
	ds_read_b128 v[194:197], v206 offset:56320
	global_load_lds_dwordx4 v132, s[100:101]
	s_mov_b32 m0, s90
	s_nop 0
	global_load_lds_dwordx4 v136, s[100:101]
	s_barrier
	s_waitcnt lgkmcnt(0)
	v_mfma_f32_16x16x32_bf16 v[56:59], v[150:153], v[166:169], v[56:59]
	v_mfma_f32_16x16x32_bf16 v[56:59], v[154:157], v[170:173], v[56:59]
	v_mfma_f32_16x16x32_bf16 v[52:55], v[162:165], v[170:173], v[52:55]
	v_mfma_f32_16x16x32_bf16 v[52:55], v[158:161], v[166:169], v[52:55]
	v_mfma_f32_16x16x32_bf16 v[36:39], v[158:161], v[174:177], v[36:39]
	v_mfma_f32_16x16x32_bf16 v[36:39], v[162:165], v[178:181], v[36:39]
	v_mfma_f32_16x16x32_bf16 v[40:43], v[154:157], v[178:181], v[40:43]
	v_mfma_f32_16x16x32_bf16 v[40:43], v[150:153], v[174:177], v[40:43]
	v_mfma_f32_16x16x32_bf16 v[24:27], v[150:153], v[182:185], v[24:27]
	v_mfma_f32_16x16x32_bf16 v[24:27], v[154:157], v[186:189], v[24:27]
	v_mfma_f32_16x16x32_bf16 v[20:23], v[162:165], v[186:189], v[20:23]
	v_mfma_f32_16x16x32_bf16 v[20:23], v[158:161], v[182:185], v[20:23]
	v_mfma_f32_16x16x32_bf16 v[4:7], v[158:161], v[190:193], v[4:7]
	v_mfma_f32_16x16x32_bf16 v[4:7], v[162:165], v[194:197], v[4:7]
	v_mfma_f32_16x16x32_bf16 v[8:11], v[154:157], v[194:197], v[8:11]
	v_mfma_f32_16x16x32_bf16 v[8:11], v[150:153], v[190:193], v[8:11]
	s_barrier
	s_add_u32 s78, s78, 0x40080
	s_addc_u32 s79, s79, 0
	s_add_i32 s69, s71, s65
	s_mov_b32 m0, s69
	s_nop 0
	global_load_lds_dwordx4 v134, s[78:79]
	s_add_i32 m0, s69, 0x2000
	s_nop 0
	global_load_lds_dwordx4 v138, s[78:79]
	s_waitcnt vmcnt(6)
	s_barrier
	v_mfma_f32_16x16x32_bf16 v[60:63], v[198:201], v[166:169], v[60:63]
	v_mfma_f32_16x16x32_bf16 v[60:63], v[210:213], v[170:173], v[60:63]
	v_mfma_f32_16x16x32_bf16 v[48:51], v[218:221], v[170:173], v[48:51]
	v_mfma_f32_16x16x32_bf16 v[48:51], v[214:217], v[166:169], v[48:51]
	v_mfma_f32_16x16x32_bf16 v[32:35], v[214:217], v[174:177], v[32:35]
	v_mfma_f32_16x16x32_bf16 v[32:35], v[218:221], v[178:181], v[32:35]
	v_mfma_f32_16x16x32_bf16 v[44:47], v[210:213], v[178:181], v[44:47]
	v_mfma_f32_16x16x32_bf16 v[44:47], v[198:201], v[174:177], v[44:47]
	v_mfma_f32_16x16x32_bf16 v[28:31], v[198:201], v[182:185], v[28:31]
	v_mfma_f32_16x16x32_bf16 v[28:31], v[210:213], v[186:189], v[28:31]
	v_mfma_f32_16x16x32_bf16 v[16:19], v[218:221], v[186:189], v[16:19]
	v_mfma_f32_16x16x32_bf16 v[16:19], v[214:217], v[182:185], v[16:19]
	v_mfma_f32_16x16x32_bf16 v[0:3], v[214:217], v[190:193], v[0:3]
	v_mfma_f32_16x16x32_bf16 v[0:3], v[218:221], v[194:197], v[0:3]
	v_mfma_f32_16x16x32_bf16 v[12:15], v[210:213], v[194:197], v[12:15]
	v_mfma_f32_16x16x32_bf16 v[12:15], v[198:201], v[190:193], v[12:15]
	s_barrier
	s_add_i32 s63, s63, 2
	s_add_u32 s6, s6, 0x100
	s_addc_u32 s7, s7, 0
	s_add_u32 s20, s20, 0x100
	s_addc_u32 s25, s25, 0
	s_cmp_gt_u32 s63, 13
	s_cbranch_scc0 .LBB0_127
	s_cmp_gt_i32 s74, 7
	s_mov_b64 s[6:7], -1
	s_cbranch_scc0 .LBB0_188
	s_sub_i32 s25, s74, 17
	s_cmp_gt_u32 s25, 3
	s_cbranch_scc0 .LBB0_170
	s_lshl_b32 s69, s76, 8
	s_cmp_gt_u32 s74, 11
	s_cbranch_scc0 .LBB0_135
	s_cmp_eq_u32 s74, 12
	s_mov_b64 s[6:7], 0
	s_cbranch_scc1 .LBB0_134
	s_cmp_gt_u32 s74, 16
	s_cbranch_scc1 .LBB0_191
	s_lshl_b32 s20, s74, 8
	v_readlane_b32 s80, v254, 2
	s_addk_i32 s20, 0xf300
	s_mov_b64 s[78:79], 0x400
	s_mov_b64 s[82:83], -1
	s_mov_b32 s63, s69
	v_readlane_b32 s81, v254, 3
	s_andn2_b64 vcc, exec, s[6:7]
	s_cbranch_vccz .LBB0_136
	s_branch .LBB0_137

; __device__ __forceinline__ unsigned xb_ld(unsigned* p)              { return __hip_atomic_load(p, __ATOMIC_RELAXED, __HIP_MEMORY_SCOPE_AGENT); }
; __device__ __forceinline__ void xcd_barrier_complete(unsigned* bar, unsigned x, unsigned& nloc, unsigned& nx) {
;     const unsigned G = gridDim.x * gridDim.y * gridDim.z;
;     unsigned sum, cnt, mine, sp = 0u;
;     for (;;) {
;         sum = 0u; cnt = 0u; mine = 0u;
; #pragma unroll
;         for (unsigned j = 0; j < 16; ++j) { const unsigned c = xb_ld(&bar[XB_XCNT(j)]); sum += c; cnt += (c > 0u) ? 1u : 0u; mine = (j == x) ? c : mine; }
; __device__ __forceinline__ void xcd_barrier(const XcdBarrier& b) {
;     asm volatile("s_waitcnt vmcnt(0)" ::: "memory");
;     __syncthreads();
;     if (threadIdx.x == 0) {
;         unsigned* bar = b.bar;
;         __builtin_amdgcn_s_waitcnt(0);
;         unsigned nloc = b.st[0], nx = b.st[1];
;         if (nloc == 0u) { xcd_barrier_complete(bar, b.x, nloc, nx); b.st[0] = nloc; b.st[1] = nx; }
.LBB0_195:
	s_nop 0
	s_nop 0
	s_nop 0
	s_nop 0
	s_nop 0
	s_nop 0
	s_nop 0
	s_nop 0
	s_nop 0
	s_nop 0
	s_nop 0
	s_nop 0
	s_nop 0
	s_nop 0
	s_nop 0
	s_nop 0
	s_nop 0
	s_nop 0
	s_nop 0
	s_nop 0
	s_nop 0
	s_nop 0
	s_nop 0
	s_nop 0
	s_nop 0
	s_nop 0
	s_nop 0
	s_nop 0
	s_nop 0
	s_nop 0
	s_nop 0
	s_nop 0
	s_nop 0
	s_nop 0
	s_nop 0
	s_nop 0
	s_nop 0
	s_nop 0
	s_nop 0
	s_nop 0
	s_nop 0
	s_nop 0
	s_nop 0
	s_nop 0
	s_nop 0
	s_nop 0
	s_nop 0
	s_nop 0
	s_nop 0
	s_cmp_gt_i32 s31, 2
	s_cselect_b64 s[0:1], -1, 0
	s_and_b64 s[4:5], s[18:19], s[0:1]
	s_andn2_b64 vcc, exec, s[4:5]
	s_cbranch_vccnz .LBB0_245
	s_waitcnt vmcnt(0)
	s_waitcnt vmcnt(0) lgkmcnt(0)
	s_barrier
	s_and_saveexec_b64 s[4:5], s[8:9]
	s_cbranch_execz .LBB0_244
	s_add_i32 s6, 0, 0x25ff0
	v_mov_b32_e32 v0, s6
	s_waitcnt vmcnt(0) expcnt(0) lgkmcnt(0)
	ds_read_b32 v2, v0
	s_add_i32 s6, 0, 0x25ff4
	v_mov_b32_e32 v0, s6
	ds_read_b32 v0, v0
	s_waitcnt lgkmcnt(1)
	v_cmp_ne_u32_e32 vcc, 0, v2
	s_cbranch_vccnz .LBB0_212
	s_load_dwordx2 s[18:19], s[52:53], 0x4
	s_add_u32 s6, s28, 0x3e800200
	s_addc_u32 s7, s29, 0
	s_add_u32 s10, s28, 0x3e800400
	s_addc_u32 s11, s29, 0
	s_waitcnt lgkmcnt(0)
	s_mul_i32 s76, s18, s3
	s_add_u32 s18, s28, 0x3e800500
	s_mul_i32 s76, s76, s19
	s_addc_u32 s19, s29, 0
	s_add_u32 s20, s28, 0x3e800600
	s_addc_u32 s21, s29, 0
	s_add_u32 s22, s28, 0x3e800700
	s_addc_u32 s23, s29, 0
	s_add_u32 s24, s28, 0x3e800800
	s_addc_u32 s25, s29, 0
	s_add_u32 s42, s28, 0x3e800900
	s_addc_u32 s43, s29, 0
	s_add_u32 s44, s28, 0x3e800a00
	s_addc_u32 s45, s29, 0
	s_add_u32 s48, s28, 0x3e800b00
	s_addc_u32 s49, s29, 0
	s_add_u32 s54, s28, 0x3e800c00
	s_addc_u32 s55, s29, 0
	s_add_u32 s56, s28, 0x3e800d00
	s_addc_u32 s57, s29, 0
	s_add_u32 s58, s28, 0x3e800e00
	s_addc_u32 s59, s29, 0
	s_add_u32 s60, s28, 0x3e800f00
	s_addc_u32 s61, s29, 0
	s_add_u32 s62, s28, 0x3e801000
	s_addc_u32 s63, s29, 0
	s_add_u32 s64, s28, 0x3e801100
	s_addc_u32 s65, s29, 0
	s_add_u32 s66, s28, 0x3e801200
	s_addc_u32 s67, s29, 0
	s_add_u32 s68, s28, 0x3e801300
	s_addc_u32 s69, s29, 0
	s_mov_b32 s77, 1
	v_mov_b32_e32 v16, 0
	s_branch .LBB0_200

; #define PG8_STAGE(bufoff, gbase, voff) do { _Pragma("unroll") for (int _i = 0; _i < 2; ++_i) \
;         __builtin_amdgcn_global_load_lds((const unsigned*)((const char*)(gbase) + (voff)[_i]), (LAS unsigned*)(lds + (bufoff) + ldsw + _i * 8192), 16, 0, 0); } while (0)
; #define PG8_WAIT_V(n) asm volatile("s_waitcnt vmcnt(" #n ")" ::: "memory")
; #define PG8_BAR __builtin_amdgcn_s_barrier()
; template <class Epi, class Ptrs>
; __device__ __forceinline__ void gemm_phase(LAS unsigned char* lds, const int K, const StaticOrder& S, const Ptrs& P, const Epi& E) {
;     const int tid = threadIdx.x, wid = __builtin_amdgcn_readfirstlane(tid >> 6), lane = tid & 63, wr = wid >> 2, wc = wid & 3, fr = lane & 15, fq = lane >> 4;
;     const int nt = K / BK;
;     unsigned voffA[2], voffB[2];
; #pragma unroll
;     for (int i = 0; i < 2; ++i) { int R, C; stage_rc(tid * 16 + i * 8192, R, C); const int Rb = (R & ~31) + perm32(R & 31);
;         voffA[i] = (unsigned)(R * K + C) * 2u; voffB[i] = (unsigned)(Rb * K + C) * 2u; }
;     const size_t kstep = (size_t)(BK * 2);
;     const size_t hstep = (size_t)HALF * K * 2;
;     const unsigned ldsw = (unsigned)wid * 1024u;
;     const int aoff = lds_byte(wr * 64 + fr, fq * 8), boff = lds_byte(wc * 32 + fr, fq * 8);
;     ...
;     Unit cur, nxt; int ui = 0;
;     if (!S.next(0, cur)) return;
;     f32x4 acc[2][2][4][2];
; #pragma unroll
;     for (int a = 0; a < 2; ++a)
; #pragma unroll
;         for (int b = 0; b < 2; ++b)
; #pragma unroll
;             for (int m = 0; m < 4; ++m)
; #pragma unroll
;                 for (int n = 0; n < 2; ++n) acc[a][b][m][n] = (f32x4){0.f, 0.f, 0.f, 0.f};
;     bf16x8 At[4][2], B0[2][2], B1[2][2];
;     const char* cA; const char* cB; P.get(cur, cA, cB);
;     PG8_STAGE(PG8_SB(0, 0), cB, voffB); PG8_STAGE(PG8_SA(0, 0), cA, voffA); PG8_STAGE(PG8_SB(0, 1), cB + hstep, voffB); PG8_STAGE(PG8_SA(0, 1), cA + hstep, voffA);
;     if (wr == 1) PG8_BAR;
;     PG8_WAIT_V(4); PG8_BAR;
;     PG8_STAGE(PG8_SB(1, 0), cB + kstep, voffB); PG8_STAGE(PG8_SA(1, 0), cA + kstep, voffA); PG8_STAGE(PG8_SB(1, 1), cB + hstep + kstep, voffB);
;     PG8_WAIT_V(6); PG8_BAR;
.LBB0_346:
	s_add_u32 s14, s28, 0x2000000
	s_addc_u32 s15, s29, 0
	s_add_u32 s16, s28, 0x3e000000
	s_addc_u32 s17, s29, 0
	s_ashr_i32 s58, s3, 31
	s_ashr_i32 s59, s2, 31
	s_add_u32 s60, s38, 0xf8000000
	s_mov_b64 s[18:19], 0x80
	s_addc_u32 s61, s39, -1
	s_and_b32 s62, s1, 3
	s_add_i32 m0, s54, 0x18000
	v_lshl_add_u64 v[6:7], v[6:7], 0, s[18:19]
	s_lshl_b32 s1, s0, 13
	s_lshl_b32 s20, s62, 12
	s_waitcnt vmcnt(4)
	s_barrier
	global_load_lds_dwordx4 v[6:7], off
	v_lshl_add_u64 v[4:5], v[4:5], 0, s[18:19]
	s_add_i32 m0, s54, 0x1a000
	s_add_i32 s63, s54, 0x8000
	s_add_i32 s64, s54, 0xa000
	global_load_lds_dwordx4 v[4:5], off
	v_lshl_add_u64 v[2:3], v[2:3], 0, s[18:19]
	s_mov_b32 m0, s63
	s_add_u32 s4, s42, 0x40080
	global_load_lds_dwordx4 v[2:3], off
	v_lshl_add_u64 v[0:1], v[0:1], 0, s[18:19]
	s_mov_b32 m0, s64
	s_addc_u32 s5, s43, 0
	global_load_lds_dwordx4 v[0:1], off
	s_add_i32 m0, s54, 0x1c000
	v_lshl_add_u64 v[0:1], s[4:5], 0, v[178:179]
	global_load_lds_dwordx4 v[0:1], off
	v_lshl_add_u64 v[0:1], s[4:5], 0, v[182:183]
	s_add_i32 m0, s54, 0x1e000
	v_lshlrev_b32_e32 v4, 6, v208
	global_load_lds_dwordx4 v[0:1], off
	v_bfe_u32 v1, v208, 4, 2
	v_lshlrev_b32_e32 v2, 3, v1
	v_lshlrev_b32_e32 v3, 4, v1
	v_cmp_eq_u32_e64 s[6:7], 0, v1
	v_lshlrev_b32_e32 v1, 8, v208
	v_lshl_or_b32 v206, s62, 5, v2
	v_and_b32_e32 v1, 0x38000, v1
	v_lshlrev_b32_e32 v2, 11, v10
	v_or3_b32 v1, v8, v1, v2
	v_and_b32_e32 v0, 15, v208
	s_movk_i32 s4, 0x3c0
	v_lshlrev_b32_e32 v5, 2, v208
	v_add_u32_e32 v184, v1, v9
	v_lshlrev_b32_e32 v1, 4, v11
	v_and_or_b32 v4, v4, s4, v3
	v_and_b32_e32 v5, 32, v5
	v_lshl_or_b32 v204, s0, 6, v0
	v_lshl_or_b32 v0, v0, 6, v3
	s_waitcnt vmcnt(6)
	v_and_b32_e32 v1, 0x78000, v1
	v_bitop3_b32 v0, v0, s1, v5 bitop3:0xde
	v_bitop3_b32 v205, s20, v4, v5 bitop3:0xf6
	v_or3_b32 v1, v8, v1, v2
	s_add_i32 s66, 0, 0x10000
	s_add_i32 s67, 0, 0x14000
	v_mov_b32_e32 v185, v179
	v_add_u32_e32 v186, v1, v9
	v_mov_b32_e32 v187, v179
	v_mov_b64_e32 v[188:189], 0x600
	v_mov_b64_e32 v[190:191], 0x5ff
	s_movk_i32 s65, 0xc1
	v_add_u32_e32 v207, s66, v205
	v_add_u32_e32 v209, 0, v0
	v_add_u32_e32 v210, s67, v205
	s_nop 0
	s_nop 0
	s_nop 0
	s_nop 0
	s_nop 0
	s_nop 0
	s_nop 0
	s_nop 0
	s_nop 0
	s_nop 0
	s_nop 0
	s_nop 0
	s_nop 0
	s_nop 0
	s_nop 0
	s_nop 0
	s_nop 0
	s_nop 0
	s_nop 0
	s_nop 0
	s_nop 0
	s_nop 0
	s_nop 0
	s_nop 0
	s_mov_b32 s68, 0
	s_cmpk_lt_u32 s46, 0x100
	s_cbranch_scc1 .Lsprio_1
	s_setprio 1

; #define PG8_STAGE(bufoff, gbase, voff) do { _Pragma("unroll") for (int _i = 0; _i < 2; ++_i) \
;         __builtin_amdgcn_global_load_lds((const unsigned*)((const char*)(gbase) + (voff)[_i]), (LAS unsigned*)(lds + (bufoff) + ldsw + _i * 8192), 16, 0, 0); } while (0)
; #define PG8_LDA(dst, b, h) do { _Pragma("unroll") for (int m = 0; m < 4; ++m) _Pragma("unroll") for (int k = 0; k < 2; ++k) dst[m][k] = *(const LAS bf16x8*)(lds + PG8_SA(b, h) + aoff + m * 2048 + k * 1024); } while (0)
; #define PG8_LDB(dst, b, h) do { _Pragma("unroll") for (int n = 0; n < 2; ++n) _Pragma("unroll") for (int k = 0; k < 2; ++k) dst[n][k] = *(const LAS bf16x8*)(lds + PG8_SB(b, h) + boff + n * 2048 + k * 1024); } while (0)
; #define PG8_WAIT_V(n) asm volatile("s_waitcnt vmcnt(" #n ")" ::: "memory")
; #define PG8_WAIT_L(n) asm volatile("s_waitcnt lgkmcnt(" #n ")" ::: "memory")
; #define PG8_BAR __builtin_amdgcn_s_barrier()
; template <class Epi, class Ptrs>
; __device__ __forceinline__ void gemm_phase(LAS unsigned char* lds, const int K, const StaticOrder& S, const Ptrs& P, const Epi& E) {
;     ...
;         for (int t = 0; t < nt; t += 2) {
;             const bool last = (t == nt - 2);
;             const char* a1 = cA + (size_t)(t + 1) * kstep;
;             const char* a2 = last ? nA : cA + (size_t)(t + 2) * kstep; const char* b2 = last ? nB : cB + (size_t)(t + 2) * kstep;
;             const char* a3 = a2 + kstep; const char* b3 = b2 + kstep;
;             PG8_LDB(B0, 0, 0); PG8_SCHED; PG8_LDA(At, 0, 0); PG8_STAGE(PG8_SA(1, 1), a1 + hstep, voffA);
;             PG8_WAIT_L(8); PG8_BAR; PG8_WAIT_L(0); PG8_MMA(0, 0, At, B0); PG8_BAR; PG8_SCHED;
;             PG8_LDB(B1, 0, 1); PG8_STAGE(PG8_SB(0, 0), b2, voffB);
;             PG8_BAR; PG8_WAIT_L(0); PG8_MMA(0, 1, At, B1); PG8_BAR;
;             PG8_LDA(At, 0, 1); PG8_STAGE(PG8_SA(0, 0), a2, voffA);
;             PG8_BAR; PG8_WAIT_L(0); PG8_MMA(1, 0, At, B0); PG8_BAR; PG8_SCHED;
;             PG8_STAGE(PG8_SB(0, 1), b2 + hstep, voffB);
;             PG8_WAIT_V(6); PG8_BAR; PG8_MMA(1, 1, At, B1); PG8_BAR;
;     ...
; #pragma unroll
;         for (int a = 0; a < 2; ++a)
; #pragma unroll
;             for (int b = 0; b < 2; ++b)
; #pragma unroll
;                 for (int m = 0; m < 4; ++m)
; #pragma unroll
;                     for (int n = 0; n < 2; ++n) acc[a][b][m][n] = (f32x4){0.f, 0.f, 0.f, 0.f};
.LBB0_352:
	s_add_u32 s38, s44, 0x40080
	s_addc_u32 s39, s45, 0
	s_add_u32 s21, s42, 0x100
	s_addc_u32 s23, s43, 0
	s_mov_b32 s41, -2
	v_add_u32_e32 v252, 0x18000, v205
	v_add_u32_e32 v253, 0x1c000, v205
	ds_read_b128 v[128:131], v207
	ds_read_b128 v[132:135], v207 offset:1024
	ds_read_b128 v[136:139], v207 offset:2048
	ds_read_b128 v[140:143], v207 offset:3072
	s_add_u32 s42, s38, 0xfffc0080
	s_addc_u32 s43, s39, -1
	s_cmp_eq_u32 s41, 12
	s_cselect_b32 s45, s1, s43
	s_cselect_b32 s44, s0, s42
	s_cselect_b32 s43, s25, s23
	s_cselect_b32 s42, s24, s21
	s_add_i32 m0, s54, 0xc000
	ds_read_b128 v[144:147], v209
	ds_read_b128 v[148:151], v209 offset:1024
	ds_read_b128 v[152:155], v209 offset:2048
	ds_read_b128 v[156:159], v209 offset:3072
	ds_read_b128 v[160:163], v209 offset:4096
	ds_read_b128 v[164:167], v209 offset:5120
	ds_read_b128 v[168:171], v209 offset:6144
	ds_read_b128 v[172:175], v209 offset:7168
	global_load_lds_dwordx4 v184, s[38:39]
	s_add_i32 m0, s54, 0xe000
	s_nop 0
	global_load_lds_dwordx4 v186, s[38:39]
	s_waitcnt lgkmcnt(8)
	s_barrier
	s_waitcnt lgkmcnt(0)
	v_mfma_f32_16x16x32_bf16 v[124:127], v[128:131], v[144:147], 0
	v_mfma_f32_16x16x32_bf16 v[124:127], v[132:135], v[148:151], v[124:127]
	v_mfma_f32_16x16x32_bf16 v[120:123], v[140:143], v[148:151], 0
	v_mfma_f32_16x16x32_bf16 v[120:123], v[136:139], v[144:147], v[120:123]
	v_mfma_f32_16x16x32_bf16 v[104:107], v[136:139], v[152:155], 0
	v_mfma_f32_16x16x32_bf16 v[104:107], v[140:143], v[156:159], v[104:107]
	v_mfma_f32_16x16x32_bf16 v[108:111], v[132:135], v[156:159], 0
	v_mfma_f32_16x16x32_bf16 v[108:111], v[128:131], v[152:155], v[108:111]
	v_mfma_f32_16x16x32_bf16 v[92:95], v[128:131], v[160:163], 0
	v_mfma_f32_16x16x32_bf16 v[92:95], v[132:135], v[164:167], v[92:95]
	v_mfma_f32_16x16x32_bf16 v[88:91], v[140:143], v[164:167], 0
	v_mfma_f32_16x16x32_bf16 v[88:91], v[136:139], v[160:163], v[88:91]
	v_mfma_f32_16x16x32_bf16 v[72:75], v[136:139], v[168:171], 0
	v_mfma_f32_16x16x32_bf16 v[72:75], v[140:143], v[172:175], v[72:75]
	v_mfma_f32_16x16x32_bf16 v[76:79], v[132:135], v[172:175], 0
	v_mfma_f32_16x16x32_bf16 v[76:79], v[128:131], v[168:171], v[76:79]
	s_barrier
	s_add_i32 s69, s66, s51
	s_add_u32 s90, s42, 0x80
	s_addc_u32 s91, s43, 0
	s_mov_b32 m0, s69
	ds_read_b128 v[192:195], v210
	ds_read_b128 v[196:199], v210 offset:1024
	ds_read_b128 v[200:203], v210 offset:2048
	ds_read_b128 v[212:215], v210 offset:3072
	global_load_lds_dwordx4 v178, s[42:43]
	s_add_i32 m0, s69, 0x2000
	s_nop 0
	global_load_lds_dwordx4 v182, s[42:43]
	s_barrier
	s_waitcnt lgkmcnt(0)
	v_mfma_f32_16x16x32_bf16 v[116:119], v[192:195], v[144:147], 0
	v_mfma_f32_16x16x32_bf16 v[116:119], v[196:199], v[148:151], v[116:119]
	v_mfma_f32_16x16x32_bf16 v[112:115], v[212:215], v[148:151], 0
	v_mfma_f32_16x16x32_bf16 v[112:115], v[200:203], v[144:147], v[112:115]
	v_mfma_f32_16x16x32_bf16 v[96:99], v[200:203], v[152:155], 0
	v_mfma_f32_16x16x32_bf16 v[96:99], v[212:215], v[156:159], v[96:99]
	v_mfma_f32_16x16x32_bf16 v[100:103], v[196:199], v[156:159], 0
	v_mfma_f32_16x16x32_bf16 v[100:103], v[192:195], v[152:155], v[100:103]
	v_mfma_f32_16x16x32_bf16 v[84:87], v[192:195], v[160:163], 0
	v_mfma_f32_16x16x32_bf16 v[84:87], v[196:199], v[164:167], v[84:87]
	v_mfma_f32_16x16x32_bf16 v[80:83], v[212:215], v[164:167], 0
	v_mfma_f32_16x16x32_bf16 v[80:83], v[200:203], v[160:163], v[80:83]
	v_mfma_f32_16x16x32_bf16 v[64:67], v[200:203], v[168:171], 0
	v_mfma_f32_16x16x32_bf16 v[64:67], v[212:215], v[172:175], v[64:67]
	v_mfma_f32_16x16x32_bf16 v[68:71], v[196:199], v[172:175], 0
	v_mfma_f32_16x16x32_bf16 v[68:71], v[192:195], v[168:171], v[68:71]
	s_barrier
	s_mov_b32 m0, s54
	s_add_u32 s92, s44, 0x80
	s_addc_u32 s93, s45, 0
	ds_read_b128 v[144:147], v209 offset:16384
	ds_read_b128 v[148:151], v209 offset:17408
	ds_read_b128 v[152:155], v209 offset:18432
	ds_read_b128 v[156:159], v209 offset:19456
	ds_read_b128 v[160:163], v209 offset:20480
	ds_read_b128 v[164:167], v209 offset:21504
	ds_read_b128 v[168:171], v209 offset:22528
	ds_read_b128 v[172:175], v209 offset:23552
	global_load_lds_dwordx4 v176, s[44:45]
	s_mov_b32 m0, s55
	s_nop 0
	global_load_lds_dwordx4 v180, s[44:45]
	s_barrier
	s_waitcnt lgkmcnt(0)
	v_mfma_f32_16x16x32_bf16 v[60:63], v[128:131], v[144:147], 0
	v_mfma_f32_16x16x32_bf16 v[60:63], v[132:135], v[148:151], v[60:63]
	v_mfma_f32_16x16x32_bf16 v[56:59], v[140:143], v[148:151], 0
	v_mfma_f32_16x16x32_bf16 v[56:59], v[136:139], v[144:147], v[56:59]
	v_mfma_f32_16x16x32_bf16 v[40:43], v[136:139], v[152:155], 0
	v_mfma_f32_16x16x32_bf16 v[40:43], v[140:143], v[156:159], v[40:43]
	v_mfma_f32_16x16x32_bf16 v[44:47], v[132:135], v[156:159], 0
	v_mfma_f32_16x16x32_bf16 v[44:47], v[128:131], v[152:155], v[44:47]
	v_mfma_f32_16x16x32_bf16 v[28:31], v[128:131], v[160:163], 0
	v_mfma_f32_16x16x32_bf16 v[28:31], v[132:135], v[164:167], v[28:31]
	v_mfma_f32_16x16x32_bf16 v[24:27], v[140:143], v[164:167], 0
	v_mfma_f32_16x16x32_bf16 v[24:27], v[136:139], v[160:163], v[24:27]
	v_mfma_f32_16x16x32_bf16 v[8:11], v[136:139], v[168:171], 0
	v_mfma_f32_16x16x32_bf16 v[8:11], v[140:143], v[172:175], v[8:11]
	v_mfma_f32_16x16x32_bf16 v[12:15], v[132:135], v[172:175], 0
	v_mfma_f32_16x16x32_bf16 v[12:15], v[128:131], v[168:171], v[12:15]
	s_barrier
	s_add_u32 s70, s42, 0x40000
	s_addc_u32 s71, s43, 0
	s_add_i32 s69, s67, s51
	s_mov_b32 m0, s69
	s_nop 0
	global_load_lds_dwordx4 v178, s[70:71]
	s_add_i32 m0, s69, 0x2000
	s_nop 0
	global_load_lds_dwordx4 v182, s[70:71]
	s_waitcnt vmcnt(6)
	s_barrier
; #define PG8_STAGE(bufoff, gbase, voff) do { _Pragma("unroll") for (int _i = 0; _i < 2; ++_i) \
;         __builtin_amdgcn_global_load_lds((const unsigned*)((const char*)(gbase) + (voff)[_i]), (LAS unsigned*)(lds + (bufoff) + ldsw + _i * 8192), 16, 0, 0); } while (0)
; #define PG8_LDA(dst, b, h) do { _Pragma("unroll") for (int m = 0; m < 4; ++m) _Pragma("unroll") for (int k = 0; k < 2; ++k) dst[m][k] = *(const LAS bf16x8*)(lds + PG8_SA(b, h) + aoff + m * 2048 + k * 1024); } while (0)
; #define PG8_LDB(dst, b, h) do { _Pragma("unroll") for (int n = 0; n < 2; ++n) _Pragma("unroll") for (int k = 0; k < 2; ++k) dst[n][k] = *(const LAS bf16x8*)(lds + PG8_SB(b, h) + boff + n * 2048 + k * 1024); } while (0)
; #define PG8_MMA(ai, bj, At, Bt) do { __builtin_amdgcn_s_setprio(1); _Pragma("unroll") for (int m = 0; m < 4; ++m) _Pragma("unroll") for (int n = 0; n < 2; ++n) _Pragma("unroll") for (int k = 0; k < 2; ++k) \
;         acc[ai][bj][m][n] = __builtin_amdgcn_mfma_f32_16x16x32_bf16(Bt[n][k], At[m][k], acc[ai][bj][m][n], 0, 0, 0); __builtin_amdgcn_s_setprio(0); } while (0)
; #define PG8_WAIT_V(n) asm volatile("s_waitcnt vmcnt(" #n ")" ::: "memory")
; #define PG8_WAIT_L(n) asm volatile("s_waitcnt lgkmcnt(" #n ")" ::: "memory")
; #define PG8_BAR __builtin_amdgcn_s_barrier()
; #define PG8_SCHED __builtin_amdgcn_sched_barrier(0)
; template <class Epi, class Ptrs>
; __device__ __forceinline__ void gemm_phase(LAS unsigned char* lds, const int K, const StaticOrder& S, const Ptrs& P, const Epi& E) {
;     ...
;             PG8_WAIT_V(6); PG8_BAR; PG8_MMA(1, 1, At, B1); PG8_BAR;
;             PG8_LDB(B0, 1, 0); PG8_SCHED; PG8_LDA(At, 1, 0); PG8_STAGE(PG8_SA(0, 1), a2 + hstep, voffA);
;             PG8_WAIT_L(8); PG8_BAR; PG8_WAIT_L(0); PG8_MMA(0, 0, At, B0); PG8_BAR; PG8_SCHED;
;             PG8_LDB(B1, 1, 1); PG8_STAGE(PG8_SB(1, 0), b3, voffB);
;             PG8_BAR; PG8_WAIT_L(0); PG8_MMA(0, 1, At, B1); PG8_BAR;
;             PG8_LDA(At, 1, 1); PG8_STAGE(PG8_SA(1, 0), a3, voffA);
;             PG8_BAR; PG8_WAIT_L(0); PG8_MMA(1, 0, At, B0); PG8_BAR; PG8_SCHED;
;             PG8_STAGE(PG8_SB(1, 1), b3 + hstep, voffB);
;             PG8_WAIT_V(6); PG8_BAR; PG8_MMA(1, 1, At, B1); PG8_BAR;
	v_mfma_f32_16x16x32_bf16 v[52:55], v[192:195], v[144:147], 0
	v_mfma_f32_16x16x32_bf16 v[52:55], v[196:199], v[148:151], v[52:55]
	v_mfma_f32_16x16x32_bf16 v[48:51], v[212:215], v[148:151], 0
	v_mfma_f32_16x16x32_bf16 v[48:51], v[200:203], v[144:147], v[48:51]
	v_mfma_f32_16x16x32_bf16 v[32:35], v[200:203], v[152:155], 0
	v_mfma_f32_16x16x32_bf16 v[32:35], v[212:215], v[156:159], v[32:35]
	v_mfma_f32_16x16x32_bf16 v[36:39], v[196:199], v[156:159], 0
	v_mfma_f32_16x16x32_bf16 v[36:39], v[192:195], v[152:155], v[36:39]
	v_mfma_f32_16x16x32_bf16 v[20:23], v[192:195], v[160:163], 0
	v_mfma_f32_16x16x32_bf16 v[20:23], v[196:199], v[164:167], v[20:23]
	v_mfma_f32_16x16x32_bf16 v[16:19], v[212:215], v[164:167], 0
	v_mfma_f32_16x16x32_bf16 v[16:19], v[200:203], v[160:163], v[16:19]
	v_mfma_f32_16x16x32_bf16 v[0:3], v[200:203], v[168:171], 0
	v_mfma_f32_16x16x32_bf16 v[0:3], v[212:215], v[172:175], v[0:3]
	v_mfma_f32_16x16x32_bf16 v[4:7], v[196:199], v[172:175], 0
	v_mfma_f32_16x16x32_bf16 v[4:7], v[192:195], v[168:171], v[4:7]
	s_barrier
	s_add_i32 s69, 0, 0x18000
	ds_read_b128 v[128:131], v252
	ds_read_b128 v[132:135], v252 offset:1024
	ds_read_b128 v[136:139], v252 offset:2048
	ds_read_b128 v[140:143], v252 offset:3072
	s_add_u32 s44, s44, 0x40000
	s_addc_u32 s45, s45, 0
	s_mov_b32 m0, s56
	ds_read_b128 v[144:147], v209 offset:32768
	ds_read_b128 v[148:151], v209 offset:33792
	ds_read_b128 v[152:155], v209 offset:34816
	ds_read_b128 v[156:159], v209 offset:35840
	ds_read_b128 v[160:163], v209 offset:36864
	ds_read_b128 v[164:167], v209 offset:37888
	ds_read_b128 v[168:171], v209 offset:38912
	ds_read_b128 v[172:175], v209 offset:39936
	global_load_lds_dwordx4 v176, s[44:45]
	s_mov_b32 m0, s57
	s_nop 0
	global_load_lds_dwordx4 v180, s[44:45]
	s_waitcnt lgkmcnt(8)
	s_barrier
	s_waitcnt lgkmcnt(0)
	v_mfma_f32_16x16x32_bf16 v[124:127], v[128:131], v[144:147], v[124:127]
	v_mfma_f32_16x16x32_bf16 v[124:127], v[132:135], v[148:151], v[124:127]
	v_mfma_f32_16x16x32_bf16 v[120:123], v[140:143], v[148:151], v[120:123]
	v_mfma_f32_16x16x32_bf16 v[120:123], v[136:139], v[144:147], v[120:123]
	v_mfma_f32_16x16x32_bf16 v[104:107], v[136:139], v[152:155], v[104:107]
	v_mfma_f32_16x16x32_bf16 v[104:107], v[140:143], v[156:159], v[104:107]
	v_mfma_f32_16x16x32_bf16 v[108:111], v[132:135], v[156:159], v[108:111]
	v_mfma_f32_16x16x32_bf16 v[108:111], v[128:131], v[152:155], v[108:111]
	v_mfma_f32_16x16x32_bf16 v[92:95], v[128:131], v[160:163], v[92:95]
	v_mfma_f32_16x16x32_bf16 v[92:95], v[132:135], v[164:167], v[92:95]
	v_mfma_f32_16x16x32_bf16 v[88:91], v[140:143], v[164:167], v[88:91]
	v_mfma_f32_16x16x32_bf16 v[88:91], v[136:139], v[160:163], v[88:91]
	v_mfma_f32_16x16x32_bf16 v[72:75], v[136:139], v[168:171], v[72:75]
	v_mfma_f32_16x16x32_bf16 v[72:75], v[140:143], v[172:175], v[72:75]
	v_mfma_f32_16x16x32_bf16 v[76:79], v[132:135], v[172:175], v[76:79]
	v_mfma_f32_16x16x32_bf16 v[76:79], v[128:131], v[168:171], v[76:79]
	s_barrier
	s_add_i32 s44, 0, 0x1c000
	s_add_i32 s45, s69, s51
	s_mov_b32 m0, s45
	ds_read_b128 v[192:195], v253
	ds_read_b128 v[196:199], v253 offset:1024
	ds_read_b128 v[200:203], v253 offset:2048
	ds_read_b128 v[212:215], v253 offset:3072
	global_load_lds_dwordx4 v178, s[90:91]
	s_add_i32 m0, s45, 0x2000
	s_nop 0
	global_load_lds_dwordx4 v182, s[90:91]
	s_barrier
	s_waitcnt lgkmcnt(0)
	v_mfma_f32_16x16x32_bf16 v[116:119], v[192:195], v[144:147], v[116:119]
	v_mfma_f32_16x16x32_bf16 v[116:119], v[196:199], v[148:151], v[116:119]
	v_mfma_f32_16x16x32_bf16 v[112:115], v[212:215], v[148:151], v[112:115]
	v_mfma_f32_16x16x32_bf16 v[112:115], v[200:203], v[144:147], v[112:115]
	v_mfma_f32_16x16x32_bf16 v[96:99], v[200:203], v[152:155], v[96:99]
	v_mfma_f32_16x16x32_bf16 v[96:99], v[212:215], v[156:159], v[96:99]
	v_mfma_f32_16x16x32_bf16 v[100:103], v[196:199], v[156:159], v[100:103]
	v_mfma_f32_16x16x32_bf16 v[100:103], v[192:195], v[152:155], v[100:103]
	v_mfma_f32_16x16x32_bf16 v[84:87], v[192:195], v[160:163], v[84:87]
	v_mfma_f32_16x16x32_bf16 v[84:87], v[196:199], v[164:167], v[84:87]
	v_mfma_f32_16x16x32_bf16 v[80:83], v[212:215], v[164:167], v[80:83]
	v_mfma_f32_16x16x32_bf16 v[80:83], v[200:203], v[160:163], v[80:83]
	v_mfma_f32_16x16x32_bf16 v[64:67], v[200:203], v[168:171], v[64:67]
	v_mfma_f32_16x16x32_bf16 v[64:67], v[212:215], v[172:175], v[64:67]
	v_mfma_f32_16x16x32_bf16 v[68:71], v[196:199], v[172:175], v[68:71]
	v_mfma_f32_16x16x32_bf16 v[68:71], v[192:195], v[168:171], v[68:71]
	s_barrier
	s_mov_b32 m0, s63
	ds_read_b128 v[144:147], v209 offset:49152
	ds_read_b128 v[148:151], v209 offset:50176
	ds_read_b128 v[152:155], v209 offset:51200
	ds_read_b128 v[156:159], v209 offset:52224
	ds_read_b128 v[160:163], v209 offset:53248
	ds_read_b128 v[164:167], v209 offset:54272
	ds_read_b128 v[168:171], v209 offset:55296
	ds_read_b128 v[172:175], v209 offset:56320
	global_load_lds_dwordx4 v176, s[92:93]
	s_mov_b32 m0, s64
	s_nop 0
	global_load_lds_dwordx4 v180, s[92:93]
	s_barrier
	s_waitcnt lgkmcnt(0)
	v_mfma_f32_16x16x32_bf16 v[60:63], v[128:131], v[144:147], v[60:63]
	v_mfma_f32_16x16x32_bf16 v[60:63], v[132:135], v[148:151], v[60:63]
	v_mfma_f32_16x16x32_bf16 v[56:59], v[140:143], v[148:151], v[56:59]
	v_mfma_f32_16x16x32_bf16 v[56:59], v[136:139], v[144:147], v[56:59]
	v_mfma_f32_16x16x32_bf16 v[40:43], v[136:139], v[152:155], v[40:43]
	v_mfma_f32_16x16x32_bf16 v[40:43], v[140:143], v[156:159], v[40:43]
	v_mfma_f32_16x16x32_bf16 v[44:47], v[132:135], v[156:159], v[44:47]
	v_mfma_f32_16x16x32_bf16 v[44:47], v[128:131], v[152:155], v[44:47]
	v_mfma_f32_16x16x32_bf16 v[28:31], v[128:131], v[160:163], v[28:31]
	v_mfma_f32_16x16x32_bf16 v[28:31], v[132:135], v[164:167], v[28:31]
	v_mfma_f32_16x16x32_bf16 v[24:27], v[140:143], v[164:167], v[24:27]
	v_mfma_f32_16x16x32_bf16 v[24:27], v[136:139], v[160:163], v[24:27]
	v_mfma_f32_16x16x32_bf16 v[8:11], v[136:139], v[168:171], v[8:11]
	v_mfma_f32_16x16x32_bf16 v[8:11], v[140:143], v[172:175], v[8:11]
	v_mfma_f32_16x16x32_bf16 v[12:15], v[132:135], v[172:175], v[12:15]
	v_mfma_f32_16x16x32_bf16 v[12:15], v[128:131], v[168:171], v[12:15]
	s_barrier
; #define PG8_STAGE(bufoff, gbase, voff) do { _Pragma("unroll") for (int _i = 0; _i < 2; ++_i) \
;         __builtin_amdgcn_global_load_lds((const unsigned*)((const char*)(gbase) + (voff)[_i]), (LAS unsigned*)(lds + (bufoff) + ldsw + _i * 8192), 16, 0, 0); } while (0)
; #define PG8_LDA(dst, b, h) do { _Pragma("unroll") for (int m = 0; m < 4; ++m) _Pragma("unroll") for (int k = 0; k < 2; ++k) dst[m][k] = *(const LAS bf16x8*)(lds + PG8_SA(b, h) + aoff + m * 2048 + k * 1024); } while (0)
; #define PG8_LDB(dst, b, h) do { _Pragma("unroll") for (int n = 0; n < 2; ++n) _Pragma("unroll") for (int k = 0; k < 2; ++k) dst[n][k] = *(const LAS bf16x8*)(lds + PG8_SB(b, h) + boff + n * 2048 + k * 1024); } while (0)
; #define PG8_WAIT_V(n) asm volatile("s_waitcnt vmcnt(" #n ")" ::: "memory")
; #define PG8_WAIT_L(n) asm volatile("s_waitcnt lgkmcnt(" #n ")" ::: "memory")
; #define PG8_BAR __builtin_amdgcn_s_barrier()
; #define PG8_SCHED __builtin_amdgcn_sched_barrier(0)
; template <class Epi, class Ptrs>
; __device__ __forceinline__ void gemm_phase(LAS unsigned char* lds, const int K, const StaticOrder& S, const Ptrs& P, const Epi& E) {
;     ...
;             PG8_LDB(B0, 0, 0); PG8_SCHED; PG8_LDA(At, 0, 0); PG8_STAGE(PG8_SA(1, 1), a1 + hstep, voffA);
;             PG8_WAIT_L(8); PG8_BAR; PG8_WAIT_L(0); PG8_MMA(0, 0, At, B0); PG8_BAR; PG8_SCHED;
;             PG8_LDB(B1, 0, 1); PG8_STAGE(PG8_SB(0, 0), b2, voffB);
;             PG8_BAR; PG8_WAIT_L(0); PG8_MMA(0, 1, At, B1); PG8_BAR;
;             PG8_LDA(At, 0, 1); PG8_STAGE(PG8_SA(0, 0), a2, voffA);
;             PG8_BAR; PG8_WAIT_L(0); PG8_MMA(1, 0, At, B0); PG8_BAR; PG8_SCHED;
;             PG8_STAGE(PG8_SB(0, 1), b2 + hstep, voffB);
;             PG8_WAIT_V(6); PG8_BAR; PG8_MMA(1, 1, At, B1); PG8_BAR;
;             PG8_LDB(B0, 1, 0); PG8_SCHED; PG8_LDA(At, 1, 0); PG8_STAGE(PG8_SA(0, 1), a2 + hstep, voffA);
;             PG8_WAIT_L(8); PG8_BAR; PG8_WAIT_L(0); PG8_MMA(0, 0, At, B0); PG8_BAR; PG8_SCHED;
;             PG8_LDB(B1, 1, 1); PG8_STAGE(PG8_SB(1, 0), b3, voffB);
;             PG8_BAR; PG8_WAIT_L(0); PG8_MMA(0, 1, At, B1); PG8_BAR;
;             PG8_LDA(At, 1, 1); PG8_STAGE(PG8_SA(1, 0), a3, voffA);
;             PG8_BAR; PG8_WAIT_L(0); PG8_MMA(1, 0, At, B0); PG8_BAR; PG8_SCHED;
;             PG8_STAGE(PG8_SB(1, 1), b3 + hstep, voffB);
;             PG8_WAIT_V(6); PG8_BAR; PG8_MMA(1, 1, At, B1); PG8_BAR;
	s_add_u32 s42, s42, 0x40080
	s_addc_u32 s43, s43, 0
	s_add_i32 s44, s44, s51
	s_mov_b32 m0, s44
	s_nop 0
	global_load_lds_dwordx4 v178, s[42:43]
	s_add_i32 m0, s44, 0x2000
	s_nop 0
	global_load_lds_dwordx4 v182, s[42:43]
	s_waitcnt vmcnt(6)
	s_barrier
	v_mfma_f32_16x16x32_bf16 v[52:55], v[192:195], v[144:147], v[52:55]
	v_mfma_f32_16x16x32_bf16 v[52:55], v[196:199], v[148:151], v[52:55]
	v_mfma_f32_16x16x32_bf16 v[48:51], v[212:215], v[148:151], v[48:51]
	v_mfma_f32_16x16x32_bf16 v[48:51], v[200:203], v[144:147], v[48:51]
	v_mfma_f32_16x16x32_bf16 v[32:35], v[200:203], v[152:155], v[32:35]
	v_mfma_f32_16x16x32_bf16 v[32:35], v[212:215], v[156:159], v[32:35]
	v_mfma_f32_16x16x32_bf16 v[36:39], v[196:199], v[156:159], v[36:39]
	v_mfma_f32_16x16x32_bf16 v[36:39], v[192:195], v[152:155], v[36:39]
	v_mfma_f32_16x16x32_bf16 v[20:23], v[192:195], v[160:163], v[20:23]
	v_mfma_f32_16x16x32_bf16 v[20:23], v[196:199], v[164:167], v[20:23]
	v_mfma_f32_16x16x32_bf16 v[16:19], v[212:215], v[164:167], v[16:19]
	v_mfma_f32_16x16x32_bf16 v[16:19], v[200:203], v[160:163], v[16:19]
	v_mfma_f32_16x16x32_bf16 v[0:3], v[200:203], v[168:171], v[0:3]
	v_mfma_f32_16x16x32_bf16 v[0:3], v[212:215], v[172:175], v[0:3]
	v_mfma_f32_16x16x32_bf16 v[4:7], v[196:199], v[172:175], v[4:7]
	v_mfma_f32_16x16x32_bf16 v[4:7], v[192:195], v[168:171], v[4:7]
	s_barrier
	s_add_i32 s41, s41, 2
	s_add_u32 s38, s38, 0x100
	s_addc_u32 s39, s39, 0
	s_add_u32 s21, s21, 0x100
	s_addc_u32 s23, s23, 0
	s_cmp_gt_u32 s41, 13
.LBB0_353:
	ds_read_b128 v[128:131], v207
	ds_read_b128 v[132:135], v207 offset:1024
	ds_read_b128 v[136:139], v207 offset:2048
	ds_read_b128 v[140:143], v207 offset:3072
	s_add_u32 s42, s38, 0xfffc0080
	s_addc_u32 s43, s39, -1
	s_cmp_eq_u32 s41, 12
	s_cselect_b32 s45, s1, s43
	s_cselect_b32 s44, s0, s42
	s_cselect_b32 s43, s25, s23
	s_cselect_b32 s42, s24, s21
	s_add_i32 m0, s54, 0xc000
	ds_read_b128 v[144:147], v209
	ds_read_b128 v[148:151], v209 offset:1024
	ds_read_b128 v[152:155], v209 offset:2048
	ds_read_b128 v[156:159], v209 offset:3072
	ds_read_b128 v[160:163], v209 offset:4096
	ds_read_b128 v[164:167], v209 offset:5120
	ds_read_b128 v[168:171], v209 offset:6144
	ds_read_b128 v[172:175], v209 offset:7168
	global_load_lds_dwordx4 v184, s[38:39]
	s_add_i32 m0, s54, 0xe000
	s_nop 0
	global_load_lds_dwordx4 v186, s[38:39]
	s_waitcnt lgkmcnt(8)
	s_barrier
	s_waitcnt lgkmcnt(0)
	v_mfma_f32_16x16x32_bf16 v[124:127], v[128:131], v[144:147], v[124:127]
	v_mfma_f32_16x16x32_bf16 v[124:127], v[132:135], v[148:151], v[124:127]
	v_mfma_f32_16x16x32_bf16 v[120:123], v[140:143], v[148:151], v[120:123]
	v_mfma_f32_16x16x32_bf16 v[120:123], v[136:139], v[144:147], v[120:123]
	v_mfma_f32_16x16x32_bf16 v[104:107], v[136:139], v[152:155], v[104:107]
	v_mfma_f32_16x16x32_bf16 v[104:107], v[140:143], v[156:159], v[104:107]
	v_mfma_f32_16x16x32_bf16 v[108:111], v[132:135], v[156:159], v[108:111]
	v_mfma_f32_16x16x32_bf16 v[108:111], v[128:131], v[152:155], v[108:111]
	v_mfma_f32_16x16x32_bf16 v[92:95], v[128:131], v[160:163], v[92:95]
	v_mfma_f32_16x16x32_bf16 v[92:95], v[132:135], v[164:167], v[92:95]
	v_mfma_f32_16x16x32_bf16 v[88:91], v[140:143], v[164:167], v[88:91]
	v_mfma_f32_16x16x32_bf16 v[88:91], v[136:139], v[160:163], v[88:91]
	v_mfma_f32_16x16x32_bf16 v[72:75], v[136:139], v[168:171], v[72:75]
	v_mfma_f32_16x16x32_bf16 v[72:75], v[140:143], v[172:175], v[72:75]
	v_mfma_f32_16x16x32_bf16 v[76:79], v[132:135], v[172:175], v[76:79]
	v_mfma_f32_16x16x32_bf16 v[76:79], v[128:131], v[168:171], v[76:79]
	s_barrier
	s_add_i32 s69, s66, s51
	s_add_u32 s90, s42, 0x80
	s_addc_u32 s91, s43, 0
	s_mov_b32 m0, s69
	ds_read_b128 v[192:195], v210
	ds_read_b128 v[196:199], v210 offset:1024
	ds_read_b128 v[200:203], v210 offset:2048
	ds_read_b128 v[212:215], v210 offset:3072
	global_load_lds_dwordx4 v178, s[42:43]
	s_add_i32 m0, s69, 0x2000
	s_nop 0
	global_load_lds_dwordx4 v182, s[42:43]
	s_barrier
	s_waitcnt lgkmcnt(0)
	v_mfma_f32_16x16x32_bf16 v[116:119], v[192:195], v[144:147], v[116:119]
	v_mfma_f32_16x16x32_bf16 v[116:119], v[196:199], v[148:151], v[116:119]
	v_mfma_f32_16x16x32_bf16 v[112:115], v[212:215], v[148:151], v[112:115]
	v_mfma_f32_16x16x32_bf16 v[112:115], v[200:203], v[144:147], v[112:115]
	v_mfma_f32_16x16x32_bf16 v[96:99], v[200:203], v[152:155], v[96:99]
	v_mfma_f32_16x16x32_bf16 v[96:99], v[212:215], v[156:159], v[96:99]
	v_mfma_f32_16x16x32_bf16 v[100:103], v[196:199], v[156:159], v[100:103]
	v_mfma_f32_16x16x32_bf16 v[100:103], v[192:195], v[152:155], v[100:103]
	v_mfma_f32_16x16x32_bf16 v[84:87], v[192:195], v[160:163], v[84:87]
	v_mfma_f32_16x16x32_bf16 v[84:87], v[196:199], v[164:167], v[84:87]
	v_mfma_f32_16x16x32_bf16 v[80:83], v[212:215], v[164:167], v[80:83]
	v_mfma_f32_16x16x32_bf16 v[80:83], v[200:203], v[160:163], v[80:83]
	v_mfma_f32_16x16x32_bf16 v[64:67], v[200:203], v[168:171], v[64:67]
	v_mfma_f32_16x16x32_bf16 v[64:67], v[212:215], v[172:175], v[64:67]
	v_mfma_f32_16x16x32_bf16 v[68:71], v[196:199], v[172:175], v[68:71]
	v_mfma_f32_16x16x32_bf16 v[68:71], v[192:195], v[168:171], v[68:71]
	s_barrier
	s_mov_b32 m0, s54
	s_add_u32 s92, s44, 0x80
	s_addc_u32 s93, s45, 0
	ds_read_b128 v[144:147], v209 offset:16384
	ds_read_b128 v[148:151], v209 offset:17408
	ds_read_b128 v[152:155], v209 offset:18432
	ds_read_b128 v[156:159], v209 offset:19456
	ds_read_b128 v[160:163], v209 offset:20480
	ds_read_b128 v[164:167], v209 offset:21504
	ds_read_b128 v[168:171], v209 offset:22528
	ds_read_b128 v[172:175], v209 offset:23552
	global_load_lds_dwordx4 v176, s[44:45]
	s_mov_b32 m0, s55
	s_nop 0
	global_load_lds_dwordx4 v180, s[44:45]
	s_barrier
; #define PG8_STAGE(bufoff, gbase, voff) do { _Pragma("unroll") for (int _i = 0; _i < 2; ++_i) \
;         __builtin_amdgcn_global_load_lds((const unsigned*)((const char*)(gbase) + (voff)[_i]), (LAS unsigned*)(lds + (bufoff) + ldsw + _i * 8192), 16, 0, 0); } while (0)
; #define PG8_LDA(dst, b, h) do { _Pragma("unroll") for (int m = 0; m < 4; ++m) _Pragma("unroll") for (int k = 0; k < 2; ++k) dst[m][k] = *(const LAS bf16x8*)(lds + PG8_SA(b, h) + aoff + m * 2048 + k * 1024); } while (0)
; #define PG8_LDB(dst, b, h) do { _Pragma("unroll") for (int n = 0; n < 2; ++n) _Pragma("unroll") for (int k = 0; k < 2; ++k) dst[n][k] = *(const LAS bf16x8*)(lds + PG8_SB(b, h) + boff + n * 2048 + k * 1024); } while (0)
; #define PG8_MMA(ai, bj, At, Bt) do { __builtin_amdgcn_s_setprio(1); _Pragma("unroll") for (int m = 0; m < 4; ++m) _Pragma("unroll") for (int n = 0; n < 2; ++n) _Pragma("unroll") for (int k = 0; k < 2; ++k) \
;         acc[ai][bj][m][n] = __builtin_amdgcn_mfma_f32_16x16x32_bf16(Bt[n][k], At[m][k], acc[ai][bj][m][n], 0, 0, 0); __builtin_amdgcn_s_setprio(0); } while (0)
; #define PG8_WAIT_V(n) asm volatile("s_waitcnt vmcnt(" #n ")" ::: "memory")
; #define PG8_WAIT_L(n) asm volatile("s_waitcnt lgkmcnt(" #n ")" ::: "memory")
; #define PG8_BAR __builtin_amdgcn_s_barrier()
; #define PG8_SCHED __builtin_amdgcn_sched_barrier(0)
; template <class Epi, class Ptrs>
; __device__ __forceinline__ void gemm_phase(LAS unsigned char* lds, const int K, const StaticOrder& S, const Ptrs& P, const Epi& E) {
;     ...
;             PG8_BAR; PG8_WAIT_L(0); PG8_MMA(1, 0, At, B0); PG8_BAR; PG8_SCHED;
;             PG8_STAGE(PG8_SB(0, 1), b2 + hstep, voffB);
;             PG8_WAIT_V(6); PG8_BAR; PG8_MMA(1, 1, At, B1); PG8_BAR;
;             PG8_LDB(B0, 1, 0); PG8_SCHED; PG8_LDA(At, 1, 0); PG8_STAGE(PG8_SA(0, 1), a2 + hstep, voffA);
;             PG8_WAIT_L(8); PG8_BAR; PG8_WAIT_L(0); PG8_MMA(0, 0, At, B0); PG8_BAR; PG8_SCHED;
;             PG8_LDB(B1, 1, 1); PG8_STAGE(PG8_SB(1, 0), b3, voffB);
;             PG8_BAR; PG8_WAIT_L(0); PG8_MMA(0, 1, At, B1); PG8_BAR;
	s_waitcnt lgkmcnt(0)
	v_mfma_f32_16x16x32_bf16 v[60:63], v[128:131], v[144:147], v[60:63]
	v_mfma_f32_16x16x32_bf16 v[60:63], v[132:135], v[148:151], v[60:63]
	v_mfma_f32_16x16x32_bf16 v[56:59], v[140:143], v[148:151], v[56:59]
	v_mfma_f32_16x16x32_bf16 v[56:59], v[136:139], v[144:147], v[56:59]
	v_mfma_f32_16x16x32_bf16 v[40:43], v[136:139], v[152:155], v[40:43]
	v_mfma_f32_16x16x32_bf16 v[40:43], v[140:143], v[156:159], v[40:43]
	v_mfma_f32_16x16x32_bf16 v[44:47], v[132:135], v[156:159], v[44:47]
	v_mfma_f32_16x16x32_bf16 v[44:47], v[128:131], v[152:155], v[44:47]
	v_mfma_f32_16x16x32_bf16 v[28:31], v[128:131], v[160:163], v[28:31]
	v_mfma_f32_16x16x32_bf16 v[28:31], v[132:135], v[164:167], v[28:31]
	v_mfma_f32_16x16x32_bf16 v[24:27], v[140:143], v[164:167], v[24:27]
	v_mfma_f32_16x16x32_bf16 v[24:27], v[136:139], v[160:163], v[24:27]
	v_mfma_f32_16x16x32_bf16 v[8:11], v[136:139], v[168:171], v[8:11]
	v_mfma_f32_16x16x32_bf16 v[8:11], v[140:143], v[172:175], v[8:11]
	v_mfma_f32_16x16x32_bf16 v[12:15], v[132:135], v[172:175], v[12:15]
	v_mfma_f32_16x16x32_bf16 v[12:15], v[128:131], v[168:171], v[12:15]
	s_barrier
	s_add_u32 s70, s42, 0x40000
	s_addc_u32 s71, s43, 0
	s_add_i32 s69, s67, s51
	s_mov_b32 m0, s69
	s_nop 0
	global_load_lds_dwordx4 v178, s[70:71]
	s_add_i32 m0, s69, 0x2000
	s_nop 0
	global_load_lds_dwordx4 v182, s[70:71]
	s_waitcnt vmcnt(6)
	s_barrier
	v_mfma_f32_16x16x32_bf16 v[52:55], v[192:195], v[144:147], v[52:55]
	v_mfma_f32_16x16x32_bf16 v[52:55], v[196:199], v[148:151], v[52:55]
	v_mfma_f32_16x16x32_bf16 v[48:51], v[212:215], v[148:151], v[48:51]
	v_mfma_f32_16x16x32_bf16 v[48:51], v[200:203], v[144:147], v[48:51]
	v_mfma_f32_16x16x32_bf16 v[32:35], v[200:203], v[152:155], v[32:35]
	v_mfma_f32_16x16x32_bf16 v[32:35], v[212:215], v[156:159], v[32:35]
	v_mfma_f32_16x16x32_bf16 v[36:39], v[196:199], v[156:159], v[36:39]
	v_mfma_f32_16x16x32_bf16 v[36:39], v[192:195], v[152:155], v[36:39]
	v_mfma_f32_16x16x32_bf16 v[20:23], v[192:195], v[160:163], v[20:23]
	v_mfma_f32_16x16x32_bf16 v[20:23], v[196:199], v[164:167], v[20:23]
	v_mfma_f32_16x16x32_bf16 v[16:19], v[212:215], v[164:167], v[16:19]
	v_mfma_f32_16x16x32_bf16 v[16:19], v[200:203], v[160:163], v[16:19]
	v_mfma_f32_16x16x32_bf16 v[0:3], v[200:203], v[168:171], v[0:3]
	v_mfma_f32_16x16x32_bf16 v[0:3], v[212:215], v[172:175], v[0:3]
	v_mfma_f32_16x16x32_bf16 v[4:7], v[196:199], v[172:175], v[4:7]
	v_mfma_f32_16x16x32_bf16 v[4:7], v[192:195], v[168:171], v[4:7]
	s_barrier
	s_add_i32 s69, 0, 0x18000
	ds_read_b128 v[128:131], v252
	ds_read_b128 v[132:135], v252 offset:1024
	ds_read_b128 v[136:139], v252 offset:2048
	ds_read_b128 v[140:143], v252 offset:3072
	s_add_u32 s44, s44, 0x40000
	s_addc_u32 s45, s45, 0
	s_mov_b32 m0, s56
	ds_read_b128 v[144:147], v209 offset:32768
	ds_read_b128 v[148:151], v209 offset:33792
	ds_read_b128 v[152:155], v209 offset:34816
	ds_read_b128 v[156:159], v209 offset:35840
	ds_read_b128 v[160:163], v209 offset:36864
	ds_read_b128 v[164:167], v209 offset:37888
	ds_read_b128 v[168:171], v209 offset:38912
	ds_read_b128 v[172:175], v209 offset:39936
	global_load_lds_dwordx4 v176, s[44:45]
	s_mov_b32 m0, s57
	s_nop 0
	global_load_lds_dwordx4 v180, s[44:45]
	s_waitcnt lgkmcnt(8)
	s_barrier
	s_waitcnt lgkmcnt(0)
	v_mfma_f32_16x16x32_bf16 v[124:127], v[128:131], v[144:147], v[124:127]
	v_mfma_f32_16x16x32_bf16 v[124:127], v[132:135], v[148:151], v[124:127]
	v_mfma_f32_16x16x32_bf16 v[120:123], v[140:143], v[148:151], v[120:123]
	v_mfma_f32_16x16x32_bf16 v[120:123], v[136:139], v[144:147], v[120:123]
	v_mfma_f32_16x16x32_bf16 v[104:107], v[136:139], v[152:155], v[104:107]
	v_mfma_f32_16x16x32_bf16 v[104:107], v[140:143], v[156:159], v[104:107]
	v_mfma_f32_16x16x32_bf16 v[108:111], v[132:135], v[156:159], v[108:111]
	v_mfma_f32_16x16x32_bf16 v[108:111], v[128:131], v[152:155], v[108:111]
	v_mfma_f32_16x16x32_bf16 v[92:95], v[128:131], v[160:163], v[92:95]
	v_mfma_f32_16x16x32_bf16 v[92:95], v[132:135], v[164:167], v[92:95]
	v_mfma_f32_16x16x32_bf16 v[88:91], v[140:143], v[164:167], v[88:91]
	v_mfma_f32_16x16x32_bf16 v[88:91], v[136:139], v[160:163], v[88:91]
	v_mfma_f32_16x16x32_bf16 v[72:75], v[136:139], v[168:171], v[72:75]
	v_mfma_f32_16x16x32_bf16 v[72:75], v[140:143], v[172:175], v[72:75]
	v_mfma_f32_16x16x32_bf16 v[76:79], v[132:135], v[172:175], v[76:79]
	v_mfma_f32_16x16x32_bf16 v[76:79], v[128:131], v[168:171], v[76:79]
	s_barrier
	s_add_i32 s44, 0, 0x1c000
	s_add_i32 s45, s69, s51
	s_mov_b32 m0, s45
	ds_read_b128 v[192:195], v253
	ds_read_b128 v[196:199], v253 offset:1024
	ds_read_b128 v[200:203], v253 offset:2048
	ds_read_b128 v[212:215], v253 offset:3072
	global_load_lds_dwordx4 v178, s[90:91]
	s_add_i32 m0, s45, 0x2000
	s_nop 0
	global_load_lds_dwordx4 v182, s[90:91]
	s_barrier
	s_waitcnt lgkmcnt(0)
	v_mfma_f32_16x16x32_bf16 v[116:119], v[192:195], v[144:147], v[116:119]
	v_mfma_f32_16x16x32_bf16 v[116:119], v[196:199], v[148:151], v[116:119]
	v_mfma_f32_16x16x32_bf16 v[112:115], v[212:215], v[148:151], v[112:115]
	v_mfma_f32_16x16x32_bf16 v[112:115], v[200:203], v[144:147], v[112:115]
	v_mfma_f32_16x16x32_bf16 v[96:99], v[200:203], v[152:155], v[96:99]
	v_mfma_f32_16x16x32_bf16 v[96:99], v[212:215], v[156:159], v[96:99]
	v_mfma_f32_16x16x32_bf16 v[100:103], v[196:199], v[156:159], v[100:103]
	v_mfma_f32_16x16x32_bf16 v[100:103], v[192:195], v[152:155], v[100:103]
	v_mfma_f32_16x16x32_bf16 v[84:87], v[192:195], v[160:163], v[84:87]
	v_mfma_f32_16x16x32_bf16 v[84:87], v[196:199], v[164:167], v[84:87]
	v_mfma_f32_16x16x32_bf16 v[80:83], v[212:215], v[164:167], v[80:83]
	v_mfma_f32_16x16x32_bf16 v[80:83], v[200:203], v[160:163], v[80:83]
	v_mfma_f32_16x16x32_bf16 v[64:67], v[200:203], v[168:171], v[64:67]
	v_mfma_f32_16x16x32_bf16 v[64:67], v[212:215], v[172:175], v[64:67]
	v_mfma_f32_16x16x32_bf16 v[68:71], v[196:199], v[172:175], v[68:71]
	v_mfma_f32_16x16x32_bf16 v[68:71], v[192:195], v[168:171], v[68:71]
	s_barrier
; #define PG8_STAGE(bufoff, gbase, voff) do { _Pragma("unroll") for (int _i = 0; _i < 2; ++_i) \
;         __builtin_amdgcn_global_load_lds((const unsigned*)((const char*)(gbase) + (voff)[_i]), (LAS unsigned*)(lds + (bufoff) + ldsw + _i * 8192), 16, 0, 0); } while (0)
; #define PG8_LDA(dst, b, h) do { _Pragma("unroll") for (int m = 0; m < 4; ++m) _Pragma("unroll") for (int k = 0; k < 2; ++k) dst[m][k] = *(const LAS bf16x8*)(lds + PG8_SA(b, h) + aoff + m * 2048 + k * 1024); } while (0)
; #define PG8_MMA(ai, bj, At, Bt) do { __builtin_amdgcn_s_setprio(1); _Pragma("unroll") for (int m = 0; m < 4; ++m) _Pragma("unroll") for (int n = 0; n < 2; ++n) _Pragma("unroll") for (int k = 0; k < 2; ++k) \
;         acc[ai][bj][m][n] = __builtin_amdgcn_mfma_f32_16x16x32_bf16(Bt[n][k], At[m][k], acc[ai][bj][m][n], 0, 0, 0); __builtin_amdgcn_s_setprio(0); } while (0)
; #define PG8_WAIT_V(n) asm volatile("s_waitcnt vmcnt(" #n ")" ::: "memory")
; #define PG8_WAIT_L(n) asm volatile("s_waitcnt lgkmcnt(" #n ")" ::: "memory")
; #define PG8_BAR __builtin_amdgcn_s_barrier()
; #define PG8_SCHED __builtin_amdgcn_sched_barrier(0)
; template <class Epi, class Ptrs>
; __device__ __forceinline__ void gemm_phase(LAS unsigned char* lds, const int K, const StaticOrder& S, const Ptrs& P, const Epi& E) {
;     ...
;             PG8_LDA(At, 1, 1); PG8_STAGE(PG8_SA(1, 0), a3, voffA);
;             PG8_BAR; PG8_WAIT_L(0); PG8_MMA(1, 0, At, B0); PG8_BAR; PG8_SCHED;
;             PG8_STAGE(PG8_SB(1, 1), b3 + hstep, voffB);
;             PG8_WAIT_V(6); PG8_BAR; PG8_MMA(1, 1, At, B1); PG8_BAR;
	s_mov_b32 m0, s63
	ds_read_b128 v[144:147], v209 offset:49152
	ds_read_b128 v[148:151], v209 offset:50176
	ds_read_b128 v[152:155], v209 offset:51200
	ds_read_b128 v[156:159], v209 offset:52224
	ds_read_b128 v[160:163], v209 offset:53248
	ds_read_b128 v[164:167], v209 offset:54272
	ds_read_b128 v[168:171], v209 offset:55296
	ds_read_b128 v[172:175], v209 offset:56320
	global_load_lds_dwordx4 v176, s[92:93]
	s_mov_b32 m0, s64
	s_nop 0
	global_load_lds_dwordx4 v180, s[92:93]
	s_barrier
	s_waitcnt lgkmcnt(0)
	v_mfma_f32_16x16x32_bf16 v[60:63], v[128:131], v[144:147], v[60:63]
	v_mfma_f32_16x16x32_bf16 v[60:63], v[132:135], v[148:151], v[60:63]
	v_mfma_f32_16x16x32_bf16 v[56:59], v[140:143], v[148:151], v[56:59]
	v_mfma_f32_16x16x32_bf16 v[56:59], v[136:139], v[144:147], v[56:59]
	v_mfma_f32_16x16x32_bf16 v[40:43], v[136:139], v[152:155], v[40:43]
	v_mfma_f32_16x16x32_bf16 v[40:43], v[140:143], v[156:159], v[40:43]
	v_mfma_f32_16x16x32_bf16 v[44:47], v[132:135], v[156:159], v[44:47]
	v_mfma_f32_16x16x32_bf16 v[44:47], v[128:131], v[152:155], v[44:47]
	v_mfma_f32_16x16x32_bf16 v[28:31], v[128:131], v[160:163], v[28:31]
	v_mfma_f32_16x16x32_bf16 v[28:31], v[132:135], v[164:167], v[28:31]
	v_mfma_f32_16x16x32_bf16 v[24:27], v[140:143], v[164:167], v[24:27]
	v_mfma_f32_16x16x32_bf16 v[24:27], v[136:139], v[160:163], v[24:27]
	v_mfma_f32_16x16x32_bf16 v[8:11], v[136:139], v[168:171], v[8:11]
	v_mfma_f32_16x16x32_bf16 v[8:11], v[140:143], v[172:175], v[8:11]
	v_mfma_f32_16x16x32_bf16 v[12:15], v[132:135], v[172:175], v[12:15]
	v_mfma_f32_16x16x32_bf16 v[12:15], v[128:131], v[168:171], v[12:15]
	s_barrier
	s_add_u32 s42, s42, 0x40080
	s_addc_u32 s43, s43, 0
	s_add_i32 s44, s44, s51
	s_mov_b32 m0, s44
	s_nop 0
	global_load_lds_dwordx4 v178, s[42:43]
	s_add_i32 m0, s44, 0x2000
	s_nop 0
	global_load_lds_dwordx4 v182, s[42:43]
	s_waitcnt vmcnt(6)
	s_barrier
	v_mfma_f32_16x16x32_bf16 v[52:55], v[192:195], v[144:147], v[52:55]
	v_mfma_f32_16x16x32_bf16 v[52:55], v[196:199], v[148:151], v[52:55]
	v_mfma_f32_16x16x32_bf16 v[48:51], v[212:215], v[148:151], v[48:51]
	v_mfma_f32_16x16x32_bf16 v[48:51], v[200:203], v[144:147], v[48:51]
	v_mfma_f32_16x16x32_bf16 v[32:35], v[200:203], v[152:155], v[32:35]
	v_mfma_f32_16x16x32_bf16 v[32:35], v[212:215], v[156:159], v[32:35]
	v_mfma_f32_16x16x32_bf16 v[36:39], v[196:199], v[156:159], v[36:39]
	v_mfma_f32_16x16x32_bf16 v[36:39], v[192:195], v[152:155], v[36:39]
	v_mfma_f32_16x16x32_bf16 v[20:23], v[192:195], v[160:163], v[20:23]
	v_mfma_f32_16x16x32_bf16 v[20:23], v[196:199], v[164:167], v[20:23]
	v_mfma_f32_16x16x32_bf16 v[16:19], v[212:215], v[164:167], v[16:19]
	v_mfma_f32_16x16x32_bf16 v[16:19], v[200:203], v[160:163], v[16:19]
	v_mfma_f32_16x16x32_bf16 v[0:3], v[200:203], v[168:171], v[0:3]
	v_mfma_f32_16x16x32_bf16 v[0:3], v[212:215], v[172:175], v[0:3]
	v_mfma_f32_16x16x32_bf16 v[4:7], v[196:199], v[172:175], v[4:7]
	v_mfma_f32_16x16x32_bf16 v[4:7], v[192:195], v[168:171], v[4:7]
	s_barrier
	s_add_i32 s41, s41, 2
	s_add_u32 s38, s38, 0x100
	s_addc_u32 s39, s39, 0
	s_add_u32 s21, s21, 0x100
	s_addc_u32 s23, s23, 0
	s_cmp_gt_u32 s41, 13
	s_cbranch_scc0 .LBB0_353
; __device__ __forceinline__ unsigned cvt_pk_bf16(float lo, float hi) { unsigned r; asm volatile("v_cvt_pk_bf16_f32 %0, %1, %2" : "=v"(r) : "v"(lo), "v"(hi)); return r; }
; __device__ __forceinline__ float x16_sum(float x) { auto s = __builtin_amdgcn_permlane16_swap(__float_as_uint(x), __float_as_uint(x), false, false); return __uint_as_float(s[0]) + __uint_as_float(s[1]); }
; __device__ __forceinline__ float x32_sum(float x) { auto s = __builtin_amdgcn_permlane32_swap(__float_as_uint(x), __float_as_uint(x), false, false); return __uint_as_float(s[0]) + __uint_as_float(s[1]); }
;     __device__ __forceinline__ void operator()(const f32x4 (&acc)[2][2][4][2], const Unit& u, int ui, int wr, int wc, int fr, int fq) const {
;         const int row0 = u.pm * 256 + wr * 64 + fr, col0 = u.pn * 256 + wc * 32 + 8 * fq;
;         const float* xb0 = (u.pm * 256 < MP) ? xp : xs - (size_t)MP * DM;
; #pragma unroll
;         for (int ai = 0; ai < 2; ++ai) {
;             f32x4 xv[4][2][2];
; #pragma unroll
;             for (int m = 0; m < 4; ++m)
; #pragma unroll
;                 for (int bj = 0; bj < 2; ++bj) { const float* p = xb0 + (size_t)(row0 + ai * 128 + m * 16) * DM + col0 + bj * 128; xv[m][bj][0] = *(const f32x4*)p; xv[m][bj][1] = *(const f32x4*)(p + 4); }
; #pragma unroll
;             for (int m = 0; m < 4; ++m) { const int row = row0 + ai * 128 + m * 16; const size_t off = (size_t)row * DM + col0; float ss = 0.f;
; #pragma unroll
;                 for (int bj = 0; bj < 2; ++bj) {
;                     const f32x4 v0 = acc[ai][bj][m][0] + xv[m][bj][0], v1 = acc[ai][bj][m][1] + xv[m][bj][1];
;                     u32x4 w; w.x = cvt_pk_bf16(v0[0], v0[1]); w.y = cvt_pk_bf16(v0[2], v0[3]); w.z = cvt_pk_bf16(v1[0], v1[1]); w.w = cvt_pk_bf16(v1[2], v1[3]);
;                     *(u32x4*)(xb + off + bj * 128) = w;
;                     ss += (v0[0] * v0[0] + v0[1] * v0[1]) + (v0[2] * v0[2] + v0[3] * v0[3]) + (v1[0] * v1[0] + v1[1] * v1[1]) + (v1[2] * v1[2] + v1[3] * v1[3]); }
;                 ss = x32_sum(x16_sum(ss));
;                 if (fq == 0) part[(size_t)row * 16 + u.pn * 4 + wc] = ss; }
	s_cmpk_lt_i32 s40, 0x80
	v_lshl_add_u32 v194, s40, 8, v204
	v_lshl_or_b32 v192, s12, 8, v206
	s_cselect_b32 s21, s37, s61
	s_cselect_b32 s23, s36, s60
	v_mov_b32_e32 v128, s23
	v_mov_b32_e32 v129, s21
	v_ashrrev_i32_e32 v193, 31, v192
	v_ashrrev_i32_e32 v195, 31, v194
	v_lshl_add_u64 v[196:197], v[192:193], 2, v[128:129]
	v_lshlrev_b64 v[128:129], 12, v[194:195]
	v_or_b32_e32 v202, 16, v194
	v_or_b32_e32 v200, 32, v194
	v_or_b32_e32 v198, 48, v194
	v_lshl_add_u64 v[128:129], v[196:197], 0, v[128:129]
	v_ashrrev_i32_e32 v203, 31, v202
	v_ashrrev_i32_e32 v201, 31, v200
	v_ashrrev_i32_e32 v199, 31, v198
	global_load_dwordx4 v[212:215], v[128:129], off
	global_load_dwordx4 v[216:219], v[128:129], off offset:16
	global_load_dwordx4 v[220:223], v[128:129], off offset:512
	global_load_dwordx4 v[224:227], v[128:129], off offset:528
	v_lshlrev_b64 v[128:129], 12, v[202:203]
	v_lshlrev_b64 v[130:131], 12, v[200:201]
	v_lshlrev_b64 v[132:133], 12, v[198:199]
	v_lshl_add_u64 v[128:129], v[196:197], 0, v[128:129]
	v_lshl_add_u64 v[130:131], v[196:197], 0, v[130:131]
	v_lshl_add_u64 v[132:133], v[196:197], 0, v[132:133]
	global_load_dwordx4 v[168:171], v[128:129], off offset:16
	global_load_dwordx4 v[172:175], v[128:129], off
	global_load_dwordx4 v[160:163], v[128:129], off offset:528
	global_load_dwordx4 v[164:167], v[128:129], off offset:512
	global_load_dwordx4 v[152:155], v[130:131], off offset:16
	global_load_dwordx4 v[156:159], v[130:131], off
	global_load_dwordx4 v[144:147], v[130:131], off offset:528
	global_load_dwordx4 v[148:151], v[130:131], off offset:512
	global_load_dwordx4 v[136:139], v[132:133], off offset:16
	global_load_dwordx4 v[140:143], v[132:133], off
	s_nop 0
	global_load_dwordx4 v[128:131], v[132:133], off offset:528
	s_nop 0
	global_load_dwordx4 v[132:135], v[132:133], off offset:512
	v_lshlrev_b64 v[228:229], 11, v[194:195]
	v_lshl_add_u64 v[228:229], s[14:15], 0, v[228:229]
	v_lshl_add_u64 v[228:229], v[192:193], 1, v[228:229]
	s_lshl_b32 s38, s12, 2
	s_ashr_i32 s39, s38, 31
	s_waitcnt vmcnt(0)
	v_pk_add_f32 v[126:127], v[126:127], v[214:215]
	v_pk_add_f32 v[124:125], v[124:125], v[212:213]
	v_pk_add_f32 v[118:119], v[118:119], v[222:223]
	v_pk_add_f32 v[116:117], v[116:117], v[220:221]
	v_pk_add_f32 v[120:121], v[120:121], v[216:217]
	v_pk_add_f32 v[214:215], v[112:113], v[224:225]
	v_cvt_pk_bf16_f32 v112, v124, v125
	v_cvt_pk_bf16_f32 v113, v126, v127
	v_mul_f32_e32 v125, v125, v125
	v_mul_f32_e32 v127, v127, v127
	v_mul_f32_e32 v211, v117, v117
	v_mul_f32_e32 v216, v119, v119
	v_pk_add_f32 v[122:123], v[122:123], v[218:219]
	v_pk_add_f32 v[212:213], v[114:115], v[226:227]
	v_cvt_pk_bf16_f32 v114, v120, v121
	v_cvt_pk_bf16_f32 v115, v122, v123
	v_mul_f32_e32 v121, v121, v121
	v_mul_f32_e32 v217, v215, v215
	global_store_dwordx4 v[228:229], v[112:115], off
	v_fmac_f32_e32 v125, v124, v124
	v_fmac_f32_e32 v127, v126, v126
	v_cvt_pk_bf16_f32 v112, v116, v117
	v_fmac_f32_e32 v211, v116, v116
	v_fmac_f32_e32 v216, v118, v118
	v_mul_f32_e32 v123, v123, v123
	v_mul_f32_e32 v218, v213, v213
	v_fmac_f32_e32 v121, v120, v120
	v_cvt_pk_bf16_f32 v113, v118, v119
	v_cvt_pk_bf16_f32 v114, v214, v215
	v_cvt_pk_bf16_f32 v115, v212, v213
	v_fmac_f32_e32 v217, v214, v214
	v_add_f32_e32 v116, v125, v127
	global_store_dwordx4 v[228:229], v[112:115], off offset:256
	v_fmac_f32_e32 v123, v122, v122
	v_fmac_f32_e32 v218, v212, v212
	v_add_f32_e32 v112, v211, v216
	v_add_f32_e32 v113, v116, v121
	v_add_f32_e32 v112, v112, v217
	v_add_f32_e32 v113, v123, v113
	v_add_f32_e32 v112, v218, v112
	v_add_f32_e32 v112, v113, v112
	v_mov_b32_e32 v113, v112
	s_nop 1
	v_permlane16_swap_b32_e32 v112, v113
	v_add_f32_e32 v112, v112, v113
	v_mov_b32_e32 v113, v112
	s_nop 1
	v_permlane32_swap_b32_e32 v112, v113
	s_and_saveexec_b64 s[40:41], s[6:7]
	s_cbranch_execz .LBB0_356
	v_lshlrev_b64 v[114:115], 6, v[194:195]
	v_lshl_add_u64 v[114:115], s[16:17], 0, v[114:115]
	v_lshl_add_u64 v[114:115], s[38:39], 2, v[114:115]
	s_lshl_b32 s12, s62, 2
	v_lshl_add_u64 v[114:115], v[114:115], 0, s[12:13]
	v_add_f32_e32 v112, v112, v113
	global_store_dword v[114:115], v112, off

; __device__ __forceinline__ unsigned xb_ld(unsigned* p)              { return __hip_atomic_load(p, __ATOMIC_RELAXED, __HIP_MEMORY_SCOPE_AGENT); }
; __device__ __forceinline__ void xcd_barrier_complete(unsigned* bar, unsigned x, unsigned& nloc, unsigned& nx) {
;     const unsigned G = gridDim.x * gridDim.y * gridDim.z;
;     unsigned sum, cnt, mine, sp = 0u;
;     for (;;) {
;         sum = 0u; cnt = 0u; mine = 0u;
; #pragma unroll
;         for (unsigned j = 0; j < 16; ++j) { const unsigned c = xb_ld(&bar[XB_XCNT(j)]); sum += c; cnt += (c > 0u) ? 1u : 0u; mine = (j == x) ? c : mine; }
; __device__ __forceinline__ void xcd_barrier(const XcdBarrier& b) {
;     asm volatile("s_waitcnt vmcnt(0)" ::: "memory");
;     __syncthreads();
;     if (threadIdx.x == 0) {
;         unsigned* bar = b.bar;
;         __builtin_amdgcn_s_waitcnt(0);
;         unsigned nloc = b.st[0], nx = b.st[1];
;         if (nloc == 0u) { xcd_barrier_complete(bar, b.x, nloc, nx); b.st[0] = nloc; b.st[1] = nx; }
.LBB0_373:
	s_nop 0
	s_nop 0
	s_nop 0
	s_nop 0
	s_nop 0
	s_nop 0
	s_nop 0
	s_nop 0
	s_nop 0
	s_nop 0
	s_nop 0
	s_nop 0
	s_nop 0
	s_nop 0
	s_nop 0
	s_nop 0
	s_nop 0
	s_nop 0
	s_nop 0
	s_nop 0
	s_nop 0
	s_nop 0
	s_nop 0
	s_nop 0
	s_nop 0
	s_nop 0
	s_nop 0
	s_nop 0
	s_nop 0
	s_nop 0
	s_nop 0
	s_nop 0
	s_nop 0
	s_nop 0
	s_nop 0
	s_nop 0
	s_nop 0
	s_nop 0
	s_nop 0
	s_nop 0
	s_nop 0
	s_nop 0
	s_nop 0
	s_nop 0
	s_nop 0
	s_nop 0
	s_nop 0
	s_nop 0
	s_nop 0
	s_cmp_gt_i32 s31, 4
	s_cselect_b64 s[0:1], -1, 0
	s_and_b64 s[4:5], s[10:11], s[0:1]
	s_andn2_b64 vcc, exec, s[4:5]
	s_cbranch_vccnz .LBB0_423
	s_waitcnt vmcnt(0)
	s_waitcnt vmcnt(0) lgkmcnt(0)
	s_barrier
	s_and_saveexec_b64 s[4:5], s[8:9]
	s_cbranch_execz .LBB0_422
	s_add_i32 s6, 0, 0x25ff0
	v_mov_b32_e32 v0, s6
	s_waitcnt vmcnt(0) expcnt(0) lgkmcnt(0)
	ds_read_b32 v2, v0
	s_add_i32 s6, 0, 0x25ff4
	v_mov_b32_e32 v0, s6
	ds_read_b32 v0, v0
	s_waitcnt lgkmcnt(1)
	v_cmp_ne_u32_e32 vcc, 0, v2
	s_cbranch_vccnz .LBB0_390
	s_load_dwordx2 s[12:13], s[52:53], 0x4
	s_add_u32 s6, s28, 0x3e800200
	s_addc_u32 s7, s29, 0
	s_add_u32 s10, s28, 0x3e800400
	s_addc_u32 s11, s29, 0
	s_waitcnt lgkmcnt(0)
	s_mul_i32 s60, s12, s3
	s_add_u32 s12, s28, 0x3e800500
	s_mul_i32 s60, s60, s13
	s_addc_u32 s13, s29, 0
	s_add_u32 s14, s28, 0x3e800600
	s_addc_u32 s15, s29, 0
	s_add_u32 s16, s28, 0x3e800700
	s_addc_u32 s17, s29, 0
	s_add_u32 s18, s28, 0x3e800800
	s_addc_u32 s19, s29, 0
	s_add_u32 s20, s28, 0x3e800900
	s_addc_u32 s21, s29, 0
	s_add_u32 s22, s28, 0x3e800a00
	s_addc_u32 s23, s29, 0
	s_add_u32 s24, s28, 0x3e800b00
	s_addc_u32 s25, s29, 0
	s_add_u32 s36, s28, 0x3e800c00
	s_addc_u32 s37, s29, 0
	s_add_u32 s38, s28, 0x3e800d00
	s_addc_u32 s39, s29, 0
	s_add_u32 s40, s28, 0x3e800e00
	s_addc_u32 s41, s29, 0
	s_add_u32 s42, s28, 0x3e800f00
	s_addc_u32 s43, s29, 0
	s_add_u32 s44, s28, 0x3e801000
	s_addc_u32 s45, s29, 0
	s_add_u32 s46, s28, 0x3e801100
	s_addc_u32 s47, s29, 0
	s_add_u32 s48, s28, 0x3e801200
	s_addc_u32 s49, s29, 0
	s_add_u32 s50, s28, 0x3e801300
	s_addc_u32 s51, s29, 0
	s_mov_b32 s61, 1
	v_mov_b32_e32 v16, 0
	s_branch .LBB0_378

; #define PG8_STAGE(bufoff, gbase, voff) do { _Pragma("unroll") for (int _i = 0; _i < 2; ++_i) \
;         __builtin_amdgcn_global_load_lds((const unsigned*)((const char*)(gbase) + (voff)[_i]), (LAS unsigned*)(lds + (bufoff) + ldsw + _i * 8192), 16, 0, 0); } while (0)
; #define PG8_WAIT_V(n) asm volatile("s_waitcnt vmcnt(" #n ")" ::: "memory")
; #define PG8_BAR __builtin_amdgcn_s_barrier()
; template <class Epi, class Ptrs>
; __device__ __forceinline__ void gemm_phase(LAS unsigned char* lds, const int K, const StaticOrder& S, const Ptrs& P, const Epi& E) {
;     ...
;     for (int i = 0; i < 2; ++i) { int R, C; stage_rc(tid * 16 + i * 8192, R, C); const int Rb = (R & ~31) + perm32(R & 31);
;         voffA[i] = (unsigned)(R * K + C) * 2u; voffB[i] = (unsigned)(Rb * K + C) * 2u; }
;     const size_t kstep = (size_t)(BK * 2);
;     const size_t hstep = (size_t)HALF * K * 2;
;     const unsigned ldsw = (unsigned)wid * 1024u;
;     const int aoff = lds_byte(wr * 64 + fr, fq * 8), boff = lds_byte(wc * 32 + fr, fq * 8);
;     ...
;     PG8_WAIT_V(4); PG8_BAR;
;     PG8_STAGE(PG8_SB(1, 0), cB + kstep, voffB); PG8_STAGE(PG8_SA(1, 0), cA + kstep, voffA); PG8_STAGE(PG8_SB(1, 1), cB + hstep + kstep, voffB);
;     PG8_WAIT_V(6); PG8_BAR;
.LBB0_427:
	s_nop 0
	s_nop 0
	s_nop 0
	s_nop 0
	s_nop 0
	s_nop 0
	s_nop 0
	s_nop 0
	s_nop 0
	s_nop 0
	s_nop 0
	s_nop 0
	s_nop 0
	s_nop 0
	s_nop 0
	s_nop 0
	s_nop 0
	s_add_u32 s10, s28, 0xe000000
	s_addc_u32 s11, s29, 0
	s_lshl_b32 s4, s4, 5
	s_mov_b64 s[12:13], 0x80
	s_and_b32 s15, s4, 0x60
	s_add_i32 m0, s39, 0x18000
	v_lshl_add_u64 v[6:7], v[6:7], 0, s[12:13]
	s_ashr_i32 s60, s3, 31
	s_lshl_b32 s14, s1, 13
	s_lshl_b32 s16, s15, 7
	s_waitcnt vmcnt(4)
	s_barrier
	global_load_lds_dwordx4 v[6:7], off
	v_lshl_add_u64 v[4:5], v[4:5], 0, s[12:13]
	s_add_i32 m0, s39, 0x1a000
	s_add_i32 s61, s39, 0x8000
	s_add_i32 s62, s39, 0xa000
	global_load_lds_dwordx4 v[4:5], off
	v_lshl_add_u64 v[2:3], v[2:3], 0, s[12:13]
	s_mov_b32 m0, s61
	s_add_u32 s4, s42, 0x40080
	global_load_lds_dwordx4 v[2:3], off
	v_lshl_add_u64 v[0:1], v[0:1], 0, s[12:13]
	s_mov_b32 m0, s62
	s_addc_u32 s5, s43, 0
	global_load_lds_dwordx4 v[0:1], off
	s_add_i32 m0, s39, 0x1c000
	v_lshl_add_u64 v[0:1], s[4:5], 0, v[130:131]
	global_load_lds_dwordx4 v[0:1], off
	v_lshl_add_u64 v[0:1], s[4:5], 0, v[134:135]
	s_add_i32 m0, s39, 0x1e000
	s_sext_i32_i8 s69, s0
	global_load_lds_dwordx4 v[0:1], off
	v_and_b32_e32 v0, 15, v208
	v_lshlrev_b32_e32 v1, 1, v11
	v_lshlrev_b32_e32 v2, 6, v208
	s_movk_i32 s0, 0x3c0
	v_lshlrev_b32_e32 v3, 2, v208
	v_and_or_b32 v2, v2, s0, v1
	v_and_b32_e32 v3, 32, v3
	v_lshl_or_b32 v146, s1, 6, v0
	v_lshl_or_b32 v0, v0, 6, v1
	v_lshlrev_b32_e32 v1, 8, v208
	v_bitop3_b32 v147, s16, v2, v3 bitop3:0xf6
	v_and_b32_e32 v1, 0x38000, v1
	v_lshlrev_b32_e32 v2, 11, v10
	v_or3_b32 v1, v8, v1, v2
	v_add_u32_e32 v136, v1, v9
	v_lshlrev_b32_e32 v1, 4, v12
	s_waitcnt vmcnt(6)
	v_and_b32_e32 v1, 0x78000, v1
	v_bitop3_b32 v0, v0, s14, v3 bitop3:0xde
	v_or3_b32 v1, v8, v1, v2
	s_add_i32 s63, 0, 0x10000
	s_add_i32 s64, 0, 0x14000
	v_or_b32_e32 v148, s15, v11
	v_mov_b32_e32 v137, v131
	v_add_u32_e32 v138, v1, v9
	v_mov_b32_e32 v139, v131
	v_mov_b64_e32 v[140:141], 0x1800
	v_mov_b64_e32 v[142:143], 0x17ff
	v_add_u32_e32 v149, s63, v147
	v_add_u32_e32 v150, 0, v0
	v_add_u32_e32 v151, s64, v147
	s_mov_b64 s[14:15], 0x100000
	s_mov_b32 s65, 0x100000
	s_mov_b64 s[16:17], 0x120000
	s_mov_b32 s66, 0x120000
	s_mov_b64 s[18:19], 0x140000
	s_mov_b32 s67, 0x140000
	s_mov_b64 s[20:21], 0x160000
	s_mov_b32 s68, 0x160000
	s_cmpk_lt_u32 s46, 0x100
	s_cbranch_scc1 .Lsprio_2
	s_setprio 1

; #define PG8_STAGE(bufoff, gbase, voff) do { _Pragma("unroll") for (int _i = 0; _i < 2; ++_i) \
;         __builtin_amdgcn_global_load_lds((const unsigned*)((const char*)(gbase) + (voff)[_i]), (LAS unsigned*)(lds + (bufoff) + ldsw + _i * 8192), 16, 0, 0); } while (0)
; #define PG8_LDA(dst, b, h) do { _Pragma("unroll") for (int m = 0; m < 4; ++m) _Pragma("unroll") for (int k = 0; k < 2; ++k) dst[m][k] = *(const LAS bf16x8*)(lds + PG8_SA(b, h) + aoff + m * 2048 + k * 1024); } while (0)
; #define PG8_LDB(dst, b, h) do { _Pragma("unroll") for (int n = 0; n < 2; ++n) _Pragma("unroll") for (int k = 0; k < 2; ++k) dst[n][k] = *(const LAS bf16x8*)(lds + PG8_SB(b, h) + boff + n * 2048 + k * 1024); } while (0)
; #define PG8_MMA(ai, bj, At, Bt) do { __builtin_amdgcn_s_setprio(1); _Pragma("unroll") for (int m = 0; m < 4; ++m) _Pragma("unroll") for (int n = 0; n < 2; ++n) _Pragma("unroll") for (int k = 0; k < 2; ++k) \
;         acc[ai][bj][m][n] = __builtin_amdgcn_mfma_f32_16x16x32_bf16(Bt[n][k], At[m][k], acc[ai][bj][m][n], 0, 0, 0); __builtin_amdgcn_s_setprio(0); } while (0)
; #define PG8_WAIT_V(n) asm volatile("s_waitcnt vmcnt(" #n ")" ::: "memory")
; #define PG8_WAIT_L(n) asm volatile("s_waitcnt lgkmcnt(" #n ")" ::: "memory")
; #define PG8_BAR __builtin_amdgcn_s_barrier()
; #define PG8_SCHED __builtin_amdgcn_sched_barrier(0)
; template <class Epi, class Ptrs>
; __device__ __forceinline__ void gemm_phase(LAS unsigned char* lds, const int K, const StaticOrder& S, const Ptrs& P, const Epi& E) {
;     ...
;             PG8_LDB(B0, 0, 0); PG8_SCHED; PG8_LDA(At, 0, 0); PG8_STAGE(PG8_SA(1, 1), a1 + hstep, voffA);
;             PG8_WAIT_L(8); PG8_BAR; PG8_WAIT_L(0); PG8_MMA(0, 0, At, B0); PG8_BAR; PG8_SCHED;
;             PG8_LDB(B1, 0, 1); PG8_STAGE(PG8_SB(0, 0), b2, voffB);
;             PG8_BAR; PG8_WAIT_L(0); PG8_MMA(0, 1, At, B1); PG8_BAR;
;             PG8_LDA(At, 0, 1); PG8_STAGE(PG8_SA(0, 0), a2, voffA);
;             PG8_BAR; PG8_WAIT_L(0); PG8_MMA(1, 0, At, B0); PG8_BAR; PG8_SCHED;
;             PG8_STAGE(PG8_SB(0, 1), b2 + hstep, voffB);
;             PG8_WAIT_V(6); PG8_BAR; PG8_MMA(1, 1, At, B1); PG8_BAR;
.LBB0_432:
	s_add_u32 s40, s40, 0x40080
	s_addc_u32 s41, s41, 0
	s_add_u32 s23, s42, 0x100
	s_addc_u32 s25, s43, 0
	s_mov_b32 s70, -2
	v_add_u32_e32 v252, 0x18000, v147
	v_add_u32_e32 v253, 0x1c000, v147
	ds_read_b128 v[152:155], v149
	ds_read_b128 v[156:159], v149 offset:1024
	ds_read_b128 v[160:163], v149 offset:2048
	ds_read_b128 v[164:167], v149 offset:3072
	s_add_u32 s42, s40, 0xfffc0080
	s_addc_u32 s43, s41, -1
	s_cmp_eq_u32 s70, 12
	s_cselect_b32 s45, s1, s43
	s_cselect_b32 s44, s0, s42
	s_cselect_b32 s43, s37, s25
	s_cselect_b32 s42, s36, s23
	s_add_i32 m0, s39, 0xc000
	ds_read_b128 v[168:171], v150
	ds_read_b128 v[172:175], v150 offset:1024
	ds_read_b128 v[176:179], v150 offset:2048
	ds_read_b128 v[180:183], v150 offset:3072
	ds_read_b128 v[184:187], v150 offset:4096
	ds_read_b128 v[188:191], v150 offset:5120
	ds_read_b128 v[192:195], v150 offset:6144
	ds_read_b128 v[196:199], v150 offset:7168
	global_load_lds_dwordx4 v136, s[40:41]
	s_add_i32 m0, s39, 0xe000
	s_nop 0
	global_load_lds_dwordx4 v138, s[40:41]
	s_waitcnt lgkmcnt(8)
	s_barrier
	s_waitcnt lgkmcnt(0)
	v_mfma_f32_16x16x32_bf16 v[124:127], v[152:155], v[168:171], 0
	v_mfma_f32_16x16x32_bf16 v[124:127], v[156:159], v[172:175], v[124:127]
	v_mfma_f32_16x16x32_bf16 v[120:123], v[164:167], v[172:175], 0
	v_mfma_f32_16x16x32_bf16 v[120:123], v[160:163], v[168:171], v[120:123]
	v_mfma_f32_16x16x32_bf16 v[104:107], v[160:163], v[176:179], 0
	v_mfma_f32_16x16x32_bf16 v[104:107], v[164:167], v[180:183], v[104:107]
	v_mfma_f32_16x16x32_bf16 v[108:111], v[156:159], v[180:183], 0
	v_mfma_f32_16x16x32_bf16 v[108:111], v[152:155], v[176:179], v[108:111]
	v_mfma_f32_16x16x32_bf16 v[92:95], v[152:155], v[184:187], 0
	v_mfma_f32_16x16x32_bf16 v[92:95], v[156:159], v[188:191], v[92:95]
	v_mfma_f32_16x16x32_bf16 v[88:91], v[164:167], v[188:191], 0
	v_mfma_f32_16x16x32_bf16 v[88:91], v[160:163], v[184:187], v[88:91]
	v_mfma_f32_16x16x32_bf16 v[72:75], v[160:163], v[192:195], 0
	v_mfma_f32_16x16x32_bf16 v[72:75], v[164:167], v[196:199], v[72:75]
	v_mfma_f32_16x16x32_bf16 v[76:79], v[156:159], v[196:199], 0
	v_mfma_f32_16x16x32_bf16 v[76:79], v[152:155], v[192:195], v[76:79]
	s_barrier
	s_add_i32 s71, s63, s51
	s_add_u32 s76, s42, 0x80
	s_addc_u32 s77, s43, 0
	s_mov_b32 m0, s71
	ds_read_b128 v[200:203], v151
	ds_read_b128 v[204:207], v151 offset:1024
	ds_read_b128 v[210:213], v151 offset:2048
	ds_read_b128 v[214:217], v151 offset:3072
	global_load_lds_dwordx4 v130, s[42:43]
	s_add_i32 m0, s71, 0x2000
	s_nop 0
	global_load_lds_dwordx4 v134, s[42:43]
	s_barrier
	s_waitcnt lgkmcnt(0)
	v_mfma_f32_16x16x32_bf16 v[116:119], v[200:203], v[168:171], 0
	v_mfma_f32_16x16x32_bf16 v[116:119], v[204:207], v[172:175], v[116:119]
	v_mfma_f32_16x16x32_bf16 v[112:115], v[214:217], v[172:175], 0
	v_mfma_f32_16x16x32_bf16 v[112:115], v[210:213], v[168:171], v[112:115]
	v_mfma_f32_16x16x32_bf16 v[96:99], v[210:213], v[176:179], 0
	v_mfma_f32_16x16x32_bf16 v[96:99], v[214:217], v[180:183], v[96:99]
	v_mfma_f32_16x16x32_bf16 v[100:103], v[204:207], v[180:183], 0
	v_mfma_f32_16x16x32_bf16 v[100:103], v[200:203], v[176:179], v[100:103]
	v_mfma_f32_16x16x32_bf16 v[84:87], v[200:203], v[184:187], 0
	v_mfma_f32_16x16x32_bf16 v[84:87], v[204:207], v[188:191], v[84:87]
	v_mfma_f32_16x16x32_bf16 v[80:83], v[214:217], v[188:191], 0
	v_mfma_f32_16x16x32_bf16 v[80:83], v[210:213], v[184:187], v[80:83]
	v_mfma_f32_16x16x32_bf16 v[64:67], v[210:213], v[192:195], 0
	v_mfma_f32_16x16x32_bf16 v[64:67], v[214:217], v[196:199], v[64:67]
	v_mfma_f32_16x16x32_bf16 v[68:71], v[204:207], v[196:199], 0
	v_mfma_f32_16x16x32_bf16 v[68:71], v[200:203], v[192:195], v[68:71]
	s_barrier
	s_mov_b32 m0, s39
	s_add_u32 s78, s44, 0x80
	s_addc_u32 s79, s45, 0
	ds_read_b128 v[168:171], v150 offset:16384
	ds_read_b128 v[172:175], v150 offset:17408
	ds_read_b128 v[176:179], v150 offset:18432
	ds_read_b128 v[180:183], v150 offset:19456
	ds_read_b128 v[184:187], v150 offset:20480
	ds_read_b128 v[188:191], v150 offset:21504
	ds_read_b128 v[192:195], v150 offset:22528
	ds_read_b128 v[196:199], v150 offset:23552
	global_load_lds_dwordx4 v128, s[44:45]
	s_mov_b32 m0, s56
	s_nop 0
	global_load_lds_dwordx4 v132, s[44:45]
	s_barrier
	s_waitcnt lgkmcnt(0)
	v_mfma_f32_16x16x32_bf16 v[60:63], v[152:155], v[168:171], 0
	v_mfma_f32_16x16x32_bf16 v[60:63], v[156:159], v[172:175], v[60:63]
	v_mfma_f32_16x16x32_bf16 v[56:59], v[164:167], v[172:175], 0
	v_mfma_f32_16x16x32_bf16 v[56:59], v[160:163], v[168:171], v[56:59]
	v_mfma_f32_16x16x32_bf16 v[40:43], v[160:163], v[176:179], 0
	v_mfma_f32_16x16x32_bf16 v[40:43], v[164:167], v[180:183], v[40:43]
	v_mfma_f32_16x16x32_bf16 v[44:47], v[156:159], v[180:183], 0
	v_mfma_f32_16x16x32_bf16 v[44:47], v[152:155], v[176:179], v[44:47]
	v_mfma_f32_16x16x32_bf16 v[28:31], v[152:155], v[184:187], 0
	v_mfma_f32_16x16x32_bf16 v[28:31], v[156:159], v[188:191], v[28:31]
	v_mfma_f32_16x16x32_bf16 v[24:27], v[164:167], v[188:191], 0
	v_mfma_f32_16x16x32_bf16 v[24:27], v[160:163], v[184:187], v[24:27]
	v_mfma_f32_16x16x32_bf16 v[8:11], v[160:163], v[192:195], 0
	v_mfma_f32_16x16x32_bf16 v[8:11], v[164:167], v[196:199], v[8:11]
	v_mfma_f32_16x16x32_bf16 v[12:15], v[156:159], v[196:199], 0
	v_mfma_f32_16x16x32_bf16 v[12:15], v[152:155], v[192:195], v[12:15]
	s_barrier
	s_add_u32 s72, s42, 0x40000
	s_addc_u32 s73, s43, 0
	s_add_i32 s71, s64, s51
	s_mov_b32 m0, s71
	s_nop 0
	global_load_lds_dwordx4 v130, s[72:73]
	s_add_i32 m0, s71, 0x2000
	s_nop 0
	global_load_lds_dwordx4 v134, s[72:73]
	s_waitcnt vmcnt(6)
	s_barrier
; #define PG8_STAGE(bufoff, gbase, voff) do { _Pragma("unroll") for (int _i = 0; _i < 2; ++_i) \
;         __builtin_amdgcn_global_load_lds((const unsigned*)((const char*)(gbase) + (voff)[_i]), (LAS unsigned*)(lds + (bufoff) + ldsw + _i * 8192), 16, 0, 0); } while (0)
; #define PG8_LDA(dst, b, h) do { _Pragma("unroll") for (int m = 0; m < 4; ++m) _Pragma("unroll") for (int k = 0; k < 2; ++k) dst[m][k] = *(const LAS bf16x8*)(lds + PG8_SA(b, h) + aoff + m * 2048 + k * 1024); } while (0)
; #define PG8_LDB(dst, b, h) do { _Pragma("unroll") for (int n = 0; n < 2; ++n) _Pragma("unroll") for (int k = 0; k < 2; ++k) dst[n][k] = *(const LAS bf16x8*)(lds + PG8_SB(b, h) + boff + n * 2048 + k * 1024); } while (0)
; #define PG8_MMA(ai, bj, At, Bt) do { __builtin_amdgcn_s_setprio(1); _Pragma("unroll") for (int m = 0; m < 4; ++m) _Pragma("unroll") for (int n = 0; n < 2; ++n) _Pragma("unroll") for (int k = 0; k < 2; ++k) \
;         acc[ai][bj][m][n] = __builtin_amdgcn_mfma_f32_16x16x32_bf16(Bt[n][k], At[m][k], acc[ai][bj][m][n], 0, 0, 0); __builtin_amdgcn_s_setprio(0); } while (0)
; #define PG8_WAIT_V(n) asm volatile("s_waitcnt vmcnt(" #n ")" ::: "memory")
; #define PG8_WAIT_L(n) asm volatile("s_waitcnt lgkmcnt(" #n ")" ::: "memory")
; #define PG8_BAR __builtin_amdgcn_s_barrier()
; #define PG8_SCHED __builtin_amdgcn_sched_barrier(0)
; template <class Epi, class Ptrs>
; __device__ __forceinline__ void gemm_phase(LAS unsigned char* lds, const int K, const StaticOrder& S, const Ptrs& P, const Epi& E) {
;     ...
;             PG8_WAIT_V(6); PG8_BAR; PG8_MMA(1, 1, At, B1); PG8_BAR;
;             PG8_LDB(B0, 1, 0); PG8_SCHED; PG8_LDA(At, 1, 0); PG8_STAGE(PG8_SA(0, 1), a2 + hstep, voffA);
;             PG8_WAIT_L(8); PG8_BAR; PG8_WAIT_L(0); PG8_MMA(0, 0, At, B0); PG8_BAR; PG8_SCHED;
;             PG8_LDB(B1, 1, 1); PG8_STAGE(PG8_SB(1, 0), b3, voffB);
;             PG8_BAR; PG8_WAIT_L(0); PG8_MMA(0, 1, At, B1); PG8_BAR;
;             PG8_LDA(At, 1, 1); PG8_STAGE(PG8_SA(1, 0), a3, voffA);
;             PG8_BAR; PG8_WAIT_L(0); PG8_MMA(1, 0, At, B0); PG8_BAR; PG8_SCHED;
	v_mfma_f32_16x16x32_bf16 v[52:55], v[200:203], v[168:171], 0
	v_mfma_f32_16x16x32_bf16 v[52:55], v[204:207], v[172:175], v[52:55]
	v_mfma_f32_16x16x32_bf16 v[48:51], v[214:217], v[172:175], 0
	v_mfma_f32_16x16x32_bf16 v[48:51], v[210:213], v[168:171], v[48:51]
	v_mfma_f32_16x16x32_bf16 v[32:35], v[210:213], v[176:179], 0
	v_mfma_f32_16x16x32_bf16 v[32:35], v[214:217], v[180:183], v[32:35]
	v_mfma_f32_16x16x32_bf16 v[36:39], v[204:207], v[180:183], 0
	v_mfma_f32_16x16x32_bf16 v[36:39], v[200:203], v[176:179], v[36:39]
	v_mfma_f32_16x16x32_bf16 v[20:23], v[200:203], v[184:187], 0
	v_mfma_f32_16x16x32_bf16 v[20:23], v[204:207], v[188:191], v[20:23]
	v_mfma_f32_16x16x32_bf16 v[16:19], v[214:217], v[188:191], 0
	v_mfma_f32_16x16x32_bf16 v[16:19], v[210:213], v[184:187], v[16:19]
	v_mfma_f32_16x16x32_bf16 v[0:3], v[210:213], v[192:195], 0
	v_mfma_f32_16x16x32_bf16 v[0:3], v[214:217], v[196:199], v[0:3]
	v_mfma_f32_16x16x32_bf16 v[4:7], v[204:207], v[196:199], 0
	v_mfma_f32_16x16x32_bf16 v[4:7], v[200:203], v[192:195], v[4:7]
	s_barrier
	s_add_i32 s71, 0, 0x18000
	ds_read_b128 v[152:155], v252
	ds_read_b128 v[156:159], v252 offset:1024
	ds_read_b128 v[160:163], v252 offset:2048
	ds_read_b128 v[164:167], v252 offset:3072
	s_add_u32 s44, s44, 0x40000
	s_addc_u32 s45, s45, 0
	s_mov_b32 m0, s57
	ds_read_b128 v[168:171], v150 offset:32768
	ds_read_b128 v[172:175], v150 offset:33792
	ds_read_b128 v[176:179], v150 offset:34816
	ds_read_b128 v[180:183], v150 offset:35840
	ds_read_b128 v[184:187], v150 offset:36864
	ds_read_b128 v[188:191], v150 offset:37888
	ds_read_b128 v[192:195], v150 offset:38912
	ds_read_b128 v[196:199], v150 offset:39936
	global_load_lds_dwordx4 v128, s[44:45]
	s_mov_b32 m0, s58
	s_nop 0
	global_load_lds_dwordx4 v132, s[44:45]
	s_waitcnt lgkmcnt(8)
	s_barrier
	s_waitcnt lgkmcnt(0)
	v_mfma_f32_16x16x32_bf16 v[124:127], v[152:155], v[168:171], v[124:127]
	v_mfma_f32_16x16x32_bf16 v[124:127], v[156:159], v[172:175], v[124:127]
	v_mfma_f32_16x16x32_bf16 v[120:123], v[164:167], v[172:175], v[120:123]
	v_mfma_f32_16x16x32_bf16 v[120:123], v[160:163], v[168:171], v[120:123]
	v_mfma_f32_16x16x32_bf16 v[104:107], v[160:163], v[176:179], v[104:107]
	v_mfma_f32_16x16x32_bf16 v[104:107], v[164:167], v[180:183], v[104:107]
	v_mfma_f32_16x16x32_bf16 v[108:111], v[156:159], v[180:183], v[108:111]
	v_mfma_f32_16x16x32_bf16 v[108:111], v[152:155], v[176:179], v[108:111]
	v_mfma_f32_16x16x32_bf16 v[92:95], v[152:155], v[184:187], v[92:95]
	v_mfma_f32_16x16x32_bf16 v[92:95], v[156:159], v[188:191], v[92:95]
	v_mfma_f32_16x16x32_bf16 v[88:91], v[164:167], v[188:191], v[88:91]
	v_mfma_f32_16x16x32_bf16 v[88:91], v[160:163], v[184:187], v[88:91]
	v_mfma_f32_16x16x32_bf16 v[72:75], v[160:163], v[192:195], v[72:75]
	v_mfma_f32_16x16x32_bf16 v[72:75], v[164:167], v[196:199], v[72:75]
	v_mfma_f32_16x16x32_bf16 v[76:79], v[156:159], v[196:199], v[76:79]
	v_mfma_f32_16x16x32_bf16 v[76:79], v[152:155], v[192:195], v[76:79]
	s_barrier
	s_add_i32 s44, 0, 0x1c000
	s_add_i32 s45, s71, s51
	s_mov_b32 m0, s45
	ds_read_b128 v[200:203], v253
	ds_read_b128 v[204:207], v253 offset:1024
	ds_read_b128 v[210:213], v253 offset:2048
	ds_read_b128 v[214:217], v253 offset:3072
	global_load_lds_dwordx4 v130, s[76:77]
	s_add_i32 m0, s45, 0x2000
	s_nop 0
	global_load_lds_dwordx4 v134, s[76:77]
	s_barrier
	s_waitcnt lgkmcnt(0)
	v_mfma_f32_16x16x32_bf16 v[116:119], v[200:203], v[168:171], v[116:119]
	v_mfma_f32_16x16x32_bf16 v[116:119], v[204:207], v[172:175], v[116:119]
	v_mfma_f32_16x16x32_bf16 v[112:115], v[214:217], v[172:175], v[112:115]
	v_mfma_f32_16x16x32_bf16 v[112:115], v[210:213], v[168:171], v[112:115]
	v_mfma_f32_16x16x32_bf16 v[96:99], v[210:213], v[176:179], v[96:99]
	v_mfma_f32_16x16x32_bf16 v[96:99], v[214:217], v[180:183], v[96:99]
	v_mfma_f32_16x16x32_bf16 v[100:103], v[204:207], v[180:183], v[100:103]
	v_mfma_f32_16x16x32_bf16 v[100:103], v[200:203], v[176:179], v[100:103]
	v_mfma_f32_16x16x32_bf16 v[84:87], v[200:203], v[184:187], v[84:87]
	v_mfma_f32_16x16x32_bf16 v[84:87], v[204:207], v[188:191], v[84:87]
	v_mfma_f32_16x16x32_bf16 v[80:83], v[214:217], v[188:191], v[80:83]
	v_mfma_f32_16x16x32_bf16 v[80:83], v[210:213], v[184:187], v[80:83]
	v_mfma_f32_16x16x32_bf16 v[64:67], v[210:213], v[192:195], v[64:67]
	v_mfma_f32_16x16x32_bf16 v[64:67], v[214:217], v[196:199], v[64:67]
	v_mfma_f32_16x16x32_bf16 v[68:71], v[204:207], v[196:199], v[68:71]
	v_mfma_f32_16x16x32_bf16 v[68:71], v[200:203], v[192:195], v[68:71]
	s_barrier
	s_mov_b32 m0, s61
	ds_read_b128 v[168:171], v150 offset:49152
	ds_read_b128 v[172:175], v150 offset:50176
	ds_read_b128 v[176:179], v150 offset:51200
	ds_read_b128 v[180:183], v150 offset:52224
	ds_read_b128 v[184:187], v150 offset:53248
	ds_read_b128 v[188:191], v150 offset:54272
	ds_read_b128 v[192:195], v150 offset:55296
	ds_read_b128 v[196:199], v150 offset:56320
	global_load_lds_dwordx4 v128, s[78:79]
	s_mov_b32 m0, s62
	s_nop 0
	global_load_lds_dwordx4 v132, s[78:79]
	s_barrier
	s_waitcnt lgkmcnt(0)
	v_mfma_f32_16x16x32_bf16 v[60:63], v[152:155], v[168:171], v[60:63]
	v_mfma_f32_16x16x32_bf16 v[60:63], v[156:159], v[172:175], v[60:63]
	v_mfma_f32_16x16x32_bf16 v[56:59], v[164:167], v[172:175], v[56:59]
	v_mfma_f32_16x16x32_bf16 v[56:59], v[160:163], v[168:171], v[56:59]
	v_mfma_f32_16x16x32_bf16 v[40:43], v[160:163], v[176:179], v[40:43]
	v_mfma_f32_16x16x32_bf16 v[40:43], v[164:167], v[180:183], v[40:43]
	v_mfma_f32_16x16x32_bf16 v[44:47], v[156:159], v[180:183], v[44:47]
	v_mfma_f32_16x16x32_bf16 v[44:47], v[152:155], v[176:179], v[44:47]
	v_mfma_f32_16x16x32_bf16 v[28:31], v[152:155], v[184:187], v[28:31]
	v_mfma_f32_16x16x32_bf16 v[28:31], v[156:159], v[188:191], v[28:31]
	v_mfma_f32_16x16x32_bf16 v[24:27], v[164:167], v[188:191], v[24:27]
	v_mfma_f32_16x16x32_bf16 v[24:27], v[160:163], v[184:187], v[24:27]
	v_mfma_f32_16x16x32_bf16 v[8:11], v[160:163], v[192:195], v[8:11]
	v_mfma_f32_16x16x32_bf16 v[8:11], v[164:167], v[196:199], v[8:11]
	v_mfma_f32_16x16x32_bf16 v[12:15], v[156:159], v[196:199], v[12:15]
	v_mfma_f32_16x16x32_bf16 v[12:15], v[152:155], v[192:195], v[12:15]
	s_barrier
; #define PG8_STAGE(bufoff, gbase, voff) do { _Pragma("unroll") for (int _i = 0; _i < 2; ++_i) \
;         __builtin_amdgcn_global_load_lds((const unsigned*)((const char*)(gbase) + (voff)[_i]), (LAS unsigned*)(lds + (bufoff) + ldsw + _i * 8192), 16, 0, 0); } while (0)
; #define PG8_LDA(dst, b, h) do { _Pragma("unroll") for (int m = 0; m < 4; ++m) _Pragma("unroll") for (int k = 0; k < 2; ++k) dst[m][k] = *(const LAS bf16x8*)(lds + PG8_SA(b, h) + aoff + m * 2048 + k * 1024); } while (0)
; #define PG8_LDB(dst, b, h) do { _Pragma("unroll") for (int n = 0; n < 2; ++n) _Pragma("unroll") for (int k = 0; k < 2; ++k) dst[n][k] = *(const LAS bf16x8*)(lds + PG8_SB(b, h) + boff + n * 2048 + k * 1024); } while (0)
; #define PG8_WAIT_V(n) asm volatile("s_waitcnt vmcnt(" #n ")" ::: "memory")
; #define PG8_WAIT_L(n) asm volatile("s_waitcnt lgkmcnt(" #n ")" ::: "memory")
; #define PG8_BAR __builtin_amdgcn_s_barrier()
; #define PG8_SCHED __builtin_amdgcn_sched_barrier(0)
; template <class Epi, class Ptrs>
; __device__ __forceinline__ void gemm_phase(LAS unsigned char* lds, const int K, const StaticOrder& S, const Ptrs& P, const Epi& E) {
;     ...
;             PG8_LDB(B0, 0, 0); PG8_SCHED; PG8_LDA(At, 0, 0); PG8_STAGE(PG8_SA(1, 1), a1 + hstep, voffA);
;             PG8_WAIT_L(8); PG8_BAR; PG8_WAIT_L(0); PG8_MMA(0, 0, At, B0); PG8_BAR; PG8_SCHED;
;             PG8_LDB(B1, 0, 1); PG8_STAGE(PG8_SB(0, 0), b2, voffB);
;             PG8_BAR; PG8_WAIT_L(0); PG8_MMA(0, 1, At, B1); PG8_BAR;
;             PG8_LDA(At, 0, 1); PG8_STAGE(PG8_SA(0, 0), a2, voffA);
;             PG8_BAR; PG8_WAIT_L(0); PG8_MMA(1, 0, At, B0); PG8_BAR; PG8_SCHED;
;             PG8_STAGE(PG8_SB(0, 1), b2 + hstep, voffB);
;             PG8_WAIT_V(6); PG8_BAR; PG8_MMA(1, 1, At, B1); PG8_BAR;
;             PG8_LDB(B0, 1, 0); PG8_SCHED; PG8_LDA(At, 1, 0); PG8_STAGE(PG8_SA(0, 1), a2 + hstep, voffA);
;             PG8_WAIT_L(8); PG8_BAR; PG8_WAIT_L(0); PG8_MMA(0, 0, At, B0); PG8_BAR; PG8_SCHED;
;             PG8_LDB(B1, 1, 1); PG8_STAGE(PG8_SB(1, 0), b3, voffB);
;             PG8_BAR; PG8_WAIT_L(0); PG8_MMA(0, 1, At, B1); PG8_BAR;
;             PG8_LDA(At, 1, 1); PG8_STAGE(PG8_SA(1, 0), a3, voffA);
;             PG8_BAR; PG8_WAIT_L(0); PG8_MMA(1, 0, At, B0); PG8_BAR; PG8_SCHED;
;             PG8_STAGE(PG8_SB(1, 1), b3 + hstep, voffB);
;             PG8_WAIT_V(6); PG8_BAR; PG8_MMA(1, 1, At, B1); PG8_BAR;
	s_add_u32 s42, s42, 0x40080
	s_addc_u32 s43, s43, 0
	s_add_i32 s44, s44, s51
	s_mov_b32 m0, s44
	s_nop 0
	global_load_lds_dwordx4 v130, s[42:43]
	s_add_i32 m0, s44, 0x2000
	s_nop 0
	global_load_lds_dwordx4 v134, s[42:43]
	s_waitcnt vmcnt(6)
	s_barrier
	v_mfma_f32_16x16x32_bf16 v[52:55], v[200:203], v[168:171], v[52:55]
	v_mfma_f32_16x16x32_bf16 v[52:55], v[204:207], v[172:175], v[52:55]
	v_mfma_f32_16x16x32_bf16 v[48:51], v[214:217], v[172:175], v[48:51]
	v_mfma_f32_16x16x32_bf16 v[48:51], v[210:213], v[168:171], v[48:51]
	v_mfma_f32_16x16x32_bf16 v[32:35], v[210:213], v[176:179], v[32:35]
	v_mfma_f32_16x16x32_bf16 v[32:35], v[214:217], v[180:183], v[32:35]
	v_mfma_f32_16x16x32_bf16 v[36:39], v[204:207], v[180:183], v[36:39]
	v_mfma_f32_16x16x32_bf16 v[36:39], v[200:203], v[176:179], v[36:39]
	v_mfma_f32_16x16x32_bf16 v[20:23], v[200:203], v[184:187], v[20:23]
	v_mfma_f32_16x16x32_bf16 v[20:23], v[204:207], v[188:191], v[20:23]
	v_mfma_f32_16x16x32_bf16 v[16:19], v[214:217], v[188:191], v[16:19]
	v_mfma_f32_16x16x32_bf16 v[16:19], v[210:213], v[184:187], v[16:19]
	v_mfma_f32_16x16x32_bf16 v[0:3], v[210:213], v[192:195], v[0:3]
	v_mfma_f32_16x16x32_bf16 v[0:3], v[214:217], v[196:199], v[0:3]
	v_mfma_f32_16x16x32_bf16 v[4:7], v[204:207], v[196:199], v[4:7]
	v_mfma_f32_16x16x32_bf16 v[4:7], v[200:203], v[192:195], v[4:7]
	s_barrier
	s_add_i32 s70, s70, 2
	s_add_u32 s40, s40, 0x100
	s_addc_u32 s41, s41, 0
	s_add_u32 s23, s23, 0x100
	s_addc_u32 s25, s25, 0
	s_cmp_gt_u32 s70, 13
.LBB0_433:
	ds_read_b128 v[152:155], v149
	ds_read_b128 v[156:159], v149 offset:1024
	ds_read_b128 v[160:163], v149 offset:2048
	ds_read_b128 v[164:167], v149 offset:3072
	s_add_u32 s42, s40, 0xfffc0080
	s_addc_u32 s43, s41, -1
	s_cmp_eq_u32 s70, 12
	s_cselect_b32 s45, s1, s43
	s_cselect_b32 s44, s0, s42
	s_cselect_b32 s43, s37, s25
	s_cselect_b32 s42, s36, s23
	s_add_i32 m0, s39, 0xc000
	ds_read_b128 v[168:171], v150
	ds_read_b128 v[172:175], v150 offset:1024
	ds_read_b128 v[176:179], v150 offset:2048
	ds_read_b128 v[180:183], v150 offset:3072
	ds_read_b128 v[184:187], v150 offset:4096
	ds_read_b128 v[188:191], v150 offset:5120
	ds_read_b128 v[192:195], v150 offset:6144
	ds_read_b128 v[196:199], v150 offset:7168
	global_load_lds_dwordx4 v136, s[40:41]
	s_add_i32 m0, s39, 0xe000
	s_nop 0
	global_load_lds_dwordx4 v138, s[40:41]
	s_waitcnt lgkmcnt(8)
	s_barrier
	s_waitcnt lgkmcnt(0)
	v_mfma_f32_16x16x32_bf16 v[124:127], v[152:155], v[168:171], v[124:127]
	v_mfma_f32_16x16x32_bf16 v[124:127], v[156:159], v[172:175], v[124:127]
	v_mfma_f32_16x16x32_bf16 v[120:123], v[164:167], v[172:175], v[120:123]
	v_mfma_f32_16x16x32_bf16 v[120:123], v[160:163], v[168:171], v[120:123]
	v_mfma_f32_16x16x32_bf16 v[104:107], v[160:163], v[176:179], v[104:107]
	v_mfma_f32_16x16x32_bf16 v[104:107], v[164:167], v[180:183], v[104:107]
	v_mfma_f32_16x16x32_bf16 v[108:111], v[156:159], v[180:183], v[108:111]
	v_mfma_f32_16x16x32_bf16 v[108:111], v[152:155], v[176:179], v[108:111]
	v_mfma_f32_16x16x32_bf16 v[92:95], v[152:155], v[184:187], v[92:95]
	v_mfma_f32_16x16x32_bf16 v[92:95], v[156:159], v[188:191], v[92:95]
	v_mfma_f32_16x16x32_bf16 v[88:91], v[164:167], v[188:191], v[88:91]
	v_mfma_f32_16x16x32_bf16 v[88:91], v[160:163], v[184:187], v[88:91]
	v_mfma_f32_16x16x32_bf16 v[72:75], v[160:163], v[192:195], v[72:75]
	v_mfma_f32_16x16x32_bf16 v[72:75], v[164:167], v[196:199], v[72:75]
	v_mfma_f32_16x16x32_bf16 v[76:79], v[156:159], v[196:199], v[76:79]
	v_mfma_f32_16x16x32_bf16 v[76:79], v[152:155], v[192:195], v[76:79]
	s_barrier
	s_add_i32 s71, s63, s51
	s_add_u32 s76, s42, 0x80
	s_addc_u32 s77, s43, 0
	s_mov_b32 m0, s71
	ds_read_b128 v[200:203], v151
	ds_read_b128 v[204:207], v151 offset:1024
	ds_read_b128 v[210:213], v151 offset:2048
	ds_read_b128 v[214:217], v151 offset:3072
	global_load_lds_dwordx4 v130, s[42:43]
	s_add_i32 m0, s71, 0x2000
	s_nop 0
	global_load_lds_dwordx4 v134, s[42:43]
	s_barrier
	s_waitcnt lgkmcnt(0)
	v_mfma_f32_16x16x32_bf16 v[116:119], v[200:203], v[168:171], v[116:119]
	v_mfma_f32_16x16x32_bf16 v[116:119], v[204:207], v[172:175], v[116:119]
	v_mfma_f32_16x16x32_bf16 v[112:115], v[214:217], v[172:175], v[112:115]
	v_mfma_f32_16x16x32_bf16 v[112:115], v[210:213], v[168:171], v[112:115]
	v_mfma_f32_16x16x32_bf16 v[96:99], v[210:213], v[176:179], v[96:99]
	v_mfma_f32_16x16x32_bf16 v[96:99], v[214:217], v[180:183], v[96:99]
	v_mfma_f32_16x16x32_bf16 v[100:103], v[204:207], v[180:183], v[100:103]
	v_mfma_f32_16x16x32_bf16 v[100:103], v[200:203], v[176:179], v[100:103]
	v_mfma_f32_16x16x32_bf16 v[84:87], v[200:203], v[184:187], v[84:87]
	v_mfma_f32_16x16x32_bf16 v[84:87], v[204:207], v[188:191], v[84:87]
	v_mfma_f32_16x16x32_bf16 v[80:83], v[214:217], v[188:191], v[80:83]
	v_mfma_f32_16x16x32_bf16 v[80:83], v[210:213], v[184:187], v[80:83]
	v_mfma_f32_16x16x32_bf16 v[64:67], v[210:213], v[192:195], v[64:67]
	v_mfma_f32_16x16x32_bf16 v[64:67], v[214:217], v[196:199], v[64:67]
	v_mfma_f32_16x16x32_bf16 v[68:71], v[204:207], v[196:199], v[68:71]
	v_mfma_f32_16x16x32_bf16 v[68:71], v[200:203], v[192:195], v[68:71]
	s_barrier
	s_mov_b32 m0, s39
	s_add_u32 s78, s44, 0x80
	s_addc_u32 s79, s45, 0
	ds_read_b128 v[168:171], v150 offset:16384
	ds_read_b128 v[172:175], v150 offset:17408
	ds_read_b128 v[176:179], v150 offset:18432
	ds_read_b128 v[180:183], v150 offset:19456
	ds_read_b128 v[184:187], v150 offset:20480
	ds_read_b128 v[188:191], v150 offset:21504
	ds_read_b128 v[192:195], v150 offset:22528
	ds_read_b128 v[196:199], v150 offset:23552
	global_load_lds_dwordx4 v128, s[44:45]
	s_mov_b32 m0, s56
	s_nop 0
	global_load_lds_dwordx4 v132, s[44:45]
	s_barrier
; #define PG8_STAGE(bufoff, gbase, voff) do { _Pragma("unroll") for (int _i = 0; _i < 2; ++_i) \
;         __builtin_amdgcn_global_load_lds((const unsigned*)((const char*)(gbase) + (voff)[_i]), (LAS unsigned*)(lds + (bufoff) + ldsw + _i * 8192), 16, 0, 0); } while (0)
; #define PG8_LDA(dst, b, h) do { _Pragma("unroll") for (int m = 0; m < 4; ++m) _Pragma("unroll") for (int k = 0; k < 2; ++k) dst[m][k] = *(const LAS bf16x8*)(lds + PG8_SA(b, h) + aoff + m * 2048 + k * 1024); } while (0)
; #define PG8_LDB(dst, b, h) do { _Pragma("unroll") for (int n = 0; n < 2; ++n) _Pragma("unroll") for (int k = 0; k < 2; ++k) dst[n][k] = *(const LAS bf16x8*)(lds + PG8_SB(b, h) + boff + n * 2048 + k * 1024); } while (0)
; #define PG8_MMA(ai, bj, At, Bt) do { __builtin_amdgcn_s_setprio(1); _Pragma("unroll") for (int m = 0; m < 4; ++m) _Pragma("unroll") for (int n = 0; n < 2; ++n) _Pragma("unroll") for (int k = 0; k < 2; ++k) \
;         acc[ai][bj][m][n] = __builtin_amdgcn_mfma_f32_16x16x32_bf16(Bt[n][k], At[m][k], acc[ai][bj][m][n], 0, 0, 0); __builtin_amdgcn_s_setprio(0); } while (0)
; #define PG8_WAIT_V(n) asm volatile("s_waitcnt vmcnt(" #n ")" ::: "memory")
; #define PG8_WAIT_L(n) asm volatile("s_waitcnt lgkmcnt(" #n ")" ::: "memory")
; #define PG8_BAR __builtin_amdgcn_s_barrier()
; #define PG8_SCHED __builtin_amdgcn_sched_barrier(0)
; template <class Epi, class Ptrs>
; __device__ __forceinline__ void gemm_phase(LAS unsigned char* lds, const int K, const StaticOrder& S, const Ptrs& P, const Epi& E) {
;     ...
;             PG8_BAR; PG8_WAIT_L(0); PG8_MMA(1, 0, At, B0); PG8_BAR; PG8_SCHED;
;             PG8_STAGE(PG8_SB(0, 1), b2 + hstep, voffB);
;             PG8_WAIT_V(6); PG8_BAR; PG8_MMA(1, 1, At, B1); PG8_BAR;
;             PG8_LDB(B0, 1, 0); PG8_SCHED; PG8_LDA(At, 1, 0); PG8_STAGE(PG8_SA(0, 1), a2 + hstep, voffA);
;             PG8_WAIT_L(8); PG8_BAR; PG8_WAIT_L(0); PG8_MMA(0, 0, At, B0); PG8_BAR; PG8_SCHED;
;             PG8_LDB(B1, 1, 1); PG8_STAGE(PG8_SB(1, 0), b3, voffB);
;             PG8_BAR; PG8_WAIT_L(0); PG8_MMA(0, 1, At, B1); PG8_BAR;
	s_waitcnt lgkmcnt(0)
	v_mfma_f32_16x16x32_bf16 v[60:63], v[152:155], v[168:171], v[60:63]
	v_mfma_f32_16x16x32_bf16 v[60:63], v[156:159], v[172:175], v[60:63]
	v_mfma_f32_16x16x32_bf16 v[56:59], v[164:167], v[172:175], v[56:59]
	v_mfma_f32_16x16x32_bf16 v[56:59], v[160:163], v[168:171], v[56:59]
	v_mfma_f32_16x16x32_bf16 v[40:43], v[160:163], v[176:179], v[40:43]
	v_mfma_f32_16x16x32_bf16 v[40:43], v[164:167], v[180:183], v[40:43]
	v_mfma_f32_16x16x32_bf16 v[44:47], v[156:159], v[180:183], v[44:47]
	v_mfma_f32_16x16x32_bf16 v[44:47], v[152:155], v[176:179], v[44:47]
	v_mfma_f32_16x16x32_bf16 v[28:31], v[152:155], v[184:187], v[28:31]
	v_mfma_f32_16x16x32_bf16 v[28:31], v[156:159], v[188:191], v[28:31]
	v_mfma_f32_16x16x32_bf16 v[24:27], v[164:167], v[188:191], v[24:27]
	v_mfma_f32_16x16x32_bf16 v[24:27], v[160:163], v[184:187], v[24:27]
	v_mfma_f32_16x16x32_bf16 v[8:11], v[160:163], v[192:195], v[8:11]
	v_mfma_f32_16x16x32_bf16 v[8:11], v[164:167], v[196:199], v[8:11]
	v_mfma_f32_16x16x32_bf16 v[12:15], v[156:159], v[196:199], v[12:15]
	v_mfma_f32_16x16x32_bf16 v[12:15], v[152:155], v[192:195], v[12:15]
	s_barrier
	s_add_u32 s72, s42, 0x40000
	s_addc_u32 s73, s43, 0
	s_add_i32 s71, s64, s51
	s_mov_b32 m0, s71
	s_nop 0
	global_load_lds_dwordx4 v130, s[72:73]
	s_add_i32 m0, s71, 0x2000
	s_nop 0
	global_load_lds_dwordx4 v134, s[72:73]
	s_waitcnt vmcnt(6)
	s_barrier
	v_mfma_f32_16x16x32_bf16 v[52:55], v[200:203], v[168:171], v[52:55]
	v_mfma_f32_16x16x32_bf16 v[52:55], v[204:207], v[172:175], v[52:55]
	v_mfma_f32_16x16x32_bf16 v[48:51], v[214:217], v[172:175], v[48:51]
	v_mfma_f32_16x16x32_bf16 v[48:51], v[210:213], v[168:171], v[48:51]
	v_mfma_f32_16x16x32_bf16 v[32:35], v[210:213], v[176:179], v[32:35]
	v_mfma_f32_16x16x32_bf16 v[32:35], v[214:217], v[180:183], v[32:35]
	v_mfma_f32_16x16x32_bf16 v[36:39], v[204:207], v[180:183], v[36:39]
	v_mfma_f32_16x16x32_bf16 v[36:39], v[200:203], v[176:179], v[36:39]
	v_mfma_f32_16x16x32_bf16 v[20:23], v[200:203], v[184:187], v[20:23]
	v_mfma_f32_16x16x32_bf16 v[20:23], v[204:207], v[188:191], v[20:23]
	v_mfma_f32_16x16x32_bf16 v[16:19], v[214:217], v[188:191], v[16:19]
	v_mfma_f32_16x16x32_bf16 v[16:19], v[210:213], v[184:187], v[16:19]
	v_mfma_f32_16x16x32_bf16 v[0:3], v[210:213], v[192:195], v[0:3]
	v_mfma_f32_16x16x32_bf16 v[0:3], v[214:217], v[196:199], v[0:3]
	v_mfma_f32_16x16x32_bf16 v[4:7], v[204:207], v[196:199], v[4:7]
	v_mfma_f32_16x16x32_bf16 v[4:7], v[200:203], v[192:195], v[4:7]
	s_barrier
	s_add_i32 s71, 0, 0x18000
	ds_read_b128 v[152:155], v252
	ds_read_b128 v[156:159], v252 offset:1024
	ds_read_b128 v[160:163], v252 offset:2048
	ds_read_b128 v[164:167], v252 offset:3072
	s_add_u32 s44, s44, 0x40000
	s_addc_u32 s45, s45, 0
	s_mov_b32 m0, s57
	ds_read_b128 v[168:171], v150 offset:32768
	ds_read_b128 v[172:175], v150 offset:33792
	ds_read_b128 v[176:179], v150 offset:34816
	ds_read_b128 v[180:183], v150 offset:35840
	ds_read_b128 v[184:187], v150 offset:36864
	ds_read_b128 v[188:191], v150 offset:37888
	ds_read_b128 v[192:195], v150 offset:38912
	ds_read_b128 v[196:199], v150 offset:39936
	global_load_lds_dwordx4 v128, s[44:45]
	s_mov_b32 m0, s58
	s_nop 0
	global_load_lds_dwordx4 v132, s[44:45]
	s_waitcnt lgkmcnt(8)
	s_barrier
	s_waitcnt lgkmcnt(0)
	v_mfma_f32_16x16x32_bf16 v[124:127], v[152:155], v[168:171], v[124:127]
	v_mfma_f32_16x16x32_bf16 v[124:127], v[156:159], v[172:175], v[124:127]
	v_mfma_f32_16x16x32_bf16 v[120:123], v[164:167], v[172:175], v[120:123]
	v_mfma_f32_16x16x32_bf16 v[120:123], v[160:163], v[168:171], v[120:123]
	v_mfma_f32_16x16x32_bf16 v[104:107], v[160:163], v[176:179], v[104:107]
	v_mfma_f32_16x16x32_bf16 v[104:107], v[164:167], v[180:183], v[104:107]
	v_mfma_f32_16x16x32_bf16 v[108:111], v[156:159], v[180:183], v[108:111]
	v_mfma_f32_16x16x32_bf16 v[108:111], v[152:155], v[176:179], v[108:111]
	v_mfma_f32_16x16x32_bf16 v[92:95], v[152:155], v[184:187], v[92:95]
	v_mfma_f32_16x16x32_bf16 v[92:95], v[156:159], v[188:191], v[92:95]
	v_mfma_f32_16x16x32_bf16 v[88:91], v[164:167], v[188:191], v[88:91]
	v_mfma_f32_16x16x32_bf16 v[88:91], v[160:163], v[184:187], v[88:91]
	v_mfma_f32_16x16x32_bf16 v[72:75], v[160:163], v[192:195], v[72:75]
	v_mfma_f32_16x16x32_bf16 v[72:75], v[164:167], v[196:199], v[72:75]
	v_mfma_f32_16x16x32_bf16 v[76:79], v[156:159], v[196:199], v[76:79]
	v_mfma_f32_16x16x32_bf16 v[76:79], v[152:155], v[192:195], v[76:79]
	s_barrier
	s_add_i32 s44, 0, 0x1c000
	s_add_i32 s45, s71, s51
	s_mov_b32 m0, s45
	ds_read_b128 v[200:203], v253
	ds_read_b128 v[204:207], v253 offset:1024
	ds_read_b128 v[210:213], v253 offset:2048
	ds_read_b128 v[214:217], v253 offset:3072
	global_load_lds_dwordx4 v130, s[76:77]
	s_add_i32 m0, s45, 0x2000
	s_nop 0
	global_load_lds_dwordx4 v134, s[76:77]
	s_barrier
	s_waitcnt lgkmcnt(0)
	v_mfma_f32_16x16x32_bf16 v[116:119], v[200:203], v[168:171], v[116:119]
	v_mfma_f32_16x16x32_bf16 v[116:119], v[204:207], v[172:175], v[116:119]
	v_mfma_f32_16x16x32_bf16 v[112:115], v[214:217], v[172:175], v[112:115]
	v_mfma_f32_16x16x32_bf16 v[112:115], v[210:213], v[168:171], v[112:115]
	v_mfma_f32_16x16x32_bf16 v[96:99], v[210:213], v[176:179], v[96:99]
	v_mfma_f32_16x16x32_bf16 v[96:99], v[214:217], v[180:183], v[96:99]
	v_mfma_f32_16x16x32_bf16 v[100:103], v[204:207], v[180:183], v[100:103]
	v_mfma_f32_16x16x32_bf16 v[100:103], v[200:203], v[176:179], v[100:103]
	v_mfma_f32_16x16x32_bf16 v[84:87], v[200:203], v[184:187], v[84:87]
	v_mfma_f32_16x16x32_bf16 v[84:87], v[204:207], v[188:191], v[84:87]
	v_mfma_f32_16x16x32_bf16 v[80:83], v[214:217], v[188:191], v[80:83]
	v_mfma_f32_16x16x32_bf16 v[80:83], v[210:213], v[184:187], v[80:83]
	v_mfma_f32_16x16x32_bf16 v[64:67], v[210:213], v[192:195], v[64:67]
	v_mfma_f32_16x16x32_bf16 v[64:67], v[214:217], v[196:199], v[64:67]
	v_mfma_f32_16x16x32_bf16 v[68:71], v[204:207], v[196:199], v[68:71]
	v_mfma_f32_16x16x32_bf16 v[68:71], v[200:203], v[192:195], v[68:71]
	s_barrier
; __device__ __forceinline__ unsigned cvt_pk_bf16(float lo, float hi) { unsigned r; asm volatile("v_cvt_pk_bf16_f32 %0, %1, %2" : "=v"(r) : "v"(lo), "v"(hi)); return r; }
; #define PG8_STAGE(bufoff, gbase, voff) do { _Pragma("unroll") for (int _i = 0; _i < 2; ++_i) \
;         __builtin_amdgcn_global_load_lds((const unsigned*)((const char*)(gbase) + (voff)[_i]), (LAS unsigned*)(lds + (bufoff) + ldsw + _i * 8192), 16, 0, 0); } while (0)
; #define PG8_LDA(dst, b, h) do { _Pragma("unroll") for (int m = 0; m < 4; ++m) _Pragma("unroll") for (int k = 0; k < 2; ++k) dst[m][k] = *(const LAS bf16x8*)(lds + PG8_SA(b, h) + aoff + m * 2048 + k * 1024); } while (0)
; #define PG8_WAIT_V(n) asm volatile("s_waitcnt vmcnt(" #n ")" ::: "memory")
; #define PG8_WAIT_L(n) asm volatile("s_waitcnt lgkmcnt(" #n ")" ::: "memory")
; #define PG8_BAR __builtin_amdgcn_s_barrier()
; #define PG8_SCHED __builtin_amdgcn_sched_barrier(0)
; template <class Epi, class Ptrs>
; __device__ __forceinline__ void gemm_phase(LAS unsigned char* lds, const int K, const StaticOrder& S, const Ptrs& P, const Epi& E) {
;     ...
;             PG8_LDA(At, 1, 1); PG8_STAGE(PG8_SA(1, 0), a3, voffA);
;             PG8_BAR; PG8_WAIT_L(0); PG8_MMA(1, 0, At, B0); PG8_BAR; PG8_SCHED;
;             PG8_STAGE(PG8_SB(1, 1), b3 + hstep, voffB);
;             PG8_WAIT_V(6); PG8_BAR; PG8_MMA(1, 1, At, B1); PG8_BAR;
;     __device__ __forceinline__ void operator()(const f32x4 (&acc)[2][2][4][2], const Unit& u, int ui, int wr, int wc, int fr, int fq) const {
;         const int row0 = u.pm * 256 + wr * 64 + fr, col0 = u.pn * 256 + wc * 32 + 8 * fq;
; #pragma unroll
;         for (int ai = 0; ai < 2; ++ai)
; #pragma unroll
;             for (int m = 0; m < 4; ++m) { bf16_t* rowp = hid + (size_t)(row0 + ai * 128 + m * 16) * DFF + col0;
; #pragma unroll
;                 for (int bj = 0; bj < 2; ++bj) { f32x4 v0 = acc[ai][bj][m][0], v1 = acc[ai][bj][m][1];
; #pragma unroll
;                     for (int j = 0; j < 4; ++j) { const float a = fmaxf(v0[j], 0.f), b = fmaxf(v1[j], 0.f); v0[j] = a * a; v1[j] = b * b; }
;                     u32x4 w; w.x = cvt_pk_bf16(v0[0], v0[1]); w.y = cvt_pk_bf16(v0[2], v0[3]); w.z = cvt_pk_bf16(v1[0], v1[1]); w.w = cvt_pk_bf16(v1[2], v1[3]);
;                     *(u32x4*)(rowp + bj * 128) = w; } }
	s_mov_b32 m0, s61
	ds_read_b128 v[168:171], v150 offset:49152
	ds_read_b128 v[172:175], v150 offset:50176
	ds_read_b128 v[176:179], v150 offset:51200
	ds_read_b128 v[180:183], v150 offset:52224
	ds_read_b128 v[184:187], v150 offset:53248
	ds_read_b128 v[188:191], v150 offset:54272
	ds_read_b128 v[192:195], v150 offset:55296
	ds_read_b128 v[196:199], v150 offset:56320
	global_load_lds_dwordx4 v128, s[78:79]
	s_mov_b32 m0, s62
	s_nop 0
	global_load_lds_dwordx4 v132, s[78:79]
	s_barrier
	s_waitcnt lgkmcnt(0)
	v_mfma_f32_16x16x32_bf16 v[60:63], v[152:155], v[168:171], v[60:63]
	v_mfma_f32_16x16x32_bf16 v[60:63], v[156:159], v[172:175], v[60:63]
	v_mfma_f32_16x16x32_bf16 v[56:59], v[164:167], v[172:175], v[56:59]
	v_mfma_f32_16x16x32_bf16 v[56:59], v[160:163], v[168:171], v[56:59]
	v_mfma_f32_16x16x32_bf16 v[40:43], v[160:163], v[176:179], v[40:43]
	v_mfma_f32_16x16x32_bf16 v[40:43], v[164:167], v[180:183], v[40:43]
	v_mfma_f32_16x16x32_bf16 v[44:47], v[156:159], v[180:183], v[44:47]
	v_mfma_f32_16x16x32_bf16 v[44:47], v[152:155], v[176:179], v[44:47]
	v_mfma_f32_16x16x32_bf16 v[28:31], v[152:155], v[184:187], v[28:31]
	v_mfma_f32_16x16x32_bf16 v[28:31], v[156:159], v[188:191], v[28:31]
	v_mfma_f32_16x16x32_bf16 v[24:27], v[164:167], v[188:191], v[24:27]
	v_mfma_f32_16x16x32_bf16 v[24:27], v[160:163], v[184:187], v[24:27]
	v_mfma_f32_16x16x32_bf16 v[8:11], v[160:163], v[192:195], v[8:11]
	v_mfma_f32_16x16x32_bf16 v[8:11], v[164:167], v[196:199], v[8:11]
	v_mfma_f32_16x16x32_bf16 v[12:15], v[156:159], v[196:199], v[12:15]
	v_mfma_f32_16x16x32_bf16 v[12:15], v[152:155], v[192:195], v[12:15]
	s_barrier
	s_add_u32 s42, s42, 0x40080
	s_addc_u32 s43, s43, 0
	s_add_i32 s44, s44, s51
	s_mov_b32 m0, s44
	s_nop 0
	global_load_lds_dwordx4 v130, s[42:43]
	s_add_i32 m0, s44, 0x2000
	s_nop 0
	global_load_lds_dwordx4 v134, s[42:43]
	s_waitcnt vmcnt(6)
	s_barrier
	v_mfma_f32_16x16x32_bf16 v[52:55], v[200:203], v[168:171], v[52:55]
	v_mfma_f32_16x16x32_bf16 v[52:55], v[204:207], v[172:175], v[52:55]
	v_mfma_f32_16x16x32_bf16 v[48:51], v[214:217], v[172:175], v[48:51]
	v_mfma_f32_16x16x32_bf16 v[48:51], v[210:213], v[168:171], v[48:51]
	v_mfma_f32_16x16x32_bf16 v[32:35], v[210:213], v[176:179], v[32:35]
	v_mfma_f32_16x16x32_bf16 v[32:35], v[214:217], v[180:183], v[32:35]
	v_mfma_f32_16x16x32_bf16 v[36:39], v[204:207], v[180:183], v[36:39]
	v_mfma_f32_16x16x32_bf16 v[36:39], v[200:203], v[176:179], v[36:39]
	v_mfma_f32_16x16x32_bf16 v[20:23], v[200:203], v[184:187], v[20:23]
	v_mfma_f32_16x16x32_bf16 v[20:23], v[204:207], v[188:191], v[20:23]
	v_mfma_f32_16x16x32_bf16 v[16:19], v[214:217], v[188:191], v[16:19]
	v_mfma_f32_16x16x32_bf16 v[16:19], v[210:213], v[184:187], v[16:19]
	v_mfma_f32_16x16x32_bf16 v[0:3], v[210:213], v[192:195], v[0:3]
	v_mfma_f32_16x16x32_bf16 v[0:3], v[214:217], v[196:199], v[0:3]
	v_mfma_f32_16x16x32_bf16 v[4:7], v[204:207], v[196:199], v[4:7]
	v_mfma_f32_16x16x32_bf16 v[4:7], v[200:203], v[192:195], v[4:7]
	s_barrier
	s_add_i32 s70, s70, 2
	s_add_u32 s40, s40, 0x100
	s_addc_u32 s41, s41, 0
	s_add_u32 s23, s23, 0x100
	s_addc_u32 s25, s25, 0
	s_cmp_gt_u32 s70, 13
	s_cbranch_scc0 .LBB0_433
	v_lshl_add_u32 v152, s38, 8, v146
	v_max_f32_e32 v120, 0, v120
	v_ashrrev_i32_e32 v153, 31, v152
	v_max_f32_e32 v121, 0, v121
	v_max_f32_e32 v122, 0, v122
	v_lshl_or_b32 v144, s69, 8, v148
	v_lshlrev_b64 v[154:155], 13, v[152:153]
	v_mul_f32_e32 v153, v120, v120
	v_max_f32_e32 v120, 0, v125
	v_ashrrev_i32_e32 v145, 31, v144
	v_max_f32_e32 v124, 0, v124
	v_mul_f32_e32 v125, v121, v121
	v_max_f32_e32 v121, 0, v126
	v_mul_f32_e32 v126, v122, v122
	v_max_f32_e32 v122, 0, v127
	v_max_f32_e32 v123, 0, v123
	v_lshl_add_u64 v[154:155], s[10:11], 0, v[154:155]
	v_lshlrev_b64 v[156:157], 1, v[144:145]
	v_mul_f32_e32 v120, v120, v120
	v_max_f32_e32 v112, 0, v112
	v_lshl_add_u64 v[144:145], v[154:155], 0, v[156:157]
	v_mul_f32_e32 v124, v124, v124
	v_mul_f32_e32 v121, v121, v121
	v_mul_f32_e32 v122, v122, v122
	v_mul_f32_e32 v123, v123, v123
	v_cvt_pk_bf16_f32 v120, v124, v120
	v_max_f32_e32 v113, 0, v113
	v_max_f32_e32 v114, 0, v114
	v_cvt_pk_bf16_f32 v121, v121, v122
	v_cvt_pk_bf16_f32 v122, v153, v125
	v_cvt_pk_bf16_f32 v123, v126, v123
	global_store_dwordx4 v[144:145], v[120:123], off
	s_nop 1
	v_mul_f32_e32 v120, v112, v112
	v_max_f32_e32 v112, 0, v117
	v_max_f32_e32 v116, 0, v116
	v_mul_f32_e32 v117, v113, v113
	v_max_f32_e32 v113, 0, v118
	v_mul_f32_e32 v118, v114, v114
	v_max_f32_e32 v114, 0, v119
	v_max_f32_e32 v115, 0, v115
	v_mul_f32_e32 v112, v112, v112
	v_mul_f32_e32 v116, v116, v116
	v_mul_f32_e32 v113, v113, v113
	v_mul_f32_e32 v114, v114, v114
	v_mul_f32_e32 v115, v115, v115
	v_cvt_pk_bf16_f32 v112, v116, v112
	v_max_f32_e32 v104, 0, v104
	v_cvt_pk_bf16_f32 v113, v113, v114
	v_cvt_pk_bf16_f32 v114, v120, v117
	v_cvt_pk_bf16_f32 v115, v118, v115
	global_store_dwordx4 v[144:145], v[112:115], off offset:256
	s_nop 0
	v_max_f32_e32 v105, 0, v105
	v_or_b32_e32 v112, 16, v152
	v_max_f32_e32 v106, 0, v106
	v_ashrrev_i32_e32 v113, 31, v112
	v_mul_f32_e32 v114, v104, v104
	v_max_f32_e32 v104, 0, v109
	v_lshlrev_b64 v[112:113], 13, v[112:113]
	v_max_f32_e32 v108, 0, v108
	v_mul_f32_e32 v109, v105, v105
	v_max_f32_e32 v105, 0, v110
	v_mul_f32_e32 v110, v106, v106
	v_max_f32_e32 v106, 0, v111
	v_max_f32_e32 v107, 0, v107
	v_lshl_add_u64 v[112:113], s[10:11], 0, v[112:113]
	v_mul_f32_e32 v104, v104, v104
	v_max_f32_e32 v96, 0, v96
	v_lshl_add_u64 v[112:113], v[112:113], 0, v[156:157]
	v_mul_f32_e32 v108, v108, v108
	v_mul_f32_e32 v105, v105, v105
	v_mul_f32_e32 v106, v106, v106
	v_mul_f32_e32 v107, v107, v107
	v_cvt_pk_bf16_f32 v104, v108, v104
; __device__ __forceinline__ unsigned cvt_pk_bf16(float lo, float hi) { unsigned r; asm volatile("v_cvt_pk_bf16_f32 %0, %1, %2" : "=v"(r) : "v"(lo), "v"(hi)); return r; }
;     __device__ __forceinline__ void operator()(const f32x4 (&acc)[2][2][4][2], const Unit& u, int ui, int wr, int wc, int fr, int fq) const {
;     ...
;             for (int m = 0; m < 4; ++m) { bf16_t* rowp = hid + (size_t)(row0 + ai * 128 + m * 16) * DFF + col0;
; #pragma unroll
;                 for (int bj = 0; bj < 2; ++bj) { f32x4 v0 = acc[ai][bj][m][0], v1 = acc[ai][bj][m][1];
; #pragma unroll
;                     for (int j = 0; j < 4; ++j) { const float a = fmaxf(v0[j], 0.f), b = fmaxf(v1[j], 0.f); v0[j] = a * a; v1[j] = b * b; }
;                     u32x4 w; w.x = cvt_pk_bf16(v0[0], v0[1]); w.y = cvt_pk_bf16(v0[2], v0[3]); w.z = cvt_pk_bf16(v1[0], v1[1]); w.w = cvt_pk_bf16(v1[2], v1[3]);
;                     *(u32x4*)(rowp + bj * 128) = w; } }
	v_max_f32_e32 v97, 0, v97
	v_max_f32_e32 v98, 0, v98
	v_cvt_pk_bf16_f32 v105, v105, v106
	v_cvt_pk_bf16_f32 v106, v114, v109
	v_cvt_pk_bf16_f32 v107, v110, v107
	global_store_dwordx4 v[112:113], v[104:107], off
	s_nop 1
	v_mul_f32_e32 v104, v96, v96
	v_max_f32_e32 v96, 0, v101
	v_max_f32_e32 v100, 0, v100
	v_mul_f32_e32 v101, v97, v97
	v_max_f32_e32 v97, 0, v102
	v_mul_f32_e32 v102, v98, v98
	v_max_f32_e32 v98, 0, v103
	v_max_f32_e32 v99, 0, v99
	v_mul_f32_e32 v96, v96, v96
	v_mul_f32_e32 v100, v100, v100
	v_mul_f32_e32 v97, v97, v97
	v_mul_f32_e32 v98, v98, v98
	v_mul_f32_e32 v99, v99, v99
	v_cvt_pk_bf16_f32 v96, v100, v96
	v_max_f32_e32 v88, 0, v88
	v_cvt_pk_bf16_f32 v97, v97, v98
	v_cvt_pk_bf16_f32 v98, v104, v101
	v_cvt_pk_bf16_f32 v99, v102, v99
	global_store_dwordx4 v[112:113], v[96:99], off offset:256
	s_nop 0
	v_max_f32_e32 v89, 0, v89
	v_or_b32_e32 v96, 32, v152
	v_max_f32_e32 v90, 0, v90
	v_ashrrev_i32_e32 v97, 31, v96
	v_mul_f32_e32 v98, v88, v88
	v_max_f32_e32 v88, 0, v93
	v_lshlrev_b64 v[96:97], 13, v[96:97]
	v_max_f32_e32 v92, 0, v92
	v_mul_f32_e32 v93, v89, v89
	v_max_f32_e32 v89, 0, v94
	v_mul_f32_e32 v94, v90, v90
	v_max_f32_e32 v90, 0, v95
	v_max_f32_e32 v91, 0, v91
	v_lshl_add_u64 v[96:97], s[10:11], 0, v[96:97]
	v_mul_f32_e32 v88, v88, v88
	v_max_f32_e32 v80, 0, v80
	v_lshl_add_u64 v[96:97], v[96:97], 0, v[156:157]
	v_mul_f32_e32 v92, v92, v92
	v_mul_f32_e32 v89, v89, v89
	v_mul_f32_e32 v90, v90, v90
	v_mul_f32_e32 v91, v91, v91
	v_cvt_pk_bf16_f32 v88, v92, v88
	v_max_f32_e32 v81, 0, v81
	v_max_f32_e32 v82, 0, v82
	v_cvt_pk_bf16_f32 v89, v89, v90
	v_cvt_pk_bf16_f32 v90, v98, v93
	v_cvt_pk_bf16_f32 v91, v94, v91
	global_store_dwordx4 v[96:97], v[88:91], off
	s_nop 1
	v_mul_f32_e32 v88, v80, v80
	v_max_f32_e32 v80, 0, v85
	v_max_f32_e32 v84, 0, v84
	v_mul_f32_e32 v85, v81, v81
	v_max_f32_e32 v81, 0, v86
	v_mul_f32_e32 v86, v82, v82
	v_max_f32_e32 v82, 0, v87
	v_max_f32_e32 v83, 0, v83
	v_mul_f32_e32 v80, v80, v80
	v_mul_f32_e32 v84, v84, v84
	v_mul_f32_e32 v81, v81, v81
	v_mul_f32_e32 v82, v82, v82
	v_mul_f32_e32 v83, v83, v83
	v_cvt_pk_bf16_f32 v80, v84, v80
	v_max_f32_e32 v72, 0, v72
	v_cvt_pk_bf16_f32 v81, v81, v82
	v_cvt_pk_bf16_f32 v82, v88, v85
	v_cvt_pk_bf16_f32 v83, v86, v83
	global_store_dwordx4 v[96:97], v[80:83], off offset:256
	s_nop 0
	v_max_f32_e32 v73, 0, v73
	v_or_b32_e32 v80, 48, v152
	v_max_f32_e32 v74, 0, v74
	v_ashrrev_i32_e32 v81, 31, v80
	v_mul_f32_e32 v82, v72, v72
	v_max_f32_e32 v72, 0, v77
	v_lshlrev_b64 v[80:81], 13, v[80:81]
	v_max_f32_e32 v76, 0, v76
	v_mul_f32_e32 v77, v73, v73
	v_max_f32_e32 v73, 0, v78
	v_mul_f32_e32 v78, v74, v74
	v_max_f32_e32 v74, 0, v79
	v_max_f32_e32 v75, 0, v75
	v_lshl_add_u64 v[80:81], s[10:11], 0, v[80:81]
	v_mul_f32_e32 v72, v72, v72
	v_max_f32_e32 v64, 0, v64
	v_max_f32_e32 v65, 0, v65
	v_max_f32_e32 v66, 0, v66
	v_lshl_add_u64 v[80:81], v[80:81], 0, v[156:157]
	v_mul_f32_e32 v76, v76, v76
	v_mul_f32_e32 v73, v73, v73
	v_mul_f32_e32 v74, v74, v74
	v_mul_f32_e32 v75, v75, v75
	v_cvt_pk_bf16_f32 v72, v76, v72
	v_cvt_pk_bf16_f32 v73, v73, v74
	v_cvt_pk_bf16_f32 v74, v82, v77
	v_cvt_pk_bf16_f32 v75, v78, v75
	global_store_dwordx4 v[80:81], v[72:75], off
	v_max_f32_e32 v68, 0, v68
	v_max_f32_e32 v67, 0, v67
	v_mul_f32_e32 v72, v64, v64
	v_max_f32_e32 v64, 0, v69
	v_mul_f32_e32 v69, v65, v65
	v_max_f32_e32 v65, 0, v70
	v_mul_f32_e32 v70, v66, v66
	v_max_f32_e32 v66, 0, v71
	v_mul_f32_e32 v64, v64, v64
	v_mul_f32_e32 v65, v65, v65
	v_mul_f32_e32 v66, v66, v66
	v_max_f32_e32 v56, 0, v56
	v_mul_f32_e32 v68, v68, v68
	v_mul_f32_e32 v67, v67, v67
	v_cvt_pk_bf16_f32 v64, v68, v64
	v_cvt_pk_bf16_f32 v65, v65, v66
	v_cvt_pk_bf16_f32 v66, v72, v69
	v_max_f32_e32 v57, 0, v57
	v_max_f32_e32 v58, 0, v58
	v_cvt_pk_bf16_f32 v67, v70, v67
	global_store_dwordx4 v[80:81], v[64:67], off offset:256
	s_nop 0
	v_max_f32_e32 v60, 0, v60
	v_mul_f32_e32 v66, v56, v56
	v_max_f32_e32 v56, 0, v61
	v_mul_f32_e32 v61, v57, v57
	v_max_f32_e32 v57, 0, v62
	v_mul_f32_e32 v62, v58, v58
	v_max_f32_e32 v58, 0, v63
	v_mul_f32_e32 v60, v60, v60
	v_mul_f32_e32 v56, v56, v56
	v_max_f32_e32 v59, 0, v59
	v_mul_f32_e32 v57, v57, v57
	v_mul_f32_e32 v58, v58, v58
	v_cvt_pk_bf16_f32 v56, v60, v56
	v_add_co_u32_e32 v60, vcc, s65, v144
	v_max_f32_e32 v48, 0, v48
	v_max_f32_e32 v49, 0, v49
	v_max_f32_e32 v50, 0, v50
	v_mul_f32_e32 v59, v59, v59
	v_cvt_pk_bf16_f32 v57, v57, v58
	v_cvt_pk_bf16_f32 v58, v66, v61
	v_addc_co_u32_e32 v61, vcc, 0, v145, vcc
	v_cvt_pk_bf16_f32 v59, v62, v59
	global_store_dwordx4 v[60:61], v[56:59], off
	v_max_f32_e32 v52, 0, v52
	v_max_f32_e32 v51, 0, v51
	v_mul_f32_e32 v56, v48, v48
	v_max_f32_e32 v48, 0, v53
	v_mul_f32_e32 v53, v49, v49
	v_max_f32_e32 v49, 0, v54
	v_mul_f32_e32 v54, v50, v50
	v_max_f32_e32 v50, 0, v55
; __device__ __forceinline__ unsigned cvt_pk_bf16(float lo, float hi) { unsigned r; asm volatile("v_cvt_pk_bf16_f32 %0, %1, %2" : "=v"(r) : "v"(lo), "v"(hi)); return r; }
; #define PG8_WAIT_V(n) asm volatile("s_waitcnt vmcnt(" #n ")" ::: "memory")
; #define PG8_BAR __builtin_amdgcn_s_barrier()
; template <class Epi, class Ptrs>
; __device__ __forceinline__ void gemm_phase(LAS unsigned char* lds, const int K, const StaticOrder& S, const Ptrs& P, const Epi& E) {
;     ...
;         cur = nxt; cA = nA; cB = nB; ++ui;
;     }
;     PG8_WAIT_V(0);
;     if (wr == 0) PG8_BAR;
;     PG8_BAR;
;     __device__ __forceinline__ void operator()(const f32x4 (&acc)[2][2][4][2], const Unit& u, int ui, int wr, int wc, int fr, int fq) const {
;     ...
;             for (int m = 0; m < 4; ++m) { bf16_t* rowp = hid + (size_t)(row0 + ai * 128 + m * 16) * DFF + col0;
; #pragma unroll
;                 for (int bj = 0; bj < 2; ++bj) { f32x4 v0 = acc[ai][bj][m][0], v1 = acc[ai][bj][m][1];
; #pragma unroll
;                     for (int j = 0; j < 4; ++j) { const float a = fmaxf(v0[j], 0.f), b = fmaxf(v1[j], 0.f); v0[j] = a * a; v1[j] = b * b; }
;                     u32x4 w; w.x = cvt_pk_bf16(v0[0], v0[1]); w.y = cvt_pk_bf16(v0[2], v0[3]); w.z = cvt_pk_bf16(v1[0], v1[1]); w.w = cvt_pk_bf16(v1[2], v1[3]);
;                     *(u32x4*)(rowp + bj * 128) = w; } }
	v_mul_f32_e32 v48, v48, v48
	v_mul_f32_e32 v49, v49, v49
	v_mul_f32_e32 v50, v50, v50
	v_max_f32_e32 v40, 0, v40
	v_lshl_add_u64 v[64:65], v[144:145], 0, s[14:15]
	v_mul_f32_e32 v52, v52, v52
	v_mul_f32_e32 v51, v51, v51
	v_cvt_pk_bf16_f32 v48, v52, v48
	v_cvt_pk_bf16_f32 v49, v49, v50
	v_cvt_pk_bf16_f32 v50, v56, v53
	v_max_f32_e32 v41, 0, v41
	v_max_f32_e32 v42, 0, v42
	v_cvt_pk_bf16_f32 v51, v54, v51
	global_store_dwordx4 v[64:65], v[48:51], off offset:256
	s_nop 0
	v_max_f32_e32 v44, 0, v44
	v_mul_f32_e32 v50, v40, v40
	v_max_f32_e32 v40, 0, v45
	v_mul_f32_e32 v45, v41, v41
	v_max_f32_e32 v41, 0, v46
	v_mul_f32_e32 v46, v42, v42
	v_max_f32_e32 v42, 0, v47
	v_mul_f32_e32 v44, v44, v44
	v_mul_f32_e32 v40, v40, v40
	v_max_f32_e32 v43, 0, v43
	v_mul_f32_e32 v41, v41, v41
	v_mul_f32_e32 v42, v42, v42
	v_cvt_pk_bf16_f32 v40, v44, v40
	v_add_co_u32_e32 v44, vcc, s66, v144
	v_max_f32_e32 v32, 0, v32
	v_max_f32_e32 v33, 0, v33
	v_max_f32_e32 v34, 0, v34
	v_mul_f32_e32 v43, v43, v43
	v_cvt_pk_bf16_f32 v41, v41, v42
	v_cvt_pk_bf16_f32 v42, v50, v45
	v_addc_co_u32_e32 v45, vcc, 0, v145, vcc
	v_cvt_pk_bf16_f32 v43, v46, v43
	global_store_dwordx4 v[44:45], v[40:43], off
	v_max_f32_e32 v36, 0, v36
	v_max_f32_e32 v35, 0, v35
	v_mul_f32_e32 v40, v32, v32
	v_max_f32_e32 v32, 0, v37
	v_mul_f32_e32 v37, v33, v33
	v_max_f32_e32 v33, 0, v38
	v_mul_f32_e32 v38, v34, v34
	v_max_f32_e32 v34, 0, v39
	v_mul_f32_e32 v32, v32, v32
	v_mul_f32_e32 v33, v33, v33
	v_mul_f32_e32 v34, v34, v34
	v_max_f32_e32 v24, 0, v24
	v_lshl_add_u64 v[48:49], v[144:145], 0, s[16:17]
	v_mul_f32_e32 v36, v36, v36
	v_mul_f32_e32 v35, v35, v35
	v_cvt_pk_bf16_f32 v32, v36, v32
	v_cvt_pk_bf16_f32 v33, v33, v34
	v_cvt_pk_bf16_f32 v34, v40, v37
	v_max_f32_e32 v25, 0, v25
	v_max_f32_e32 v26, 0, v26
	v_cvt_pk_bf16_f32 v35, v38, v35
	global_store_dwordx4 v[48:49], v[32:35], off offset:256
	s_nop 0
	v_max_f32_e32 v28, 0, v28
	v_mul_f32_e32 v34, v24, v24
	v_max_f32_e32 v24, 0, v29
	v_mul_f32_e32 v29, v25, v25
	v_max_f32_e32 v25, 0, v30
	v_mul_f32_e32 v30, v26, v26
	v_max_f32_e32 v26, 0, v31
	v_mul_f32_e32 v28, v28, v28
	v_mul_f32_e32 v24, v24, v24
	v_max_f32_e32 v27, 0, v27
	v_mul_f32_e32 v25, v25, v25
	v_mul_f32_e32 v26, v26, v26
	v_cvt_pk_bf16_f32 v24, v28, v24
	v_add_co_u32_e32 v28, vcc, s67, v144
	v_max_f32_e32 v16, 0, v16
	v_max_f32_e32 v17, 0, v17
	v_max_f32_e32 v18, 0, v18
	v_mul_f32_e32 v27, v27, v27
	v_cvt_pk_bf16_f32 v25, v25, v26
	v_cvt_pk_bf16_f32 v26, v34, v29
	v_addc_co_u32_e32 v29, vcc, 0, v145, vcc
	v_cvt_pk_bf16_f32 v27, v30, v27
	global_store_dwordx4 v[28:29], v[24:27], off
	v_max_f32_e32 v20, 0, v20
	v_max_f32_e32 v19, 0, v19
	v_mul_f32_e32 v24, v16, v16
	v_max_f32_e32 v16, 0, v21
	v_mul_f32_e32 v21, v17, v17
	v_max_f32_e32 v17, 0, v22
	v_mul_f32_e32 v22, v18, v18
	v_max_f32_e32 v18, 0, v23
	v_mul_f32_e32 v16, v16, v16
	v_mul_f32_e32 v17, v17, v17
	v_mul_f32_e32 v18, v18, v18
	v_max_f32_e32 v8, 0, v8
	v_lshl_add_u64 v[32:33], v[144:145], 0, s[18:19]
	v_mul_f32_e32 v20, v20, v20
	v_mul_f32_e32 v19, v19, v19
	v_cvt_pk_bf16_f32 v16, v20, v16
	v_cvt_pk_bf16_f32 v17, v17, v18
	v_cvt_pk_bf16_f32 v18, v24, v21
	v_max_f32_e32 v9, 0, v9
	v_max_f32_e32 v10, 0, v10
	v_cvt_pk_bf16_f32 v19, v22, v19
	global_store_dwordx4 v[32:33], v[16:19], off offset:256
	s_nop 0
	v_max_f32_e32 v12, 0, v12
	v_mul_f32_e32 v18, v8, v8
	v_max_f32_e32 v8, 0, v13
	v_mul_f32_e32 v13, v9, v9
	v_max_f32_e32 v9, 0, v14
	v_mul_f32_e32 v14, v10, v10
	v_max_f32_e32 v10, 0, v15
	v_mul_f32_e32 v12, v12, v12
	v_mul_f32_e32 v8, v8, v8
	v_max_f32_e32 v11, 0, v11
	v_mul_f32_e32 v9, v9, v9
	v_mul_f32_e32 v10, v10, v10
	v_cvt_pk_bf16_f32 v8, v12, v8
	v_add_co_u32_e32 v12, vcc, s68, v144
	v_max_f32_e32 v0, 0, v0
	v_max_f32_e32 v1, 0, v1
	v_max_f32_e32 v2, 0, v2
	v_mul_f32_e32 v11, v11, v11
	v_cvt_pk_bf16_f32 v9, v9, v10
	v_cvt_pk_bf16_f32 v10, v18, v13
	v_addc_co_u32_e32 v13, vcc, 0, v145, vcc
	v_cvt_pk_bf16_f32 v11, v14, v11
	global_store_dwordx4 v[12:13], v[8:11], off
	v_max_f32_e32 v3, 0, v3
	v_max_f32_e32 v4, 0, v4
	v_mul_f32_e32 v8, v0, v0
	v_max_f32_e32 v0, 0, v5
	v_mul_f32_e32 v5, v1, v1
	v_max_f32_e32 v1, 0, v6
	v_mul_f32_e32 v6, v2, v2
	v_max_f32_e32 v2, 0, v7
	v_lshl_add_u64 v[16:17], v[144:145], 0, s[20:21]
	v_mul_f32_e32 v0, v0, v0
	v_mul_f32_e32 v1, v1, v1
	v_mul_f32_e32 v2, v2, v2
	v_mul_f32_e32 v3, v3, v3
	s_and_b64 vcc, exec, s[4:5]
	s_mov_b32 s69, s22
	s_mov_b32 s38, s24
	s_mov_b64 s[40:41], s[0:1]
	s_mov_b64 s[42:43], s[36:37]
	v_mul_f32_e32 v4, v4, v4
	v_cvt_pk_bf16_f32 v0, v4, v0
	v_cvt_pk_bf16_f32 v1, v1, v2
	v_cvt_pk_bf16_f32 v2, v8, v5
	v_cvt_pk_bf16_f32 v3, v6, v3
	global_store_dwordx4 v[16:17], v[0:3], off offset:256
	s_cbranch_vccz .LBB0_428
	s_waitcnt vmcnt(0)
	s_setprio 0
	s_cmpk_gt_u32 s46, 0xff
	s_cbranch_scc1 .LBB0_437
	s_barrier

; __device__ __forceinline__ unsigned xb_ld(unsigned* p)              { return __hip_atomic_load(p, __ATOMIC_RELAXED, __HIP_MEMORY_SCOPE_AGENT); }
; __device__ __forceinline__ void xcd_barrier_complete(unsigned* bar, unsigned x, unsigned& nloc, unsigned& nx) {
;     const unsigned G = gridDim.x * gridDim.y * gridDim.z;
;     unsigned sum, cnt, mine, sp = 0u;
;     for (;;) {
;         sum = 0u; cnt = 0u; mine = 0u;
; #pragma unroll
;         for (unsigned j = 0; j < 16; ++j) { const unsigned c = xb_ld(&bar[XB_XCNT(j)]); sum += c; cnt += (c > 0u) ? 1u : 0u; mine = (j == x) ? c : mine; }
; __device__ __forceinline__ void xcd_barrier(const XcdBarrier& b) {
;     asm volatile("s_waitcnt vmcnt(0)" ::: "memory");
;     __syncthreads();
;     if (threadIdx.x == 0) {
;         unsigned* bar = b.bar;
;         __builtin_amdgcn_s_waitcnt(0);
;         unsigned nloc = b.st[0], nx = b.st[1];
;         if (nloc == 0u) { xcd_barrier_complete(bar, b.x, nloc, nx); b.st[0] = nloc; b.st[1] = nx; }
.LBB0_438:
	s_nop 0
	s_nop 0
	s_nop 0
	s_nop 0
	s_nop 0
	s_nop 0
	s_nop 0
	s_nop 0
	s_nop 0
	s_nop 0
	s_nop 0
	s_nop 0
	s_nop 0
	s_nop 0
	s_nop 0
	s_nop 0
	s_nop 0
	s_nop 0
	s_nop 0
	s_nop 0
	s_nop 0
	s_nop 0
	s_nop 0
	s_nop 0
	s_nop 0
	s_nop 0
	s_nop 0
	s_nop 0
	s_nop 0
	s_nop 0
	s_nop 0
	s_nop 0
	s_nop 0
	s_nop 0
	s_nop 0
	s_nop 0
	s_nop 0
	s_nop 0
	s_nop 0
	s_cmp_gt_i32 s31, 5
	s_cselect_b64 s[0:1], -1, 0
	s_and_b64 s[4:5], s[6:7], s[0:1]
	s_andn2_b64 vcc, exec, s[4:5]
	s_cbranch_vccnz .LBB0_488
	s_waitcnt vmcnt(0)
	s_waitcnt vmcnt(0) lgkmcnt(0)
	s_barrier
	s_and_saveexec_b64 s[4:5], s[8:9]
	s_cbranch_execz .LBB0_487
	s_add_i32 s6, 0, 0x25ff0
	v_mov_b32_e32 v0, s6
	s_waitcnt vmcnt(0) expcnt(0) lgkmcnt(0)
	ds_read_b32 v2, v0
	s_add_i32 s6, 0, 0x25ff4
	v_mov_b32_e32 v0, s6
	ds_read_b32 v0, v0
	s_waitcnt lgkmcnt(1)
	v_cmp_ne_u32_e32 vcc, 0, v2
	s_cbranch_vccnz .LBB0_455
	s_load_dwordx2 s[10:11], s[52:53], 0x4
	s_add_u32 s6, s28, 0x3e800200
	s_addc_u32 s7, s29, 0
	s_add_u32 s8, s28, 0x3e800400
	s_addc_u32 s9, s29, 0
	s_waitcnt lgkmcnt(0)
	s_mul_i32 s31, s10, s3
	s_add_u32 s10, s28, 0x3e800500
	s_mul_i32 s31, s31, s11
	s_addc_u32 s11, s29, 0
	s_add_u32 s12, s28, 0x3e800600
	s_addc_u32 s13, s29, 0
	s_add_u32 s14, s28, 0x3e800700
	s_addc_u32 s15, s29, 0
	s_add_u32 s16, s28, 0x3e800800
	s_addc_u32 s17, s29, 0
	s_add_u32 s18, s28, 0x3e800900
	s_addc_u32 s19, s29, 0
	s_add_u32 s20, s28, 0x3e800a00
	s_addc_u32 s21, s29, 0
	s_add_u32 s22, s28, 0x3e800b00
	s_addc_u32 s23, s29, 0
	s_add_u32 s24, s28, 0x3e800c00
	s_addc_u32 s25, s29, 0
	s_add_u32 s36, s28, 0x3e800d00
	s_addc_u32 s37, s29, 0
	s_add_u32 s38, s28, 0x3e800e00
	s_addc_u32 s39, s29, 0
	s_add_u32 s40, s28, 0x3e800f00
	s_addc_u32 s41, s29, 0
	s_add_u32 s42, s28, 0x3e801000
	s_addc_u32 s43, s29, 0
	s_add_u32 s44, s28, 0x3e801100
	s_addc_u32 s45, s29, 0
	s_add_u32 s46, s28, 0x3e801200
	s_addc_u32 s47, s29, 0
	s_add_u32 s48, s28, 0x3e801300
	s_addc_u32 s49, s29, 0
	s_mov_b32 s56, 1
	v_mov_b32_e32 v16, 0
	s_branch .LBB0_443

; #define PG8_STAGE(bufoff, gbase, voff) do { _Pragma("unroll") for (int _i = 0; _i < 2; ++_i) \
;         __builtin_amdgcn_global_load_lds((const unsigned*)((const char*)(gbase) + (voff)[_i]), (LAS unsigned*)(lds + (bufoff) + ldsw + _i * 8192), 16, 0, 0); } while (0)
; #define PG8_WAIT_V(n) asm volatile("s_waitcnt vmcnt(" #n ")" ::: "memory")
; #define PG8_BAR __builtin_amdgcn_s_barrier()
; template <class Epi, class Ptrs>
; __device__ __forceinline__ void gemm_phase(LAS unsigned char* lds, const int K, const StaticOrder& S, const Ptrs& P, const Epi& E) {
;     ...
;     for (int i = 0; i < 2; ++i) { int R, C; stage_rc(tid * 16 + i * 8192, R, C); const int Rb = (R & ~31) + perm32(R & 31);
;         voffA[i] = (unsigned)(R * K + C) * 2u; voffB[i] = (unsigned)(Rb * K + C) * 2u; }
;     const size_t kstep = (size_t)(BK * 2);
;     const size_t hstep = (size_t)HALF * K * 2;
;     const unsigned ldsw = (unsigned)wid * 1024u;
;     const int aoff = lds_byte(wr * 64 + fr, fq * 8), boff = lds_byte(wc * 32 + fr, fq * 8);
;     ...
;     PG8_WAIT_V(4); PG8_BAR;
;     PG8_STAGE(PG8_SB(1, 0), cB + kstep, voffB); PG8_STAGE(PG8_SA(1, 0), cA + kstep, voffA); PG8_STAGE(PG8_SB(1, 1), cB + hstep + kstep, voffB);
;     PG8_WAIT_V(6); PG8_BAR;
.LBB0_516:
	s_lshl_b32 s1, s1, 5
	s_and_b32 s1, s1, 0x60
	s_lshl_b32 s10, s0, 13
	s_lshl_b32 s11, s1, 7
	s_add_u32 s6, s28, 0x2000000
	s_mov_b64 s[8:9], 0x80
	s_addc_u32 s7, s29, 0
	s_add_i32 m0, s17, 0x18000
	v_lshl_add_u64 v[6:7], v[6:7], 0, s[8:9]
	s_waitcnt vmcnt(4)
	s_barrier
	global_load_lds_dwordx4 v[6:7], off
	v_lshl_add_u64 v[4:5], v[4:5], 0, s[8:9]
	s_add_i32 m0, s17, 0x1a000
	s_add_i32 s28, s17, 0x8000
	s_add_i32 s29, s17, 0xa000
	global_load_lds_dwordx4 v[4:5], off
	v_lshl_add_u64 v[2:3], v[2:3], 0, s[8:9]
	s_mov_b32 m0, s28
	s_add_u32 s4, s22, 0x100080
	global_load_lds_dwordx4 v[2:3], off
	v_lshl_add_u64 v[0:1], v[0:1], 0, s[8:9]
	s_mov_b32 m0, s29
	s_addc_u32 s5, s23, 0
	global_load_lds_dwordx4 v[0:1], off
	s_add_i32 m0, s17, 0x1c000
	v_lshl_add_u64 v[0:1], s[4:5], 0, v[162:163]
	global_load_lds_dwordx4 v[0:1], off
	v_lshl_add_u64 v[0:1], s[4:5], 0, v[166:167]
	s_add_i32 m0, s17, 0x1e000
	v_lshlrev_b32_e32 v2, 6, v208
	global_load_lds_dwordx4 v[0:1], off
	v_and_b32_e32 v0, 15, v208
	v_lshlrev_b32_e32 v1, 1, v11
	s_movk_i32 s4, 0x3c0
	v_lshl_or_b32 v186, s0, 6, v0
	v_and_or_b32 v2, v2, s4, v1
	v_lshlrev_b32_e32 v3, 2, v208
	v_lshl_or_b32 v0, v0, 6, v1
	v_lshlrev_b32_e32 v1, 2, v186
	s_add_i32 s0, 0, 0x20000
	v_and_b32_e32 v3, 32, v3
	v_and_b32_e32 v4, 32, v1
	v_add_u32_e32 v192, s0, v1
	v_lshlrev_b32_e32 v1, 10, v208
	v_bitop3_b32 v187, s11, v2, v3 bitop3:0xf6
	v_and_b32_e32 v1, 0xe0000, v1
	v_lshlrev_b32_e32 v2, 13, v10
	v_or3_b32 v1, v8, v1, v2
	v_add_u32_e32 v168, v1, v9
	v_lshlrev_b32_e32 v1, 6, v12
	s_waitcnt vmcnt(6)
	v_and_b32_e32 v1, 0x1e0000, v1
	v_bitop3_b32 v0, v0, s10, v4 bitop3:0xde
	v_or3_b32 v1, v8, v1, v2
	s_add_i32 s42, 0, 0x10000
	s_add_i32 s43, 0, 0x14000
	v_or_b32_e32 v188, 16, v186
	v_or_b32_e32 v189, 32, v186
	v_or_b32_e32 v190, 48, v186
	v_or_b32_e32 v191, s1, v11
	v_mov_b32_e32 v169, v163
	v_add_u32_e32 v170, v1, v9
	v_mov_b32_e32 v171, v163
	v_mov_b64_e32 v[172:173], 0x600
	v_mov_b64_e32 v[174:175], 0x5ff
	v_add_u32_e32 v193, s42, v187
	v_add_u32_e32 v194, 0, v0
	s_nop 0
	s_nop 0
	s_nop 0
	s_nop 0
	s_nop 0
	s_nop 0
	s_nop 0
	s_nop 0
	s_nop 0
	s_nop 0
	s_nop 0
	s_nop 0
	s_nop 0
	s_nop 0
	s_nop 0
	s_nop 0
	s_nop 0
	s_nop 0
	s_nop 0
	s_nop 0
	s_nop 0
	s_nop 0
	s_nop 0
	s_nop 0
	v_add_u32_e32 v195, s43, v187
	s_cmpk_lt_u32 s33, 0x100
	s_cbranch_scc1 .Lsprio_3
	s_setprio 1

; #define PG8_STAGE(bufoff, gbase, voff) do { _Pragma("unroll") for (int _i = 0; _i < 2; ++_i) \
;         __builtin_amdgcn_global_load_lds((const unsigned*)((const char*)(gbase) + (voff)[_i]), (LAS unsigned*)(lds + (bufoff) + ldsw + _i * 8192), 16, 0, 0); } while (0)
; #define PG8_LDA(dst, b, h) do { _Pragma("unroll") for (int m = 0; m < 4; ++m) _Pragma("unroll") for (int k = 0; k < 2; ++k) dst[m][k] = *(const LAS bf16x8*)(lds + PG8_SA(b, h) + aoff + m * 2048 + k * 1024); } while (0)
; #define PG8_LDB(dst, b, h) do { _Pragma("unroll") for (int n = 0; n < 2; ++n) _Pragma("unroll") for (int k = 0; k < 2; ++k) dst[n][k] = *(const LAS bf16x8*)(lds + PG8_SB(b, h) + boff + n * 2048 + k * 1024); } while (0)
; #define PG8_MMA(ai, bj, At, Bt) do { __builtin_amdgcn_s_setprio(1); _Pragma("unroll") for (int m = 0; m < 4; ++m) _Pragma("unroll") for (int n = 0; n < 2; ++n) _Pragma("unroll") for (int k = 0; k < 2; ++k) \
;         acc[ai][bj][m][n] = __builtin_amdgcn_mfma_f32_16x16x32_bf16(Bt[n][k], At[m][k], acc[ai][bj][m][n], 0, 0, 0); __builtin_amdgcn_s_setprio(0); } while (0)
; #define PG8_WAIT_V(n) asm volatile("s_waitcnt vmcnt(" #n ")" ::: "memory")
; #define PG8_WAIT_L(n) asm volatile("s_waitcnt lgkmcnt(" #n ")" ::: "memory")
; #define PG8_BAR __builtin_amdgcn_s_barrier()
; #define PG8_SCHED __builtin_amdgcn_sched_barrier(0)
; template <class Epi, class Ptrs>
; __device__ __forceinline__ void gemm_phase(LAS unsigned char* lds, const int K, const StaticOrder& S, const Ptrs& P, const Epi& E) {
;     ...
;             PG8_LDB(B0, 0, 0); PG8_SCHED; PG8_LDA(At, 0, 0); PG8_STAGE(PG8_SA(1, 1), a1 + hstep, voffA);
;             PG8_WAIT_L(8); PG8_BAR; PG8_WAIT_L(0); PG8_MMA(0, 0, At, B0); PG8_BAR; PG8_SCHED;
;             PG8_LDB(B1, 0, 1); PG8_STAGE(PG8_SB(0, 0), b2, voffB);
;             PG8_BAR; PG8_WAIT_L(0); PG8_MMA(0, 1, At, B1); PG8_BAR;
;             PG8_LDA(At, 0, 1); PG8_STAGE(PG8_SA(0, 0), a2, voffA);
;             PG8_BAR; PG8_WAIT_L(0); PG8_MMA(1, 0, At, B0); PG8_BAR; PG8_SCHED;
;             PG8_STAGE(PG8_SB(0, 1), b2 + hstep, voffB);
;             PG8_WAIT_V(6); PG8_BAR; PG8_MMA(1, 1, At, B1); PG8_BAR;
.LBB0_521:
	s_add_u32 s20, s20, 0x100080
	s_addc_u32 s21, s21, 0
	s_add_u32 s11, s22, 0x100
	s_addc_u32 s13, s23, 0
	s_mov_b32 s46, -2
	v_add_u32_e32 v252, 0x18000, v187
	v_add_u32_e32 v253, 0x1c000, v187
	ds_read_b128 v[128:131], v193
	ds_read_b128 v[132:135], v193 offset:1024
	ds_read_b128 v[136:139], v193 offset:2048
	ds_read_b128 v[140:143], v193 offset:3072
	s_add_u32 s22, s20, 0xfff00080
	s_addc_u32 s23, s21, -1
	s_cmp_eq_u32 s46, 60
	s_cselect_b32 s25, s5, s23
	s_cselect_b32 s24, s4, s22
	s_cselect_b32 s23, s15, s13
	s_cselect_b32 s22, s14, s11
	s_add_i32 m0, s17, 0xc000
	ds_read_b128 v[144:147], v194
	ds_read_b128 v[148:151], v194 offset:1024
	ds_read_b128 v[152:155], v194 offset:2048
	ds_read_b128 v[156:159], v194 offset:3072
	ds_read_b128 v[176:179], v194 offset:4096
	ds_read_b128 v[180:183], v194 offset:5120
	ds_read_b128 v[196:199], v194 offset:6144
	ds_read_b128 v[200:203], v194 offset:7168
	global_load_lds_dwordx4 v168, s[20:21]
	s_add_i32 m0, s17, 0xe000
	s_nop 0
	global_load_lds_dwordx4 v170, s[20:21]
	s_waitcnt lgkmcnt(8)
	s_barrier
	s_waitcnt lgkmcnt(0)
	v_mfma_f32_16x16x32_bf16 v[124:127], v[128:131], v[144:147], 0
	v_mfma_f32_16x16x32_bf16 v[124:127], v[132:135], v[148:151], v[124:127]
	v_mfma_f32_16x16x32_bf16 v[120:123], v[140:143], v[148:151], 0
	v_mfma_f32_16x16x32_bf16 v[120:123], v[136:139], v[144:147], v[120:123]
	v_mfma_f32_16x16x32_bf16 v[104:107], v[136:139], v[152:155], 0
	v_mfma_f32_16x16x32_bf16 v[104:107], v[140:143], v[156:159], v[104:107]
	v_mfma_f32_16x16x32_bf16 v[112:115], v[132:135], v[156:159], 0
	v_mfma_f32_16x16x32_bf16 v[112:115], v[128:131], v[152:155], v[112:115]
	v_mfma_f32_16x16x32_bf16 v[92:95], v[128:131], v[176:179], 0
	v_mfma_f32_16x16x32_bf16 v[92:95], v[132:135], v[180:183], v[92:95]
	v_mfma_f32_16x16x32_bf16 v[88:91], v[140:143], v[180:183], 0
	v_mfma_f32_16x16x32_bf16 v[88:91], v[136:139], v[176:179], v[88:91]
	v_mfma_f32_16x16x32_bf16 v[72:75], v[136:139], v[196:199], 0
	v_mfma_f32_16x16x32_bf16 v[72:75], v[140:143], v[200:203], v[72:75]
	v_mfma_f32_16x16x32_bf16 v[76:79], v[132:135], v[200:203], 0
	v_mfma_f32_16x16x32_bf16 v[76:79], v[128:131], v[196:199], v[76:79]
	s_barrier
	s_add_i32 s47, s42, s34
	s_add_u32 s90, s22, 0x80
	s_addc_u32 s91, s23, 0
	s_mov_b32 m0, s47
	ds_read_b128 v[204:207], v195
	ds_read_b128 v[208:211], v195 offset:1024
	ds_read_b128 v[212:215], v195 offset:2048
	ds_read_b128 v[216:219], v195 offset:3072
	global_load_lds_dwordx4 v162, s[22:23]
	s_add_i32 m0, s47, 0x2000
	s_nop 0
	global_load_lds_dwordx4 v166, s[22:23]
	s_barrier
	s_waitcnt lgkmcnt(0)
	v_mfma_f32_16x16x32_bf16 v[116:119], v[204:207], v[144:147], 0
	v_mfma_f32_16x16x32_bf16 v[116:119], v[208:211], v[148:151], v[116:119]
	v_mfma_f32_16x16x32_bf16 v[108:111], v[216:219], v[148:151], 0
	v_mfma_f32_16x16x32_bf16 v[108:111], v[212:215], v[144:147], v[108:111]
	v_mfma_f32_16x16x32_bf16 v[96:99], v[212:215], v[152:155], 0
	v_mfma_f32_16x16x32_bf16 v[96:99], v[216:219], v[156:159], v[96:99]
	v_mfma_f32_16x16x32_bf16 v[100:103], v[208:211], v[156:159], 0
	v_mfma_f32_16x16x32_bf16 v[100:103], v[204:207], v[152:155], v[100:103]
	v_mfma_f32_16x16x32_bf16 v[84:87], v[204:207], v[176:179], 0
	v_mfma_f32_16x16x32_bf16 v[84:87], v[208:211], v[180:183], v[84:87]
	v_mfma_f32_16x16x32_bf16 v[80:83], v[216:219], v[180:183], 0
	v_mfma_f32_16x16x32_bf16 v[80:83], v[212:215], v[176:179], v[80:83]
	v_mfma_f32_16x16x32_bf16 v[64:67], v[212:215], v[196:199], 0
	v_mfma_f32_16x16x32_bf16 v[64:67], v[216:219], v[200:203], v[64:67]
	v_mfma_f32_16x16x32_bf16 v[68:71], v[208:211], v[200:203], 0
	v_mfma_f32_16x16x32_bf16 v[68:71], v[204:207], v[196:199], v[68:71]
	s_barrier
	s_mov_b32 m0, s17
	s_add_u32 s92, s24, 0x80
	s_addc_u32 s93, s25, 0
	ds_read_b128 v[144:147], v194 offset:16384
	ds_read_b128 v[148:151], v194 offset:17408
	ds_read_b128 v[152:155], v194 offset:18432
	ds_read_b128 v[156:159], v194 offset:19456
	ds_read_b128 v[176:179], v194 offset:20480
	ds_read_b128 v[180:183], v194 offset:21504
	ds_read_b128 v[196:199], v194 offset:22528
	ds_read_b128 v[200:203], v194 offset:23552
	global_load_lds_dwordx4 v160, s[24:25]
	s_mov_b32 m0, s19
	s_nop 0
	global_load_lds_dwordx4 v164, s[24:25]
	s_barrier
	s_waitcnt lgkmcnt(0)
	v_mfma_f32_16x16x32_bf16 v[60:63], v[128:131], v[144:147], 0
	v_mfma_f32_16x16x32_bf16 v[60:63], v[132:135], v[148:151], v[60:63]
	v_mfma_f32_16x16x32_bf16 v[56:59], v[140:143], v[148:151], 0
	v_mfma_f32_16x16x32_bf16 v[56:59], v[136:139], v[144:147], v[56:59]
	v_mfma_f32_16x16x32_bf16 v[40:43], v[136:139], v[152:155], 0
	v_mfma_f32_16x16x32_bf16 v[40:43], v[140:143], v[156:159], v[40:43]
	v_mfma_f32_16x16x32_bf16 v[48:51], v[132:135], v[156:159], 0
	v_mfma_f32_16x16x32_bf16 v[48:51], v[128:131], v[152:155], v[48:51]
	v_mfma_f32_16x16x32_bf16 v[32:35], v[128:131], v[176:179], 0
	v_mfma_f32_16x16x32_bf16 v[32:35], v[132:135], v[180:183], v[32:35]
	v_mfma_f32_16x16x32_bf16 v[24:27], v[140:143], v[180:183], 0
	v_mfma_f32_16x16x32_bf16 v[24:27], v[136:139], v[176:179], v[24:27]
	v_mfma_f32_16x16x32_bf16 v[8:11], v[136:139], v[196:199], 0
	v_mfma_f32_16x16x32_bf16 v[8:11], v[140:143], v[200:203], v[8:11]
	v_mfma_f32_16x16x32_bf16 v[16:19], v[132:135], v[200:203], 0
	v_mfma_f32_16x16x32_bf16 v[16:19], v[128:131], v[196:199], v[16:19]
	s_barrier
	s_add_u32 s48, s22, 0x100000
	s_addc_u32 s49, s23, 0
	s_add_i32 s47, s43, s34
	s_mov_b32 m0, s47
	s_nop 0
	global_load_lds_dwordx4 v162, s[48:49]
	s_add_i32 m0, s47, 0x2000
	s_nop 0
	global_load_lds_dwordx4 v166, s[48:49]
	s_waitcnt vmcnt(6)
	s_barrier
; #define PG8_STAGE(bufoff, gbase, voff) do { _Pragma("unroll") for (int _i = 0; _i < 2; ++_i) \
;         __builtin_amdgcn_global_load_lds((const unsigned*)((const char*)(gbase) + (voff)[_i]), (LAS unsigned*)(lds + (bufoff) + ldsw + _i * 8192), 16, 0, 0); } while (0)
; #define PG8_LDA(dst, b, h) do { _Pragma("unroll") for (int m = 0; m < 4; ++m) _Pragma("unroll") for (int k = 0; k < 2; ++k) dst[m][k] = *(const LAS bf16x8*)(lds + PG8_SA(b, h) + aoff + m * 2048 + k * 1024); } while (0)
; #define PG8_LDB(dst, b, h) do { _Pragma("unroll") for (int n = 0; n < 2; ++n) _Pragma("unroll") for (int k = 0; k < 2; ++k) dst[n][k] = *(const LAS bf16x8*)(lds + PG8_SB(b, h) + boff + n * 2048 + k * 1024); } while (0)
; #define PG8_MMA(ai, bj, At, Bt) do { __builtin_amdgcn_s_setprio(1); _Pragma("unroll") for (int m = 0; m < 4; ++m) _Pragma("unroll") for (int n = 0; n < 2; ++n) _Pragma("unroll") for (int k = 0; k < 2; ++k) \
;         acc[ai][bj][m][n] = __builtin_amdgcn_mfma_f32_16x16x32_bf16(Bt[n][k], At[m][k], acc[ai][bj][m][n], 0, 0, 0); __builtin_amdgcn_s_setprio(0); } while (0)
; #define PG8_WAIT_V(n) asm volatile("s_waitcnt vmcnt(" #n ")" ::: "memory")
; #define PG8_WAIT_L(n) asm volatile("s_waitcnt lgkmcnt(" #n ")" ::: "memory")
; #define PG8_BAR __builtin_amdgcn_s_barrier()
; #define PG8_SCHED __builtin_amdgcn_sched_barrier(0)
; template <class Epi, class Ptrs>
; __device__ __forceinline__ void gemm_phase(LAS unsigned char* lds, const int K, const StaticOrder& S, const Ptrs& P, const Epi& E) {
;     ...
;             PG8_WAIT_V(6); PG8_BAR; PG8_MMA(1, 1, At, B1); PG8_BAR;
;             PG8_LDB(B0, 1, 0); PG8_SCHED; PG8_LDA(At, 1, 0); PG8_STAGE(PG8_SA(0, 1), a2 + hstep, voffA);
;             PG8_WAIT_L(8); PG8_BAR; PG8_WAIT_L(0); PG8_MMA(0, 0, At, B0); PG8_BAR; PG8_SCHED;
;             PG8_LDB(B1, 1, 1); PG8_STAGE(PG8_SB(1, 0), b3, voffB);
;             PG8_BAR; PG8_WAIT_L(0); PG8_MMA(0, 1, At, B1); PG8_BAR;
;             PG8_LDA(At, 1, 1); PG8_STAGE(PG8_SA(1, 0), a3, voffA);
;             PG8_BAR; PG8_WAIT_L(0); PG8_MMA(1, 0, At, B0); PG8_BAR; PG8_SCHED;
	v_mfma_f32_16x16x32_bf16 v[52:55], v[204:207], v[144:147], 0
	v_mfma_f32_16x16x32_bf16 v[52:55], v[208:211], v[148:151], v[52:55]
	v_mfma_f32_16x16x32_bf16 v[44:47], v[216:219], v[148:151], 0
	v_mfma_f32_16x16x32_bf16 v[44:47], v[212:215], v[144:147], v[44:47]
	v_mfma_f32_16x16x32_bf16 v[28:31], v[212:215], v[152:155], 0
	v_mfma_f32_16x16x32_bf16 v[28:31], v[216:219], v[156:159], v[28:31]
	v_mfma_f32_16x16x32_bf16 v[36:39], v[208:211], v[156:159], 0
	v_mfma_f32_16x16x32_bf16 v[36:39], v[204:207], v[152:155], v[36:39]
	v_mfma_f32_16x16x32_bf16 v[20:23], v[204:207], v[176:179], 0
	v_mfma_f32_16x16x32_bf16 v[20:23], v[208:211], v[180:183], v[20:23]
	v_mfma_f32_16x16x32_bf16 v[12:15], v[216:219], v[180:183], 0
	v_mfma_f32_16x16x32_bf16 v[12:15], v[212:215], v[176:179], v[12:15]
	v_mfma_f32_16x16x32_bf16 v[0:3], v[212:215], v[196:199], 0
	v_mfma_f32_16x16x32_bf16 v[0:3], v[216:219], v[200:203], v[0:3]
	v_mfma_f32_16x16x32_bf16 v[4:7], v[208:211], v[200:203], 0
	v_mfma_f32_16x16x32_bf16 v[4:7], v[204:207], v[196:199], v[4:7]
	s_barrier
	s_add_i32 s47, 0, 0x18000
	ds_read_b128 v[128:131], v252
	ds_read_b128 v[132:135], v252 offset:1024
	ds_read_b128 v[136:139], v252 offset:2048
	ds_read_b128 v[140:143], v252 offset:3072
	s_add_u32 s24, s24, 0x100000
	s_addc_u32 s25, s25, 0
	s_mov_b32 m0, s40
	ds_read_b128 v[144:147], v194 offset:32768
	ds_read_b128 v[148:151], v194 offset:33792
	ds_read_b128 v[152:155], v194 offset:34816
	ds_read_b128 v[156:159], v194 offset:35840
	ds_read_b128 v[176:179], v194 offset:36864
	ds_read_b128 v[180:183], v194 offset:37888
	ds_read_b128 v[196:199], v194 offset:38912
	ds_read_b128 v[200:203], v194 offset:39936
	global_load_lds_dwordx4 v160, s[24:25]
	s_mov_b32 m0, s41
	s_nop 0
	global_load_lds_dwordx4 v164, s[24:25]
	s_waitcnt lgkmcnt(8)
	s_barrier
	s_waitcnt lgkmcnt(0)
	v_mfma_f32_16x16x32_bf16 v[124:127], v[128:131], v[144:147], v[124:127]
	v_mfma_f32_16x16x32_bf16 v[124:127], v[132:135], v[148:151], v[124:127]
	v_mfma_f32_16x16x32_bf16 v[120:123], v[140:143], v[148:151], v[120:123]
	v_mfma_f32_16x16x32_bf16 v[120:123], v[136:139], v[144:147], v[120:123]
	v_mfma_f32_16x16x32_bf16 v[104:107], v[136:139], v[152:155], v[104:107]
	v_mfma_f32_16x16x32_bf16 v[104:107], v[140:143], v[156:159], v[104:107]
	v_mfma_f32_16x16x32_bf16 v[112:115], v[132:135], v[156:159], v[112:115]
	v_mfma_f32_16x16x32_bf16 v[112:115], v[128:131], v[152:155], v[112:115]
	v_mfma_f32_16x16x32_bf16 v[92:95], v[128:131], v[176:179], v[92:95]
	v_mfma_f32_16x16x32_bf16 v[92:95], v[132:135], v[180:183], v[92:95]
	v_mfma_f32_16x16x32_bf16 v[88:91], v[140:143], v[180:183], v[88:91]
	v_mfma_f32_16x16x32_bf16 v[88:91], v[136:139], v[176:179], v[88:91]
	v_mfma_f32_16x16x32_bf16 v[72:75], v[136:139], v[196:199], v[72:75]
	v_mfma_f32_16x16x32_bf16 v[72:75], v[140:143], v[200:203], v[72:75]
	v_mfma_f32_16x16x32_bf16 v[76:79], v[132:135], v[200:203], v[76:79]
	v_mfma_f32_16x16x32_bf16 v[76:79], v[128:131], v[196:199], v[76:79]
	s_barrier
	s_add_i32 s24, 0, 0x1c000
	s_add_i32 s25, s47, s34
	s_mov_b32 m0, s25
	ds_read_b128 v[204:207], v253
	ds_read_b128 v[208:211], v253 offset:1024
	ds_read_b128 v[212:215], v253 offset:2048
	ds_read_b128 v[216:219], v253 offset:3072
	global_load_lds_dwordx4 v162, s[90:91]
	s_add_i32 m0, s25, 0x2000
	s_nop 0
	global_load_lds_dwordx4 v166, s[90:91]
	s_barrier
	s_waitcnt lgkmcnt(0)
	v_mfma_f32_16x16x32_bf16 v[116:119], v[204:207], v[144:147], v[116:119]
	v_mfma_f32_16x16x32_bf16 v[116:119], v[208:211], v[148:151], v[116:119]
	v_mfma_f32_16x16x32_bf16 v[108:111], v[216:219], v[148:151], v[108:111]
	v_mfma_f32_16x16x32_bf16 v[108:111], v[212:215], v[144:147], v[108:111]
	v_mfma_f32_16x16x32_bf16 v[96:99], v[212:215], v[152:155], v[96:99]
	v_mfma_f32_16x16x32_bf16 v[96:99], v[216:219], v[156:159], v[96:99]
	v_mfma_f32_16x16x32_bf16 v[100:103], v[208:211], v[156:159], v[100:103]
	v_mfma_f32_16x16x32_bf16 v[100:103], v[204:207], v[152:155], v[100:103]
	v_mfma_f32_16x16x32_bf16 v[84:87], v[204:207], v[176:179], v[84:87]
	v_mfma_f32_16x16x32_bf16 v[84:87], v[208:211], v[180:183], v[84:87]
	v_mfma_f32_16x16x32_bf16 v[80:83], v[216:219], v[180:183], v[80:83]
	v_mfma_f32_16x16x32_bf16 v[80:83], v[212:215], v[176:179], v[80:83]
	v_mfma_f32_16x16x32_bf16 v[64:67], v[212:215], v[196:199], v[64:67]
	v_mfma_f32_16x16x32_bf16 v[64:67], v[216:219], v[200:203], v[64:67]
	v_mfma_f32_16x16x32_bf16 v[68:71], v[208:211], v[200:203], v[68:71]
	v_mfma_f32_16x16x32_bf16 v[68:71], v[204:207], v[196:199], v[68:71]
	s_barrier
	s_mov_b32 m0, s28
	ds_read_b128 v[144:147], v194 offset:49152
	ds_read_b128 v[148:151], v194 offset:50176
	ds_read_b128 v[152:155], v194 offset:51200
	ds_read_b128 v[156:159], v194 offset:52224
	ds_read_b128 v[176:179], v194 offset:53248
	ds_read_b128 v[180:183], v194 offset:54272
	ds_read_b128 v[196:199], v194 offset:55296
	ds_read_b128 v[200:203], v194 offset:56320
	global_load_lds_dwordx4 v160, s[92:93]
	s_mov_b32 m0, s29
	s_nop 0
	global_load_lds_dwordx4 v164, s[92:93]
	s_barrier
	s_waitcnt lgkmcnt(0)
	v_mfma_f32_16x16x32_bf16 v[60:63], v[128:131], v[144:147], v[60:63]
	v_mfma_f32_16x16x32_bf16 v[60:63], v[132:135], v[148:151], v[60:63]
	v_mfma_f32_16x16x32_bf16 v[56:59], v[140:143], v[148:151], v[56:59]
	v_mfma_f32_16x16x32_bf16 v[56:59], v[136:139], v[144:147], v[56:59]
	v_mfma_f32_16x16x32_bf16 v[40:43], v[136:139], v[152:155], v[40:43]
	v_mfma_f32_16x16x32_bf16 v[40:43], v[140:143], v[156:159], v[40:43]
	v_mfma_f32_16x16x32_bf16 v[48:51], v[132:135], v[156:159], v[48:51]
	v_mfma_f32_16x16x32_bf16 v[48:51], v[128:131], v[152:155], v[48:51]
	v_mfma_f32_16x16x32_bf16 v[32:35], v[128:131], v[176:179], v[32:35]
	v_mfma_f32_16x16x32_bf16 v[32:35], v[132:135], v[180:183], v[32:35]
	v_mfma_f32_16x16x32_bf16 v[24:27], v[140:143], v[180:183], v[24:27]
	v_mfma_f32_16x16x32_bf16 v[24:27], v[136:139], v[176:179], v[24:27]
	v_mfma_f32_16x16x32_bf16 v[8:11], v[136:139], v[196:199], v[8:11]
	v_mfma_f32_16x16x32_bf16 v[8:11], v[140:143], v[200:203], v[8:11]
	v_mfma_f32_16x16x32_bf16 v[16:19], v[132:135], v[200:203], v[16:19]
	v_mfma_f32_16x16x32_bf16 v[16:19], v[128:131], v[196:199], v[16:19]
	s_barrier
; #define PG8_STAGE(bufoff, gbase, voff) do { _Pragma("unroll") for (int _i = 0; _i < 2; ++_i) \
;         __builtin_amdgcn_global_load_lds((const unsigned*)((const char*)(gbase) + (voff)[_i]), (LAS unsigned*)(lds + (bufoff) + ldsw + _i * 8192), 16, 0, 0); } while (0)
; #define PG8_LDA(dst, b, h) do { _Pragma("unroll") for (int m = 0; m < 4; ++m) _Pragma("unroll") for (int k = 0; k < 2; ++k) dst[m][k] = *(const LAS bf16x8*)(lds + PG8_SA(b, h) + aoff + m * 2048 + k * 1024); } while (0)
; #define PG8_LDB(dst, b, h) do { _Pragma("unroll") for (int n = 0; n < 2; ++n) _Pragma("unroll") for (int k = 0; k < 2; ++k) dst[n][k] = *(const LAS bf16x8*)(lds + PG8_SB(b, h) + boff + n * 2048 + k * 1024); } while (0)
; #define PG8_WAIT_V(n) asm volatile("s_waitcnt vmcnt(" #n ")" ::: "memory")
; #define PG8_WAIT_L(n) asm volatile("s_waitcnt lgkmcnt(" #n ")" ::: "memory")
; #define PG8_BAR __builtin_amdgcn_s_barrier()
; #define PG8_SCHED __builtin_amdgcn_sched_barrier(0)
; template <class Epi, class Ptrs>
; __device__ __forceinline__ void gemm_phase(LAS unsigned char* lds, const int K, const StaticOrder& S, const Ptrs& P, const Epi& E) {
;     ...
;             PG8_LDB(B0, 0, 0); PG8_SCHED; PG8_LDA(At, 0, 0); PG8_STAGE(PG8_SA(1, 1), a1 + hstep, voffA);
;             PG8_WAIT_L(8); PG8_BAR; PG8_WAIT_L(0); PG8_MMA(0, 0, At, B0); PG8_BAR; PG8_SCHED;
;             PG8_LDB(B1, 0, 1); PG8_STAGE(PG8_SB(0, 0), b2, voffB);
;             PG8_BAR; PG8_WAIT_L(0); PG8_MMA(0, 1, At, B1); PG8_BAR;
;             PG8_LDA(At, 0, 1); PG8_STAGE(PG8_SA(0, 0), a2, voffA);
;             PG8_BAR; PG8_WAIT_L(0); PG8_MMA(1, 0, At, B0); PG8_BAR; PG8_SCHED;
;             PG8_STAGE(PG8_SB(0, 1), b2 + hstep, voffB);
;             PG8_WAIT_V(6); PG8_BAR; PG8_MMA(1, 1, At, B1); PG8_BAR;
;             PG8_LDB(B0, 1, 0); PG8_SCHED; PG8_LDA(At, 1, 0); PG8_STAGE(PG8_SA(0, 1), a2 + hstep, voffA);
;             PG8_WAIT_L(8); PG8_BAR; PG8_WAIT_L(0); PG8_MMA(0, 0, At, B0); PG8_BAR; PG8_SCHED;
;             PG8_LDB(B1, 1, 1); PG8_STAGE(PG8_SB(1, 0), b3, voffB);
;             PG8_BAR; PG8_WAIT_L(0); PG8_MMA(0, 1, At, B1); PG8_BAR;
;             PG8_LDA(At, 1, 1); PG8_STAGE(PG8_SA(1, 0), a3, voffA);
;             PG8_BAR; PG8_WAIT_L(0); PG8_MMA(1, 0, At, B0); PG8_BAR; PG8_SCHED;
;             PG8_STAGE(PG8_SB(1, 1), b3 + hstep, voffB);
;             PG8_WAIT_V(6); PG8_BAR; PG8_MMA(1, 1, At, B1); PG8_BAR;
	s_add_u32 s22, s22, 0x100080
	s_addc_u32 s23, s23, 0
	s_add_i32 s24, s24, s34
	s_mov_b32 m0, s24
	s_nop 0
	global_load_lds_dwordx4 v162, s[22:23]
	s_add_i32 m0, s24, 0x2000
	s_nop 0
	global_load_lds_dwordx4 v166, s[22:23]
	s_waitcnt vmcnt(6)
	s_barrier
	v_mfma_f32_16x16x32_bf16 v[52:55], v[204:207], v[144:147], v[52:55]
	v_mfma_f32_16x16x32_bf16 v[52:55], v[208:211], v[148:151], v[52:55]
	v_mfma_f32_16x16x32_bf16 v[44:47], v[216:219], v[148:151], v[44:47]
	v_mfma_f32_16x16x32_bf16 v[44:47], v[212:215], v[144:147], v[44:47]
	v_mfma_f32_16x16x32_bf16 v[28:31], v[212:215], v[152:155], v[28:31]
	v_mfma_f32_16x16x32_bf16 v[28:31], v[216:219], v[156:159], v[28:31]
	v_mfma_f32_16x16x32_bf16 v[36:39], v[208:211], v[156:159], v[36:39]
	v_mfma_f32_16x16x32_bf16 v[36:39], v[204:207], v[152:155], v[36:39]
	v_mfma_f32_16x16x32_bf16 v[20:23], v[204:207], v[176:179], v[20:23]
	v_mfma_f32_16x16x32_bf16 v[20:23], v[208:211], v[180:183], v[20:23]
	v_mfma_f32_16x16x32_bf16 v[12:15], v[216:219], v[180:183], v[12:15]
	v_mfma_f32_16x16x32_bf16 v[12:15], v[212:215], v[176:179], v[12:15]
	v_mfma_f32_16x16x32_bf16 v[0:3], v[212:215], v[196:199], v[0:3]
	v_mfma_f32_16x16x32_bf16 v[0:3], v[216:219], v[200:203], v[0:3]
	v_mfma_f32_16x16x32_bf16 v[4:7], v[208:211], v[200:203], v[4:7]
	v_mfma_f32_16x16x32_bf16 v[4:7], v[204:207], v[196:199], v[4:7]
	s_barrier
	s_add_i32 s46, s46, 2
	s_add_u32 s20, s20, 0x100
	s_addc_u32 s21, s21, 0
	s_add_u32 s11, s11, 0x100
	s_addc_u32 s13, s13, 0
	s_cmp_gt_u32 s46, 61
.LBB0_522:
	ds_read_b128 v[128:131], v193
	ds_read_b128 v[132:135], v193 offset:1024
	ds_read_b128 v[136:139], v193 offset:2048
	ds_read_b128 v[140:143], v193 offset:3072
	s_add_u32 s22, s20, 0xfff00080
	s_addc_u32 s23, s21, -1
	s_cmp_eq_u32 s46, 60
	s_cselect_b32 s25, s5, s23
	s_cselect_b32 s24, s4, s22
	s_cselect_b32 s23, s15, s13
	s_cselect_b32 s22, s14, s11
	s_add_i32 m0, s17, 0xc000
	ds_read_b128 v[144:147], v194
	ds_read_b128 v[148:151], v194 offset:1024
	ds_read_b128 v[152:155], v194 offset:2048
	ds_read_b128 v[156:159], v194 offset:3072
	ds_read_b128 v[176:179], v194 offset:4096
	ds_read_b128 v[180:183], v194 offset:5120
	ds_read_b128 v[196:199], v194 offset:6144
	ds_read_b128 v[200:203], v194 offset:7168
	global_load_lds_dwordx4 v168, s[20:21]
	s_add_i32 m0, s17, 0xe000
	s_nop 0
	global_load_lds_dwordx4 v170, s[20:21]
	s_waitcnt lgkmcnt(8)
	s_barrier
	s_waitcnt lgkmcnt(0)
	v_mfma_f32_16x16x32_bf16 v[124:127], v[128:131], v[144:147], v[124:127]
	v_mfma_f32_16x16x32_bf16 v[124:127], v[132:135], v[148:151], v[124:127]
	v_mfma_f32_16x16x32_bf16 v[120:123], v[140:143], v[148:151], v[120:123]
	v_mfma_f32_16x16x32_bf16 v[120:123], v[136:139], v[144:147], v[120:123]
	v_mfma_f32_16x16x32_bf16 v[104:107], v[136:139], v[152:155], v[104:107]
	v_mfma_f32_16x16x32_bf16 v[104:107], v[140:143], v[156:159], v[104:107]
	v_mfma_f32_16x16x32_bf16 v[112:115], v[132:135], v[156:159], v[112:115]
	v_mfma_f32_16x16x32_bf16 v[112:115], v[128:131], v[152:155], v[112:115]
	v_mfma_f32_16x16x32_bf16 v[92:95], v[128:131], v[176:179], v[92:95]
	v_mfma_f32_16x16x32_bf16 v[92:95], v[132:135], v[180:183], v[92:95]
	v_mfma_f32_16x16x32_bf16 v[88:91], v[140:143], v[180:183], v[88:91]
	v_mfma_f32_16x16x32_bf16 v[88:91], v[136:139], v[176:179], v[88:91]
	v_mfma_f32_16x16x32_bf16 v[72:75], v[136:139], v[196:199], v[72:75]
	v_mfma_f32_16x16x32_bf16 v[72:75], v[140:143], v[200:203], v[72:75]
	v_mfma_f32_16x16x32_bf16 v[76:79], v[132:135], v[200:203], v[76:79]
	v_mfma_f32_16x16x32_bf16 v[76:79], v[128:131], v[196:199], v[76:79]
	s_barrier
	s_add_i32 s47, s42, s34
	s_add_u32 s90, s22, 0x80
	s_addc_u32 s91, s23, 0
	s_mov_b32 m0, s47
	ds_read_b128 v[204:207], v195
	ds_read_b128 v[208:211], v195 offset:1024
	ds_read_b128 v[212:215], v195 offset:2048
	ds_read_b128 v[216:219], v195 offset:3072
	global_load_lds_dwordx4 v162, s[22:23]
	s_add_i32 m0, s47, 0x2000
	s_nop 0
	global_load_lds_dwordx4 v166, s[22:23]
	s_barrier
	s_waitcnt lgkmcnt(0)
	v_mfma_f32_16x16x32_bf16 v[116:119], v[204:207], v[144:147], v[116:119]
	v_mfma_f32_16x16x32_bf16 v[116:119], v[208:211], v[148:151], v[116:119]
	v_mfma_f32_16x16x32_bf16 v[108:111], v[216:219], v[148:151], v[108:111]
	v_mfma_f32_16x16x32_bf16 v[108:111], v[212:215], v[144:147], v[108:111]
	v_mfma_f32_16x16x32_bf16 v[96:99], v[212:215], v[152:155], v[96:99]
	v_mfma_f32_16x16x32_bf16 v[96:99], v[216:219], v[156:159], v[96:99]
	v_mfma_f32_16x16x32_bf16 v[100:103], v[208:211], v[156:159], v[100:103]
	v_mfma_f32_16x16x32_bf16 v[100:103], v[204:207], v[152:155], v[100:103]
	v_mfma_f32_16x16x32_bf16 v[84:87], v[204:207], v[176:179], v[84:87]
	v_mfma_f32_16x16x32_bf16 v[84:87], v[208:211], v[180:183], v[84:87]
	v_mfma_f32_16x16x32_bf16 v[80:83], v[216:219], v[180:183], v[80:83]
	v_mfma_f32_16x16x32_bf16 v[80:83], v[212:215], v[176:179], v[80:83]
	v_mfma_f32_16x16x32_bf16 v[64:67], v[212:215], v[196:199], v[64:67]
	v_mfma_f32_16x16x32_bf16 v[64:67], v[216:219], v[200:203], v[64:67]
	v_mfma_f32_16x16x32_bf16 v[68:71], v[208:211], v[200:203], v[68:71]
	v_mfma_f32_16x16x32_bf16 v[68:71], v[204:207], v[196:199], v[68:71]
	s_barrier
	s_mov_b32 m0, s17
	s_add_u32 s92, s24, 0x80
	s_addc_u32 s93, s25, 0
	ds_read_b128 v[144:147], v194 offset:16384
	ds_read_b128 v[148:151], v194 offset:17408
	ds_read_b128 v[152:155], v194 offset:18432
	ds_read_b128 v[156:159], v194 offset:19456
	ds_read_b128 v[176:179], v194 offset:20480
	ds_read_b128 v[180:183], v194 offset:21504
	ds_read_b128 v[196:199], v194 offset:22528
	ds_read_b128 v[200:203], v194 offset:23552
	global_load_lds_dwordx4 v160, s[24:25]
	s_mov_b32 m0, s19
	s_nop 0
	global_load_lds_dwordx4 v164, s[24:25]
	s_barrier
; #define PG8_STAGE(bufoff, gbase, voff) do { _Pragma("unroll") for (int _i = 0; _i < 2; ++_i) \
;         __builtin_amdgcn_global_load_lds((const unsigned*)((const char*)(gbase) + (voff)[_i]), (LAS unsigned*)(lds + (bufoff) + ldsw + _i * 8192), 16, 0, 0); } while (0)
; #define PG8_LDA(dst, b, h) do { _Pragma("unroll") for (int m = 0; m < 4; ++m) _Pragma("unroll") for (int k = 0; k < 2; ++k) dst[m][k] = *(const LAS bf16x8*)(lds + PG8_SA(b, h) + aoff + m * 2048 + k * 1024); } while (0)
; #define PG8_LDB(dst, b, h) do { _Pragma("unroll") for (int n = 0; n < 2; ++n) _Pragma("unroll") for (int k = 0; k < 2; ++k) dst[n][k] = *(const LAS bf16x8*)(lds + PG8_SB(b, h) + boff + n * 2048 + k * 1024); } while (0)
; #define PG8_MMA(ai, bj, At, Bt) do { __builtin_amdgcn_s_setprio(1); _Pragma("unroll") for (int m = 0; m < 4; ++m) _Pragma("unroll") for (int n = 0; n < 2; ++n) _Pragma("unroll") for (int k = 0; k < 2; ++k) \
;         acc[ai][bj][m][n] = __builtin_amdgcn_mfma_f32_16x16x32_bf16(Bt[n][k], At[m][k], acc[ai][bj][m][n], 0, 0, 0); __builtin_amdgcn_s_setprio(0); } while (0)
; #define PG8_WAIT_V(n) asm volatile("s_waitcnt vmcnt(" #n ")" ::: "memory")
; #define PG8_WAIT_L(n) asm volatile("s_waitcnt lgkmcnt(" #n ")" ::: "memory")
; #define PG8_BAR __builtin_amdgcn_s_barrier()
; #define PG8_SCHED __builtin_amdgcn_sched_barrier(0)
; template <class Epi, class Ptrs>
; __device__ __forceinline__ void gemm_phase(LAS unsigned char* lds, const int K, const StaticOrder& S, const Ptrs& P, const Epi& E) {
;     ...
;             PG8_BAR; PG8_WAIT_L(0); PG8_MMA(1, 0, At, B0); PG8_BAR; PG8_SCHED;
;             PG8_STAGE(PG8_SB(0, 1), b2 + hstep, voffB);
;             PG8_WAIT_V(6); PG8_BAR; PG8_MMA(1, 1, At, B1); PG8_BAR;
;             PG8_LDB(B0, 1, 0); PG8_SCHED; PG8_LDA(At, 1, 0); PG8_STAGE(PG8_SA(0, 1), a2 + hstep, voffA);
;             PG8_WAIT_L(8); PG8_BAR; PG8_WAIT_L(0); PG8_MMA(0, 0, At, B0); PG8_BAR; PG8_SCHED;
;             PG8_LDB(B1, 1, 1); PG8_STAGE(PG8_SB(1, 0), b3, voffB);
;             PG8_BAR; PG8_WAIT_L(0); PG8_MMA(0, 1, At, B1); PG8_BAR;
	s_waitcnt lgkmcnt(0)
	v_mfma_f32_16x16x32_bf16 v[60:63], v[128:131], v[144:147], v[60:63]
	v_mfma_f32_16x16x32_bf16 v[60:63], v[132:135], v[148:151], v[60:63]
	v_mfma_f32_16x16x32_bf16 v[56:59], v[140:143], v[148:151], v[56:59]
	v_mfma_f32_16x16x32_bf16 v[56:59], v[136:139], v[144:147], v[56:59]
	v_mfma_f32_16x16x32_bf16 v[40:43], v[136:139], v[152:155], v[40:43]
	v_mfma_f32_16x16x32_bf16 v[40:43], v[140:143], v[156:159], v[40:43]
	v_mfma_f32_16x16x32_bf16 v[48:51], v[132:135], v[156:159], v[48:51]
	v_mfma_f32_16x16x32_bf16 v[48:51], v[128:131], v[152:155], v[48:51]
	v_mfma_f32_16x16x32_bf16 v[32:35], v[128:131], v[176:179], v[32:35]
	v_mfma_f32_16x16x32_bf16 v[32:35], v[132:135], v[180:183], v[32:35]
	v_mfma_f32_16x16x32_bf16 v[24:27], v[140:143], v[180:183], v[24:27]
	v_mfma_f32_16x16x32_bf16 v[24:27], v[136:139], v[176:179], v[24:27]
	v_mfma_f32_16x16x32_bf16 v[8:11], v[136:139], v[196:199], v[8:11]
	v_mfma_f32_16x16x32_bf16 v[8:11], v[140:143], v[200:203], v[8:11]
	v_mfma_f32_16x16x32_bf16 v[16:19], v[132:135], v[200:203], v[16:19]
	v_mfma_f32_16x16x32_bf16 v[16:19], v[128:131], v[196:199], v[16:19]
	s_barrier
	s_add_u32 s48, s22, 0x100000
	s_addc_u32 s49, s23, 0
	s_add_i32 s47, s43, s34
	s_mov_b32 m0, s47
	s_nop 0
	global_load_lds_dwordx4 v162, s[48:49]
	s_add_i32 m0, s47, 0x2000
	s_nop 0
	global_load_lds_dwordx4 v166, s[48:49]
	s_waitcnt vmcnt(6)
	s_barrier
	v_mfma_f32_16x16x32_bf16 v[52:55], v[204:207], v[144:147], v[52:55]
	v_mfma_f32_16x16x32_bf16 v[52:55], v[208:211], v[148:151], v[52:55]
	v_mfma_f32_16x16x32_bf16 v[44:47], v[216:219], v[148:151], v[44:47]
	v_mfma_f32_16x16x32_bf16 v[44:47], v[212:215], v[144:147], v[44:47]
	v_mfma_f32_16x16x32_bf16 v[28:31], v[212:215], v[152:155], v[28:31]
	v_mfma_f32_16x16x32_bf16 v[28:31], v[216:219], v[156:159], v[28:31]
	v_mfma_f32_16x16x32_bf16 v[36:39], v[208:211], v[156:159], v[36:39]
	v_mfma_f32_16x16x32_bf16 v[36:39], v[204:207], v[152:155], v[36:39]
	v_mfma_f32_16x16x32_bf16 v[20:23], v[204:207], v[176:179], v[20:23]
	v_mfma_f32_16x16x32_bf16 v[20:23], v[208:211], v[180:183], v[20:23]
	v_mfma_f32_16x16x32_bf16 v[12:15], v[216:219], v[180:183], v[12:15]
	v_mfma_f32_16x16x32_bf16 v[12:15], v[212:215], v[176:179], v[12:15]
	v_mfma_f32_16x16x32_bf16 v[0:3], v[212:215], v[196:199], v[0:3]
	v_mfma_f32_16x16x32_bf16 v[0:3], v[216:219], v[200:203], v[0:3]
	v_mfma_f32_16x16x32_bf16 v[4:7], v[208:211], v[200:203], v[4:7]
	v_mfma_f32_16x16x32_bf16 v[4:7], v[204:207], v[196:199], v[4:7]
	s_barrier
	s_add_i32 s47, 0, 0x18000
	ds_read_b128 v[128:131], v252
	ds_read_b128 v[132:135], v252 offset:1024
	ds_read_b128 v[136:139], v252 offset:2048
	ds_read_b128 v[140:143], v252 offset:3072
	s_add_u32 s24, s24, 0x100000
	s_addc_u32 s25, s25, 0
	s_mov_b32 m0, s40
	ds_read_b128 v[144:147], v194 offset:32768
	ds_read_b128 v[148:151], v194 offset:33792
	ds_read_b128 v[152:155], v194 offset:34816
	ds_read_b128 v[156:159], v194 offset:35840
	ds_read_b128 v[176:179], v194 offset:36864
	ds_read_b128 v[180:183], v194 offset:37888
	ds_read_b128 v[196:199], v194 offset:38912
	ds_read_b128 v[200:203], v194 offset:39936
	global_load_lds_dwordx4 v160, s[24:25]
	s_mov_b32 m0, s41
	s_nop 0
	global_load_lds_dwordx4 v164, s[24:25]
	s_waitcnt lgkmcnt(8)
	s_barrier
	s_waitcnt lgkmcnt(0)
	v_mfma_f32_16x16x32_bf16 v[124:127], v[128:131], v[144:147], v[124:127]
	v_mfma_f32_16x16x32_bf16 v[124:127], v[132:135], v[148:151], v[124:127]
	v_mfma_f32_16x16x32_bf16 v[120:123], v[140:143], v[148:151], v[120:123]
	v_mfma_f32_16x16x32_bf16 v[120:123], v[136:139], v[144:147], v[120:123]
	v_mfma_f32_16x16x32_bf16 v[104:107], v[136:139], v[152:155], v[104:107]
	v_mfma_f32_16x16x32_bf16 v[104:107], v[140:143], v[156:159], v[104:107]
	v_mfma_f32_16x16x32_bf16 v[112:115], v[132:135], v[156:159], v[112:115]
	v_mfma_f32_16x16x32_bf16 v[112:115], v[128:131], v[152:155], v[112:115]
	v_mfma_f32_16x16x32_bf16 v[92:95], v[128:131], v[176:179], v[92:95]
	v_mfma_f32_16x16x32_bf16 v[92:95], v[132:135], v[180:183], v[92:95]
	v_mfma_f32_16x16x32_bf16 v[88:91], v[140:143], v[180:183], v[88:91]
	v_mfma_f32_16x16x32_bf16 v[88:91], v[136:139], v[176:179], v[88:91]
	v_mfma_f32_16x16x32_bf16 v[72:75], v[136:139], v[196:199], v[72:75]
	v_mfma_f32_16x16x32_bf16 v[72:75], v[140:143], v[200:203], v[72:75]
	v_mfma_f32_16x16x32_bf16 v[76:79], v[132:135], v[200:203], v[76:79]
	v_mfma_f32_16x16x32_bf16 v[76:79], v[128:131], v[196:199], v[76:79]
	s_barrier
	s_add_i32 s24, 0, 0x1c000
	s_add_i32 s25, s47, s34
	s_mov_b32 m0, s25
	ds_read_b128 v[204:207], v253
	ds_read_b128 v[208:211], v253 offset:1024
	ds_read_b128 v[212:215], v253 offset:2048
	ds_read_b128 v[216:219], v253 offset:3072
	global_load_lds_dwordx4 v162, s[90:91]
	s_add_i32 m0, s25, 0x2000
	s_nop 0
	global_load_lds_dwordx4 v166, s[90:91]
	s_barrier
	s_waitcnt lgkmcnt(0)
	v_mfma_f32_16x16x32_bf16 v[116:119], v[204:207], v[144:147], v[116:119]
	v_mfma_f32_16x16x32_bf16 v[116:119], v[208:211], v[148:151], v[116:119]
	v_mfma_f32_16x16x32_bf16 v[108:111], v[216:219], v[148:151], v[108:111]
	v_mfma_f32_16x16x32_bf16 v[108:111], v[212:215], v[144:147], v[108:111]
	v_mfma_f32_16x16x32_bf16 v[96:99], v[212:215], v[152:155], v[96:99]
	v_mfma_f32_16x16x32_bf16 v[96:99], v[216:219], v[156:159], v[96:99]
	v_mfma_f32_16x16x32_bf16 v[100:103], v[208:211], v[156:159], v[100:103]
	v_mfma_f32_16x16x32_bf16 v[100:103], v[204:207], v[152:155], v[100:103]
	v_mfma_f32_16x16x32_bf16 v[84:87], v[204:207], v[176:179], v[84:87]
	v_mfma_f32_16x16x32_bf16 v[84:87], v[208:211], v[180:183], v[84:87]
	v_mfma_f32_16x16x32_bf16 v[80:83], v[216:219], v[180:183], v[80:83]
	v_mfma_f32_16x16x32_bf16 v[80:83], v[212:215], v[176:179], v[80:83]
	v_mfma_f32_16x16x32_bf16 v[64:67], v[212:215], v[196:199], v[64:67]
	v_mfma_f32_16x16x32_bf16 v[64:67], v[216:219], v[200:203], v[64:67]
	v_mfma_f32_16x16x32_bf16 v[68:71], v[208:211], v[200:203], v[68:71]
	v_mfma_f32_16x16x32_bf16 v[68:71], v[204:207], v[196:199], v[68:71]
	s_barrier
; #define PG8_STAGE(bufoff, gbase, voff) do { _Pragma("unroll") for (int _i = 0; _i < 2; ++_i) \
;         __builtin_amdgcn_global_load_lds((const unsigned*)((const char*)(gbase) + (voff)[_i]), (LAS unsigned*)(lds + (bufoff) + ldsw + _i * 8192), 16, 0, 0); } while (0)
; #define PG8_LDA(dst, b, h) do { _Pragma("unroll") for (int m = 0; m < 4; ++m) _Pragma("unroll") for (int k = 0; k < 2; ++k) dst[m][k] = *(const LAS bf16x8*)(lds + PG8_SA(b, h) + aoff + m * 2048 + k * 1024); } while (0)
; #define PG8_MMA(ai, bj, At, Bt) do { __builtin_amdgcn_s_setprio(1); _Pragma("unroll") for (int m = 0; m < 4; ++m) _Pragma("unroll") for (int n = 0; n < 2; ++n) _Pragma("unroll") for (int k = 0; k < 2; ++k) \
;         acc[ai][bj][m][n] = __builtin_amdgcn_mfma_f32_16x16x32_bf16(Bt[n][k], At[m][k], acc[ai][bj][m][n], 0, 0, 0); __builtin_amdgcn_s_setprio(0); } while (0)
; #define PG8_WAIT_V(n) asm volatile("s_waitcnt vmcnt(" #n ")" ::: "memory")
; #define PG8_WAIT_L(n) asm volatile("s_waitcnt lgkmcnt(" #n ")" ::: "memory")
; #define PG8_BAR __builtin_amdgcn_s_barrier()
; #define PG8_SCHED __builtin_amdgcn_sched_barrier(0)
; template <class Epi, class Ptrs>
; __device__ __forceinline__ void gemm_phase(LAS unsigned char* lds, const int K, const StaticOrder& S, const Ptrs& P, const Epi& E) {
;     ...
;             PG8_LDA(At, 1, 1); PG8_STAGE(PG8_SA(1, 0), a3, voffA);
;             PG8_BAR; PG8_WAIT_L(0); PG8_MMA(1, 0, At, B0); PG8_BAR; PG8_SCHED;
;             PG8_STAGE(PG8_SB(1, 1), b3 + hstep, voffB);
;             PG8_WAIT_V(6); PG8_BAR; PG8_MMA(1, 1, At, B1); PG8_BAR;
;     __device__ __forceinline__ void operator()(const f32x4 (&acc)[2][2][4][2], const Unit& u, int ui, int wr, int wc, int fr, int fq) const {
;         const int rl0 = wr * 64 + fr, col0 = u.pn * 256 + wc * 32 + 8 * fq;
;         u32x4 xv[2][4][2];
; #pragma unroll
;         for (int ai = 0; ai < 2; ++ai)
; #pragma unroll
;             for (int m = 0; m < 4; ++m)
; #pragma unroll
;                 for (int bj = 0; bj < 2; ++bj) xv[ai][m][bj] = *(const u32x4*)(xb + (size_t)(u.pm * 256 + rl0 + ai * 128 + m * 16) * DM + col0 + bj * 128);
	s_mov_b32 m0, s28
	ds_read_b128 v[144:147], v194 offset:49152
	ds_read_b128 v[148:151], v194 offset:50176
	ds_read_b128 v[152:155], v194 offset:51200
	ds_read_b128 v[156:159], v194 offset:52224
	ds_read_b128 v[176:179], v194 offset:53248
	ds_read_b128 v[180:183], v194 offset:54272
	ds_read_b128 v[196:199], v194 offset:55296
	ds_read_b128 v[200:203], v194 offset:56320
	global_load_lds_dwordx4 v160, s[92:93]
	s_mov_b32 m0, s29
	s_nop 0
	global_load_lds_dwordx4 v164, s[92:93]
	s_barrier
	s_waitcnt lgkmcnt(0)
	v_mfma_f32_16x16x32_bf16 v[60:63], v[128:131], v[144:147], v[60:63]
	v_mfma_f32_16x16x32_bf16 v[60:63], v[132:135], v[148:151], v[60:63]
	v_mfma_f32_16x16x32_bf16 v[56:59], v[140:143], v[148:151], v[56:59]
	v_mfma_f32_16x16x32_bf16 v[56:59], v[136:139], v[144:147], v[56:59]
	v_mfma_f32_16x16x32_bf16 v[40:43], v[136:139], v[152:155], v[40:43]
	v_mfma_f32_16x16x32_bf16 v[40:43], v[140:143], v[156:159], v[40:43]
	v_mfma_f32_16x16x32_bf16 v[48:51], v[132:135], v[156:159], v[48:51]
	v_mfma_f32_16x16x32_bf16 v[48:51], v[128:131], v[152:155], v[48:51]
	v_mfma_f32_16x16x32_bf16 v[32:35], v[128:131], v[176:179], v[32:35]
	v_mfma_f32_16x16x32_bf16 v[32:35], v[132:135], v[180:183], v[32:35]
	v_mfma_f32_16x16x32_bf16 v[24:27], v[140:143], v[180:183], v[24:27]
	v_mfma_f32_16x16x32_bf16 v[24:27], v[136:139], v[176:179], v[24:27]
	v_mfma_f32_16x16x32_bf16 v[8:11], v[136:139], v[196:199], v[8:11]
	v_mfma_f32_16x16x32_bf16 v[8:11], v[140:143], v[200:203], v[8:11]
	v_mfma_f32_16x16x32_bf16 v[16:19], v[132:135], v[200:203], v[16:19]
	v_mfma_f32_16x16x32_bf16 v[16:19], v[128:131], v[196:199], v[16:19]
	s_barrier
	s_add_u32 s22, s22, 0x100080
	s_addc_u32 s23, s23, 0
	s_add_i32 s24, s24, s34
	s_mov_b32 m0, s24
	s_nop 0
	global_load_lds_dwordx4 v162, s[22:23]
	s_add_i32 m0, s24, 0x2000
	s_nop 0
	global_load_lds_dwordx4 v166, s[22:23]
	s_waitcnt vmcnt(6)
	s_barrier
	v_mfma_f32_16x16x32_bf16 v[52:55], v[204:207], v[144:147], v[52:55]
	v_mfma_f32_16x16x32_bf16 v[52:55], v[208:211], v[148:151], v[52:55]
	v_mfma_f32_16x16x32_bf16 v[44:47], v[216:219], v[148:151], v[44:47]
	v_mfma_f32_16x16x32_bf16 v[44:47], v[212:215], v[144:147], v[44:47]
	v_mfma_f32_16x16x32_bf16 v[28:31], v[212:215], v[152:155], v[28:31]
	v_mfma_f32_16x16x32_bf16 v[28:31], v[216:219], v[156:159], v[28:31]
	v_mfma_f32_16x16x32_bf16 v[36:39], v[208:211], v[156:159], v[36:39]
	v_mfma_f32_16x16x32_bf16 v[36:39], v[204:207], v[152:155], v[36:39]
	v_mfma_f32_16x16x32_bf16 v[20:23], v[204:207], v[176:179], v[20:23]
	v_mfma_f32_16x16x32_bf16 v[20:23], v[208:211], v[180:183], v[20:23]
	v_mfma_f32_16x16x32_bf16 v[12:15], v[216:219], v[180:183], v[12:15]
	v_mfma_f32_16x16x32_bf16 v[12:15], v[212:215], v[176:179], v[12:15]
	v_mfma_f32_16x16x32_bf16 v[0:3], v[212:215], v[196:199], v[0:3]
	v_mfma_f32_16x16x32_bf16 v[0:3], v[216:219], v[200:203], v[0:3]
	v_mfma_f32_16x16x32_bf16 v[4:7], v[208:211], v[200:203], v[4:7]
	v_mfma_f32_16x16x32_bf16 v[4:7], v[204:207], v[196:199], v[4:7]
	s_barrier
	s_add_i32 s46, s46, 2
	s_add_u32 s20, s20, 0x100
	s_addc_u32 s21, s21, 0
	s_add_u32 s11, s11, 0x100
	s_addc_u32 s13, s13, 0
	s_cmp_gt_u32 s46, 61
	s_cbranch_scc0 .LBB0_522
	s_lshl_b32 s11, s18, 8
	v_lshl_or_b32 v128, s16, 8, v191
	v_add_u32_e32 v130, s11, v186
	v_ashrrev_i32_e32 v129, 31, v128
	v_ashrrev_i32_e32 v131, 31, v130
	v_lshl_add_u64 v[132:133], v[128:129], 1, s[6:7]
	v_lshlrev_b64 v[134:135], 11, v[130:131]
	v_lshl_add_u64 v[134:135], v[132:133], 0, v[134:135]
	global_load_dwordx4 v[198:201], v[134:135], off
	global_load_dwordx4 v[202:205], v[134:135], off offset:256
	v_or_b32_e32 v134, 16, v130
	v_ashrrev_i32_e32 v135, 31, v134
	v_lshlrev_b64 v[134:135], 11, v[134:135]
	v_lshl_add_u64 v[134:135], v[132:133], 0, v[134:135]
	global_load_dwordx4 v[206:209], v[134:135], off
	global_load_dwordx4 v[210:213], v[134:135], off offset:256
	v_or_b32_e32 v136, 32, v130
	v_ashrrev_i32_e32 v137, 31, v136
	v_or_b32_e32 v138, 48, v130
	v_add_u32_e32 v184, 0x80, v130
	v_add_u32_e32 v182, 0x90, v130
	v_add_u32_e32 v180, 0xa0, v130
	v_add_u32_e32 v178, 0xb0, v130
	v_lshlrev_b64 v[176:177], 2, v[128:129]
	v_lshlrev_b64 v[128:129], 12, v[130:131]
	v_lshlrev_b64 v[130:131], 11, v[136:137]
	v_lshl_add_u64 v[130:131], v[132:133], 0, v[130:131]
	global_load_dwordx4 v[214:217], v[130:131], off
	v_ashrrev_i32_e32 v139, 31, v138
	v_ashrrev_i32_e32 v185, 31, v184
	v_ashrrev_i32_e32 v183, 31, v182
	v_ashrrev_i32_e32 v181, 31, v180
	v_ashrrev_i32_e32 v179, 31, v178
	v_lshlrev_b64 v[134:135], 11, v[138:139]
	v_lshlrev_b64 v[136:137], 11, v[184:185]
	v_lshlrev_b64 v[138:139], 11, v[182:183]
	v_lshl_add_u32 v196, s45, 10, v192
	v_lshlrev_b64 v[140:141], 11, v[180:181]
	v_lshlrev_b64 v[142:143], 11, v[178:179]
	v_lshl_add_u64 v[128:129], s[26:27], 0, v[128:129]
	v_lshl_add_u64 v[134:135], v[132:133], 0, v[134:135]
	v_lshl_add_u64 v[136:137], v[132:133], 0, v[136:137]
	v_lshl_add_u64 v[138:139], v[132:133], 0, v[138:139]
	ds_read2_b32 v[230:231], v196 offset1:16
	v_lshl_add_u64 v[234:235], v[132:133], 0, v[140:141]
	v_lshl_add_u64 v[236:237], v[132:133], 0, v[142:143]
	v_lshl_add_u64 v[238:239], v[128:129], 0, v[176:177]
	global_load_dwordx4 v[218:221], v[130:131], off offset:256
	global_load_dwordx4 v[222:225], v[134:135], off
	global_load_dwordx4 v[226:229], v[134:135], off offset:256
	global_load_dwordx4 v[156:159], v[136:137], off
	global_load_dwordx4 v[152:155], v[136:137], off offset:256
	global_load_dwordx4 v[148:151], v[138:139], off
	global_load_dwordx4 v[144:147], v[138:139], off offset:256
	global_load_dwordx4 v[140:143], v[234:235], off
	s_nop 0
	global_load_dwordx4 v[136:139], v[234:235], off offset:256
	global_load_dwordx4 v[132:135], v[236:237], off
	global_load_dwordx4 v[128:131], v[236:237], off offset:256
	v_add_u32_e32 v232, s11, v188
	v_ashrrev_i32_e32 v233, 31, v232
	s_and_b64 vcc, exec, s[0:1]
	s_mov_b32 s16, s10
	s_mov_b32 s18, s12
	s_mov_b64 s[20:21], s[4:5]
	s_mov_b64 s[22:23], s[14:15]
	s_mov_b32 s45, s44
	s_waitcnt vmcnt(0)
; __device__ __forceinline__ float bf_lo(unsigned w) { return __uint_as_float(w << 16); }
; __device__ __forceinline__ float bf_hi(unsigned w) { return __uint_as_float(w & 0xffff0000u); }
;     __device__ __forceinline__ void operator()(const f32x4 (&acc)[2][2][4][2], const Unit& u, int ui, int wr, int wc, int fr, int fq) const {
;     ...
;         for (int ai = 0; ai < 2; ++ai)
; #pragma unroll
;             for (int m = 0; m < 4; ++m) { const int rl = rl0 + ai * 128 + m * 16; float* rowp = out + (size_t)(u.pm * 256 + rl) * DM + col0;
;                 const float r2 = tab[ui * 256 + rl];
; #pragma unroll
;                 for (int bj = 0; bj < 2; ++bj) { const u32x4 x = xv[ai][m][bj];
;                     const f32x4 x0 = {bf_lo(x.x), bf_hi(x.x), bf_lo(x.y), bf_hi(x.y)}, x1 = {bf_lo(x.z), bf_hi(x.z), bf_lo(x.w), bf_hi(x.w)};
;                     *(f32x4*)(rowp + bj * 128) = acc[ai][bj][m][0] * r2 + x0; *(f32x4*)(rowp + bj * 128 + 4) = acc[ai][bj][m][1] * r2 + x1; } }
	v_lshlrev_b32_e32 v234, 16, v198
	v_and_b32_e32 v235, 0xffff0000, v198
	v_lshlrev_b32_e32 v198, 16, v199
	v_and_b32_e32 v199, 0xffff0000, v199
	v_lshlrev_b32_e32 v242, 16, v204
	v_and_b32_e32 v243, 0xffff0000, v204
	v_lshlrev_b32_e32 v236, 16, v200
	v_and_b32_e32 v237, 0xffff0000, v200
	v_lshlrev_b32_e32 v200, 16, v201
	v_and_b32_e32 v201, 0xffff0000, v201
	v_lshlrev_b32_e32 v240, 16, v202
	v_and_b32_e32 v241, 0xffff0000, v202
	v_lshlrev_b32_e32 v202, 16, v203
	v_and_b32_e32 v203, 0xffff0000, v203
	v_lshlrev_b32_e32 v204, 16, v205
	v_and_b32_e32 v205, 0xffff0000, v205
	s_waitcnt lgkmcnt(0)
	v_pk_fma_f32 v[126:127], v[126:127], v[230:231], v[198:199] op_sel_hi:[1,0,1]
	v_pk_fma_f32 v[124:125], v[124:125], v[230:231], v[234:235] op_sel_hi:[1,0,1]
	v_pk_fma_f32 v[108:109], v[108:109], v[230:231], v[242:243] op_sel_hi:[1,0,1]
	v_pk_fma_f32 v[122:123], v[122:123], v[230:231], v[200:201] op_sel_hi:[1,0,1]
	v_pk_fma_f32 v[120:121], v[120:121], v[230:231], v[236:237] op_sel_hi:[1,0,1]
	v_pk_fma_f32 v[118:119], v[118:119], v[230:231], v[202:203] op_sel_hi:[1,0,1]
	v_pk_fma_f32 v[116:117], v[116:117], v[230:231], v[240:241] op_sel_hi:[1,0,1]
	v_pk_fma_f32 v[110:111], v[110:111], v[230:231], v[204:205] op_sel_hi:[1,0,1]
	global_store_dwordx4 v[238:239], v[124:127], off
	global_store_dwordx4 v[238:239], v[120:123], off offset:16
	global_store_dwordx4 v[238:239], v[116:119], off offset:512
	global_store_dwordx4 v[238:239], v[108:111], off offset:528
	v_mov_b32_e32 v122, v231
	v_lshlrev_b32_e32 v118, 16, v208
	v_lshlrev_b64 v[108:109], 12, v[232:233]
	v_lshl_add_u64 v[108:109], s[26:27], 0, v[108:109]
	v_lshl_add_u64 v[116:117], v[108:109], 0, v[176:177]
	v_lshlrev_b32_e32 v108, 16, v206
	v_and_b32_e32 v109, 0xffff0000, v206
	v_lshlrev_b32_e32 v110, 16, v207
	v_and_b32_e32 v111, 0xffff0000, v207
	v_pk_fma_f32 v[110:111], v[114:115], v[122:123], v[110:111] op_sel_hi:[1,0,1]
	v_pk_fma_f32 v[108:109], v[112:113], v[122:123], v[108:109] op_sel_hi:[1,0,1]
	global_store_dwordx4 v[116:117], v[108:111], off
	v_and_b32_e32 v119, 0xffff0000, v208
	v_lshlrev_b32_e32 v120, 16, v209
	v_lshlrev_b32_e32 v108, 16, v212
	v_and_b32_e32 v109, 0xffff0000, v212
	v_lshlrev_b32_e32 v110, 16, v213
	v_and_b32_e32 v111, 0xffff0000, v213
	v_pk_fma_f32 v[98:99], v[98:99], v[122:123], v[110:111] op_sel_hi:[1,0,1]
	v_pk_fma_f32 v[96:97], v[96:97], v[122:123], v[108:109] op_sel_hi:[1,0,1]
	v_and_b32_e32 v121, 0xffff0000, v209
	global_store_dwordx4 v[116:117], v[96:99], off offset:528
	ds_read2_b32 v[98:99], v196 offset0:32 offset1:48
	v_pk_fma_f32 v[106:107], v[106:107], v[122:123], v[120:121] op_sel_hi:[1,0,1]
	v_pk_fma_f32 v[104:105], v[104:105], v[122:123], v[118:119] op_sel_hi:[1,0,1]
	v_add_u32_e32 v96, s11, v189
	global_store_dwordx4 v[116:117], v[104:107], off offset:16
	v_ashrrev_i32_e32 v97, 31, v96
	v_lshlrev_b64 v[96:97], 12, v[96:97]
	v_lshlrev_b32_e32 v104, 16, v210
	v_and_b32_e32 v105, 0xffff0000, v210
	v_lshlrev_b32_e32 v106, 16, v211
	v_and_b32_e32 v107, 0xffff0000, v211
	v_pk_fma_f32 v[102:103], v[102:103], v[122:123], v[106:107] op_sel_hi:[1,0,1]
	v_pk_fma_f32 v[100:101], v[100:101], v[122:123], v[104:105] op_sel_hi:[1,0,1]
	global_store_dwordx4 v[116:117], v[100:103], off offset:512
	v_lshl_add_u64 v[96:97], s[26:27], 0, v[96:97]
	v_lshl_add_u64 v[96:97], v[96:97], 0, v[176:177]
	v_lshlrev_b32_e32 v100, 16, v214
	v_and_b32_e32 v101, 0xffff0000, v214
	v_lshlrev_b32_e32 v102, 16, v215
	v_and_b32_e32 v103, 0xffff0000, v215
	s_waitcnt lgkmcnt(0)
	v_pk_fma_f32 v[94:95], v[94:95], v[98:99], v[102:103] op_sel_hi:[1,0,1]
	v_pk_fma_f32 v[92:93], v[92:93], v[98:99], v[100:101] op_sel_hi:[1,0,1]
	global_store_dwordx4 v[96:97], v[92:95], off
	v_lshlrev_b32_e32 v104, 16, v216
	v_and_b32_e32 v105, 0xffff0000, v216
	v_lshlrev_b32_e32 v92, 16, v220
	v_and_b32_e32 v93, 0xffff0000, v220
	v_lshlrev_b32_e32 v94, 16, v221
	v_and_b32_e32 v95, 0xffff0000, v221
	v_lshlrev_b32_e32 v106, 16, v217
	v_and_b32_e32 v107, 0xffff0000, v217
	v_pk_fma_f32 v[82:83], v[82:83], v[98:99], v[94:95] op_sel_hi:[1,0,1]
	v_pk_fma_f32 v[80:81], v[80:81], v[98:99], v[92:93] op_sel_hi:[1,0,1]
	v_pk_fma_f32 v[90:91], v[90:91], v[98:99], v[106:107] op_sel_hi:[1,0,1]
	v_pk_fma_f32 v[88:89], v[88:89], v[98:99], v[104:105] op_sel_hi:[1,0,1]
	global_store_dwordx4 v[96:97], v[80:83], off offset:528
	global_store_dwordx4 v[96:97], v[88:91], off offset:16
	s_nop 0
	v_add_u32_e32 v80, s11, v190
	v_lshlrev_b32_e32 v88, 16, v218
	v_and_b32_e32 v89, 0xffff0000, v218
	v_lshlrev_b32_e32 v90, 16, v219
	v_and_b32_e32 v91, 0xffff0000, v219
	v_ashrrev_i32_e32 v81, 31, v80
	v_pk_fma_f32 v[86:87], v[86:87], v[98:99], v[90:91] op_sel_hi:[1,0,1]
	v_pk_fma_f32 v[84:85], v[84:85], v[98:99], v[88:89] op_sel_hi:[1,0,1]
	v_lshlrev_b64 v[80:81], 12, v[80:81]
	global_store_dwordx4 v[96:97], v[84:87], off offset:512
	v_lshl_add_u64 v[80:81], s[26:27], 0, v[80:81]
	v_lshlrev_b32_e32 v82, 16, v222
	v_and_b32_e32 v83, 0xffff0000, v222
	v_lshlrev_b32_e32 v84, 16, v223
	v_and_b32_e32 v85, 0xffff0000, v223
	v_mov_b32_e32 v90, v99
	v_lshl_add_u64 v[80:81], v[80:81], 0, v[176:177]
	v_pk_fma_f32 v[78:79], v[78:79], v[90:91], v[84:85] op_sel_hi:[1,0,1]
	v_pk_fma_f32 v[76:77], v[76:77], v[90:91], v[82:83] op_sel_hi:[1,0,1]
	global_store_dwordx4 v[80:81], v[76:79], off
	v_lshlrev_b32_e32 v86, 16, v224
	v_and_b32_e32 v87, 0xffff0000, v224
	v_lshlrev_b32_e32 v76, 16, v228
	v_and_b32_e32 v77, 0xffff0000, v228
	v_lshlrev_b32_e32 v78, 16, v229
	v_and_b32_e32 v79, 0xffff0000, v229
	v_pk_fma_f32 v[66:67], v[66:67], v[90:91], v[78:79] op_sel_hi:[1,0,1]
	v_pk_fma_f32 v[64:65], v[64:65], v[90:91], v[76:77] op_sel_hi:[1,0,1]
	v_lshlrev_b32_e32 v88, 16, v225
	v_and_b32_e32 v89, 0xffff0000, v225
	global_store_dwordx4 v[80:81], v[64:67], off offset:528
	ds_read2_b32 v[66:67], v196 offset0:128 offset1:144
	v_pk_fma_f32 v[74:75], v[74:75], v[90:91], v[88:89] op_sel_hi:[1,0,1]
	v_pk_fma_f32 v[72:73], v[72:73], v[90:91], v[86:87] op_sel_hi:[1,0,1]
	global_store_dwordx4 v[80:81], v[72:75], off offset:16
	v_lshlrev_b64 v[64:65], 12, v[184:185]
	v_lshl_add_u64 v[64:65], s[26:27], 0, v[64:65]
	v_lshlrev_b32_e32 v72, 16, v226
	v_and_b32_e32 v73, 0xffff0000, v226
	v_lshlrev_b32_e32 v74, 16, v227
	v_and_b32_e32 v75, 0xffff0000, v227
	v_pk_fma_f32 v[70:71], v[70:71], v[90:91], v[74:75] op_sel_hi:[1,0,1]
	v_pk_fma_f32 v[68:69], v[68:69], v[90:91], v[72:73] op_sel_hi:[1,0,1]
	global_store_dwordx4 v[80:81], v[68:71], off offset:512
	v_lshl_add_u64 v[64:65], v[64:65], 0, v[176:177]
	v_lshlrev_b32_e32 v72, 16, v158
	v_lshlrev_b32_e32 v68, 16, v156
	v_and_b32_e32 v69, 0xffff0000, v156
	v_lshlrev_b32_e32 v70, 16, v157
	v_and_b32_e32 v71, 0xffff0000, v157
	v_and_b32_e32 v73, 0xffff0000, v158
	v_lshlrev_b32_e32 v74, 16, v159
	v_and_b32_e32 v75, 0xffff0000, v159
	s_waitcnt lgkmcnt(0)
; __device__ __forceinline__ float bf_lo(unsigned w) { return __uint_as_float(w << 16); }
; __device__ __forceinline__ float bf_hi(unsigned w) { return __uint_as_float(w & 0xffff0000u); }
; #define PG8_WAIT_V(n) asm volatile("s_waitcnt vmcnt(" #n ")" ::: "memory")
; #define PG8_BAR __builtin_amdgcn_s_barrier()
; template <class Epi, class Ptrs>
; __device__ __forceinline__ void gemm_phase(LAS unsigned char* lds, const int K, const StaticOrder& S, const Ptrs& P, const Epi& E) {
;     ...
;         cur = nxt; cA = nA; cB = nB; ++ui;
;     }
;     PG8_WAIT_V(0);
;     if (wr == 0) PG8_BAR;
;     PG8_BAR;
;     __device__ __forceinline__ void operator()(const f32x4 (&acc)[2][2][4][2], const Unit& u, int ui, int wr, int wc, int fr, int fq) const {
;     ...
;         for (int ai = 0; ai < 2; ++ai)
; #pragma unroll
;             for (int m = 0; m < 4; ++m) { const int rl = rl0 + ai * 128 + m * 16; float* rowp = out + (size_t)(u.pm * 256 + rl) * DM + col0;
;                 const float r2 = tab[ui * 256 + rl];
; #pragma unroll
;                 for (int bj = 0; bj < 2; ++bj) { const u32x4 x = xv[ai][m][bj];
;                     const f32x4 x0 = {bf_lo(x.x), bf_hi(x.x), bf_lo(x.y), bf_hi(x.y)}, x1 = {bf_lo(x.z), bf_hi(x.z), bf_lo(x.w), bf_hi(x.w)};
;                     *(f32x4*)(rowp + bj * 128) = acc[ai][bj][m][0] * r2 + x0; *(f32x4*)(rowp + bj * 128 + 4) = acc[ai][bj][m][1] * r2 + x1; } }
	v_pk_fma_f32 v[62:63], v[62:63], v[66:67], v[70:71] op_sel_hi:[1,0,1]
	v_pk_fma_f32 v[60:61], v[60:61], v[66:67], v[68:69] op_sel_hi:[1,0,1]
	global_store_dwordx4 v[64:65], v[60:63], off
	v_pk_fma_f32 v[58:59], v[58:59], v[66:67], v[74:75] op_sel_hi:[1,0,1]
	v_pk_fma_f32 v[56:57], v[56:57], v[66:67], v[72:73] op_sel_hi:[1,0,1]
	v_lshlrev_b32_e32 v60, 16, v154
	v_and_b32_e32 v61, 0xffff0000, v154
	v_lshlrev_b32_e32 v62, 16, v155
	v_and_b32_e32 v63, 0xffff0000, v155
	global_store_dwordx4 v[64:65], v[56:59], off offset:16
	v_pk_fma_f32 v[46:47], v[46:47], v[66:67], v[62:63] op_sel_hi:[1,0,1]
	v_pk_fma_f32 v[44:45], v[44:45], v[66:67], v[60:61] op_sel_hi:[1,0,1]
	v_lshlrev_b32_e32 v56, 16, v152
	v_and_b32_e32 v57, 0xffff0000, v152
	v_lshlrev_b32_e32 v58, 16, v153
	v_and_b32_e32 v59, 0xffff0000, v153
	v_pk_fma_f32 v[54:55], v[54:55], v[66:67], v[58:59] op_sel_hi:[1,0,1]
	v_pk_fma_f32 v[52:53], v[52:53], v[66:67], v[56:57] op_sel_hi:[1,0,1]
	global_store_dwordx4 v[64:65], v[44:47], off offset:528
	global_store_dwordx4 v[64:65], v[52:55], off offset:512
	v_lshlrev_b32_e32 v56, 16, v151
	v_lshlrev_b64 v[44:45], 12, v[182:183]
	v_lshl_add_u64 v[44:45], s[26:27], 0, v[44:45]
	v_lshlrev_b32_e32 v54, 16, v150
	v_and_b32_e32 v55, 0xffff0000, v150
	v_and_b32_e32 v57, 0xffff0000, v151
	v_mov_b32_e32 v58, v67
	v_lshl_add_u64 v[52:53], v[44:45], 0, v[176:177]
	v_pk_fma_f32 v[42:43], v[42:43], v[58:59], v[56:57] op_sel_hi:[1,0,1]
	v_pk_fma_f32 v[40:41], v[40:41], v[58:59], v[54:55] op_sel_hi:[1,0,1]
	v_lshlrev_b32_e32 v44, 16, v148
	v_and_b32_e32 v45, 0xffff0000, v148
	v_lshlrev_b32_e32 v46, 16, v149
	v_and_b32_e32 v47, 0xffff0000, v149
	global_store_dwordx4 v[52:53], v[40:43], off offset:16
	v_pk_fma_f32 v[46:47], v[50:51], v[58:59], v[46:47] op_sel_hi:[1,0,1]
	v_pk_fma_f32 v[44:45], v[48:49], v[58:59], v[44:45] op_sel_hi:[1,0,1]
	v_lshlrev_b32_e32 v40, 16, v144
	v_and_b32_e32 v41, 0xffff0000, v144
	v_lshlrev_b32_e32 v42, 16, v145
	v_and_b32_e32 v43, 0xffff0000, v145
	v_pk_fma_f32 v[38:39], v[38:39], v[58:59], v[42:43] op_sel_hi:[1,0,1]
	v_pk_fma_f32 v[36:37], v[36:37], v[58:59], v[40:41] op_sel_hi:[1,0,1]
	global_store_dwordx4 v[52:53], v[44:47], off
	global_store_dwordx4 v[52:53], v[36:39], off offset:512
	ds_read2_b32 v[38:39], v196 offset0:160 offset1:176
	v_lshlrev_b32_e32 v44, 16, v146
	v_and_b32_e32 v45, 0xffff0000, v146
	v_lshlrev_b32_e32 v46, 16, v147
	v_and_b32_e32 v47, 0xffff0000, v147
	v_pk_fma_f32 v[30:31], v[30:31], v[58:59], v[46:47] op_sel_hi:[1,0,1]
	v_pk_fma_f32 v[28:29], v[28:29], v[58:59], v[44:45] op_sel_hi:[1,0,1]
	global_store_dwordx4 v[52:53], v[28:31], off offset:528
	v_lshlrev_b32_e32 v40, 16, v142
	v_and_b32_e32 v41, 0xffff0000, v142
	v_lshlrev_b64 v[28:29], 12, v[180:181]
	v_lshl_add_u64 v[28:29], s[26:27], 0, v[28:29]
	v_lshl_add_u64 v[36:37], v[28:29], 0, v[176:177]
	v_lshlrev_b32_e32 v28, 16, v140
	v_and_b32_e32 v29, 0xffff0000, v140
	v_lshlrev_b32_e32 v30, 16, v141
	v_and_b32_e32 v31, 0xffff0000, v141
	s_waitcnt lgkmcnt(0)
	v_pk_fma_f32 v[30:31], v[34:35], v[38:39], v[30:31] op_sel_hi:[1,0,1]
	v_pk_fma_f32 v[28:29], v[32:33], v[38:39], v[28:29] op_sel_hi:[1,0,1]
	v_lshlrev_b32_e32 v42, 16, v143
	v_and_b32_e32 v43, 0xffff0000, v143
	global_store_dwordx4 v[36:37], v[28:31], off
	v_pk_fma_f32 v[26:27], v[26:27], v[38:39], v[42:43] op_sel_hi:[1,0,1]
	v_pk_fma_f32 v[24:25], v[24:25], v[38:39], v[40:41] op_sel_hi:[1,0,1]
	v_lshlrev_b32_e32 v28, 16, v138
	v_and_b32_e32 v29, 0xffff0000, v138
	v_lshlrev_b32_e32 v30, 16, v139
	v_and_b32_e32 v31, 0xffff0000, v139
	v_pk_fma_f32 v[14:15], v[14:15], v[38:39], v[30:31] op_sel_hi:[1,0,1]
	v_pk_fma_f32 v[12:13], v[12:13], v[38:39], v[28:29] op_sel_hi:[1,0,1]
	global_store_dwordx4 v[36:37], v[24:27], off offset:16
	global_store_dwordx4 v[36:37], v[12:15], off offset:528
	s_nop 0
	v_lshlrev_b32_e32 v24, 16, v136
	v_and_b32_e32 v25, 0xffff0000, v136
	v_lshlrev_b32_e32 v26, 16, v137
	v_and_b32_e32 v27, 0xffff0000, v137
	v_lshlrev_b64 v[12:13], 12, v[178:179]
	v_pk_fma_f32 v[22:23], v[22:23], v[38:39], v[26:27] op_sel_hi:[1,0,1]
	v_pk_fma_f32 v[20:21], v[20:21], v[38:39], v[24:25] op_sel_hi:[1,0,1]
	v_lshl_add_u64 v[12:13], s[26:27], 0, v[12:13]
	global_store_dwordx4 v[36:37], v[20:23], off offset:512
	v_lshlrev_b32_e32 v14, 16, v133
	v_and_b32_e32 v15, 0xffff0000, v133
	v_lshl_add_u64 v[20:21], v[12:13], 0, v[176:177]
	v_lshlrev_b32_e32 v12, 16, v132
	v_and_b32_e32 v13, 0xffff0000, v132
	v_lshlrev_b32_e32 v22, 16, v134
	v_and_b32_e32 v23, 0xffff0000, v134
	v_lshlrev_b32_e32 v24, 16, v135
	v_and_b32_e32 v25, 0xffff0000, v135
	v_mov_b32_e32 v26, v39
	v_pk_fma_f32 v[14:15], v[18:19], v[26:27], v[14:15] op_sel_hi:[1,0,1]
	v_pk_fma_f32 v[12:13], v[16:17], v[26:27], v[12:13] op_sel_hi:[1,0,1]
	v_pk_fma_f32 v[10:11], v[10:11], v[26:27], v[24:25] op_sel_hi:[1,0,1]
	v_pk_fma_f32 v[8:9], v[8:9], v[26:27], v[22:23] op_sel_hi:[1,0,1]
	global_store_dwordx4 v[20:21], v[12:15], off
	global_store_dwordx4 v[20:21], v[8:11], off offset:16
	s_nop 0
	v_lshlrev_b32_e32 v12, 16, v130
	v_lshlrev_b32_e32 v8, 16, v128
	v_and_b32_e32 v9, 0xffff0000, v128
	v_lshlrev_b32_e32 v10, 16, v129
	v_and_b32_e32 v11, 0xffff0000, v129
	v_and_b32_e32 v13, 0xffff0000, v130
	v_lshlrev_b32_e32 v14, 16, v131
	v_and_b32_e32 v15, 0xffff0000, v131
	v_pk_fma_f32 v[6:7], v[6:7], v[26:27], v[10:11] op_sel_hi:[1,0,1]
	v_pk_fma_f32 v[4:5], v[4:5], v[26:27], v[8:9] op_sel_hi:[1,0,1]
	v_pk_fma_f32 v[2:3], v[2:3], v[26:27], v[14:15] op_sel_hi:[1,0,1]
	v_pk_fma_f32 v[0:1], v[0:1], v[26:27], v[12:13] op_sel_hi:[1,0,1]
	global_store_dwordx4 v[20:21], v[4:7], off offset:512
	global_store_dwordx4 v[20:21], v[0:3], off offset:528
	s_cbranch_vccz .LBB0_517
	s_waitcnt vmcnt(0)
	s_setprio 0
	s_cmpk_gt_u32 s33, 0xff
	s_cbranch_scc1 .LBB0_526
	s_barrier
